# gemm_tile8 mainloops: LDS staging writes and next-tile global loads interleaved into MFMA cluster, saddr-form loads
# speedup vs baseline: 1.0056x; 1.0056x over previous
; DI int tidx() { int t = __builtin_amdgcn_workitem_id_x(); asm volatile("" : "+v"(t)); return t; }
;   DI unsigned rowoff(int r, int sch) const { const int g = r & 3, bc = r >> 2, b = bc / NCMP, c = bc - b * NCMP; return (unsigned)(b * Sn + c * 16) * 512u + g * 64 + sch; }
; template <int NI, class XL, class EP>
; DI void gemm_tile(const u16* __restrict__ W, int ldw, int f0, int t0, int K, XL xl, EP ep, unsigned char* smem) {
;   constexpr int LST = 48;
;   constexpr int XR = NI / 2;
;   constexpr int BUF = (128 + NI * 32) * LST;
;   u16* S0 = (u16*)smem;
;   const int tid = tidx(), lane = tid & 63, wave = tid >> 6;
;   const int wf = wave >> 1, wt = wave & 1, lr = lane & 15, lq = lane >> 4;
;   const int srow = tid >> 2, sch = (tid & 3) * 8;
;   f32x4 acc[4][NI];
; #pragma unroll
;   for (int i = 0; i < 4; ++i)
; #pragma unroll
;     for (int j = 0; j < NI; ++j) acc[i][j] = (f32x4){0.f, 0.f, 0.f, 0.f};
;   u32x4 wr[2], xr[XR];
;   const unsigned wbyte = ((unsigned)(f0 + srow * 2) * 32u + sch) * 2u;
;   const unsigned xbyte = xl.rowoff(t0 + srow * XR, sch) * 2u;
;   const int xrs = xl.rstride();
;   const int nk = K >> 5;
;   auto gload = [&](int it) {
;     const int k = it * 32;
;     const char* wb = (const char*)(W + (size_t)(k >> 5) * ldw * 32);
;     const char* xb = (const char*)xl.kbase(k);
; #pragma unroll
;     for (int i = 0; i < 2; ++i) wr[i] = *(const u32x4*)(wb + wbyte + i * 64);
; #pragma unroll
;     for (int i = 0; i < XR; ++i) xr[i] = *(const u32x4*)(xb + xbyte + i * xrs);
;   };
;   auto lstore = [&](int buf) {
;     u16* Ws = S0 + buf * BUF; u16* Xs = Ws + 128 * LST;
; #pragma unroll
;     for (int i = 0; i < 2; ++i) *(u32x4*)(Ws + (srow * 2 + i) * LST + sch) = wr[i];
; #pragma unroll
;     for (int i = 0; i < XR; ++i) *(u32x4*)(Xs + (srow * XR + i) * LST + sch) = xr[i];
;   };
;   gload(0);
;   __syncthreads();
;   lstore(0);
;   __syncthreads();
;   if (nk > 1) gload(1);
; DI void phase1(const Params& p, const Sched& sched, unsigned char* smem) {
;     ...
;   for_tiles_st(256, ZC / 128, sched, [&](int tm, int tn) {
;     const int f0 = tn * 128, t0 = tm * 256;
;     gemm_tile<8>(W, ZC, f0, t0, 1024, xl, [&](f32x4 (&acc)[4][8], int fb, int tb, int lr, int lq, int wf, int wt) {
.LBB0_268:
	v_mov_b32_e32 v161, v218
	s_and_b32 s22, s59, 7
	s_or_b32 s61, s22, s53
	v_ashrrev_i32_e32 v44, 2, v161
	s_lshl_b32 s22, s59, 5
	v_lshlrev_b32_e32 v0, 3, v161
	v_lshlrev_b32_e32 v46, 6, v44
	s_and_b32 s60, s22, 0xffffff00
	v_and_b32_e32 v45, 24, v0
	v_lshl_add_u32 v0, s61, 12, v46
	s_add_i32 s60, s60, s54
	v_or_b32_e32 v0, v0, v45
	v_and_b32_e32 v48, 0x3fffffc, v161
	v_lshlrev_b32_e32 v47, 1, v0
	v_add_u32_e32 v0, s60, v48
	v_lshlrev_b32_e32 v162, 1, v45
	v_readlane_b32 s22, v245, 25
	v_lshl_or_b32 v49, v0, 6, v162
	v_readlane_b32 s23, v245, 26
	global_load_dwordx4 v[16:19], v47, s[42:43]
	global_load_dwordx4 v[20:23], v47, s[42:43] offset:64
	s_nop 2
	global_load_dwordx4 v[24:27], v49, s[22:23]
	global_load_dwordx4 v[28:31], v49, s[22:23] offset:64
	global_load_dwordx4 v[32:35], v49, s[22:23] offset:128
	global_load_dwordx4 v[36:39], v49, s[22:23] offset:192
	v_mul_lo_u32 v167, v44, s37
	v_or_b32_e32 v163, v167, v162
	v_add_u32_e32 v164, v163, v167
	s_barrier
	s_and_b32 s23, s58, 0x3ffff00
	s_and_b32 s24, s57, 7
	s_add_i32 s24, s56, s24
	s_add_i32 s23, s54, s23
	v_ashrrev_i32_e32 v51, 1, v161
	v_and_b32_e32 v50, 15, v161
	v_lshrrev_b32_e32 v52, 1, v161
	v_lshlrev_b32_e32 v53, 1, v161
	v_and_b32_e32 v159, 0xffffffc0, v51
	v_add_u32_e32 v44, s23, v48
	v_lshl_add_u32 v46, s24, 12, v46
	v_mov_b32_e32 v0, 0
	v_and_b32_e32 v158, 24, v52
	v_and_or_b32 v160, v53, s44, v50
	v_or_b32_e32 v48, v159, v50
	v_lshl_or_b32 v152, v44, 6, v162
	v_or_b32_e32 v44, v46, v45
	s_mov_b32 s22, 1
	v_mov_b32_e32 v155, v153
	v_mov_b32_e32 v1, v0
	v_mov_b32_e32 v2, v0
	v_mov_b32_e32 v3, v0
	v_mov_b32_e32 v4, v0
	v_mov_b32_e32 v5, v0
	v_mov_b32_e32 v6, v0
	v_mov_b32_e32 v7, v0
	v_mov_b32_e32 v8, v0
	v_mov_b32_e32 v9, v0
	v_mov_b32_e32 v10, v0
	v_mov_b32_e32 v11, v0
	v_mov_b32_e32 v12, v0
	v_mov_b32_e32 v13, v0
	v_mov_b32_e32 v14, v0
	v_mov_b32_e32 v15, v0
	v_mov_b32_e32 v40, v0
	v_mov_b32_e32 v41, v0
	v_mov_b32_e32 v42, v0
	v_mov_b32_e32 v43, v0
	v_mul_u32_u24_e32 v165, 48, v160
	v_lshlrev_b32_e32 v166, 1, v158
	v_mul_lo_u32 v168, v48, 48
	v_lshlrev_b32_e32 v154, 1, v44
	v_mov_b64_e32 v[156:157], v[152:153]
	v_mov_b32_e32 v56, v0
	v_mov_b32_e32 v57, v0
	v_mov_b32_e32 v58, v0
	v_mov_b32_e32 v59, v0
	v_mov_b32_e32 v68, v0
	v_mov_b32_e32 v69, v0
	v_mov_b32_e32 v70, v0
	v_mov_b32_e32 v71, v0
	v_mov_b32_e32 v80, v0
	v_mov_b32_e32 v81, v0
	v_mov_b32_e32 v82, v0
	v_mov_b32_e32 v83, v0
	v_mov_b32_e32 v44, v0
	v_mov_b32_e32 v45, v0
	v_mov_b32_e32 v46, v0
	v_mov_b32_e32 v48, v0
	s_waitcnt vmcnt(5)
	ds_write_b128 v163, v[16:19]
	s_waitcnt vmcnt(4)
	ds_write_b128 v163, v[20:23] offset:96
	s_waitcnt vmcnt(3)
	ds_write_b128 v164, v[24:27] offset:12288
	s_waitcnt vmcnt(2)
	ds_write_b128 v164, v[28:31] offset:12384
	s_waitcnt vmcnt(1)
	ds_write_b128 v164, v[32:35] offset:12480
	s_waitcnt vmcnt(0)
	ds_write_b128 v164, v[36:39] offset:12576
	s_waitcnt lgkmcnt(0)
	s_barrier
	global_load_dwordx4 v[20:23], v47, s[6:7]
	global_load_dwordx4 v[16:19], v47, s[6:7] offset:64
	global_load_dwordx4 v[36:39], v49, s[8:9]
	global_load_dwordx4 v[32:35], v49, s[8:9] offset:64
	global_load_dwordx4 v[28:31], v49, s[8:9] offset:128
	global_load_dwordx4 v[24:27], v49, s[8:9] offset:192
	v_mov_b32_e32 v47, v0
	v_mov_b32_e32 v49, v0
	v_mov_b32_e32 v50, v0
	v_mov_b32_e32 v51, v0
	v_mov_b32_e32 v52, v0
	v_mov_b32_e32 v53, v0
	v_mov_b32_e32 v54, v0
	v_mov_b32_e32 v55, v0
	v_mov_b32_e32 v64, v0
	v_mov_b32_e32 v65, v0
	v_mov_b32_e32 v66, v0
	v_mov_b32_e32 v67, v0
	v_mov_b32_e32 v76, v0
	v_mov_b32_e32 v77, v0
	v_mov_b32_e32 v78, v0
	v_mov_b32_e32 v79, v0
	v_mov_b32_e32 v88, v0
	v_mov_b32_e32 v89, v0
	v_mov_b32_e32 v90, v0
	v_mov_b32_e32 v91, v0
	v_mov_b32_e32 v100, v0
	v_mov_b32_e32 v101, v0
	v_mov_b32_e32 v102, v0
	v_mov_b32_e32 v103, v0
	v_mov_b32_e32 v112, v0
	v_mov_b32_e32 v113, v0
	v_mov_b32_e32 v114, v0
	v_mov_b32_e32 v115, v0
	v_mov_b32_e32 v60, v0
	v_mov_b32_e32 v61, v0
	v_mov_b32_e32 v62, v0
	v_mov_b32_e32 v63, v0
	v_mov_b32_e32 v72, v0
	v_mov_b32_e32 v73, v0
	v_mov_b32_e32 v74, v0
	v_mov_b32_e32 v75, v0
	v_mov_b32_e32 v84, v0
	v_mov_b32_e32 v85, v0
	v_mov_b32_e32 v86, v0
	v_mov_b32_e32 v87, v0
	v_mov_b32_e32 v96, v0
	v_mov_b32_e32 v97, v0
	v_mov_b32_e32 v98, v0
	v_mov_b32_e32 v99, v0
	v_mov_b32_e32 v108, v0
	v_mov_b32_e32 v109, v0
	v_mov_b32_e32 v110, v0
	v_mov_b32_e32 v111, v0
	v_mov_b32_e32 v120, v0
	v_mov_b32_e32 v121, v0
	v_mov_b32_e32 v122, v0
	v_mov_b32_e32 v123, v0
	v_mov_b32_e32 v128, v0
	v_mov_b32_e32 v129, v0
	v_mov_b32_e32 v130, v0
	v_mov_b32_e32 v131, v0
	v_mov_b32_e32 v136, v0
	v_mov_b32_e32 v137, v0
	v_mov_b32_e32 v138, v0
	v_mov_b32_e32 v139, v0
	v_mov_b32_e32 v92, v0
	v_mov_b32_e32 v93, v0
	v_mov_b32_e32 v94, v0
	v_mov_b32_e32 v95, v0
	v_mov_b32_e32 v104, v0
	v_mov_b32_e32 v105, v0
	v_mov_b32_e32 v106, v0
	v_mov_b32_e32 v107, v0
	v_mov_b32_e32 v116, v0
	v_mov_b32_e32 v117, v0
	v_mov_b32_e32 v118, v0
	v_mov_b32_e32 v119, v0
	v_mov_b32_e32 v124, v0
	v_mov_b32_e32 v125, v0
	v_mov_b32_e32 v126, v0
	v_mov_b32_e32 v127, v0
	v_mov_b32_e32 v132, v0
	v_mov_b32_e32 v133, v0
	v_mov_b32_e32 v134, v0
	v_mov_b32_e32 v135, v0
	v_mov_b32_e32 v140, v0
	v_mov_b32_e32 v141, v0
	v_mov_b32_e32 v142, v0
	v_mov_b32_e32 v143, v0
	v_mov_b32_e32 v144, v0
	v_mov_b32_e32 v145, v0
	v_mov_b32_e32 v146, v0
	v_mov_b32_e32 v147, v0
	v_mov_b32_e32 v148, v0
	v_mov_b32_e32 v149, v0
	v_mov_b32_e32 v150, v0
	v_mov_b32_e32 v151, v0
	s_add_u32 s98, s42, s45
	s_addc_u32 s99, s43, 0
	s_add_u32 s100, s42, s46
	s_addc_u32 s101, s43, 0
; DI f32x4 mfma16(bf16x8 a, bf16x8 b, f32x4 c) { return __builtin_amdgcn_mfma_f32_16x16x32_bf16(a, b, c, 0, 0, 0); }
; template <int NI, class XL, class EP>
; DI void gemm_tile(const u16* __restrict__ W, int ldw, int f0, int t0, int K, XL xl, EP ep, unsigned char* smem) {
;     ...
;   for (int it = 0; it < nk; ++it) {
;     const u16* Ws = S0 + (it & 1) * BUF; const u16* Xs = Ws + 128 * LST;
;     __builtin_amdgcn_s_setprio(1);
;     bf16x8 a[4];
; #pragma unroll
;     for (int mi = 0; mi < 4; ++mi) a[mi] = *(const bf16x8*)(Ws + (wf * 64 + mi * 16 + lr) * LST + lq * 8);
; #pragma unroll
;     for (int ni = 0; ni < NI; ++ni) {
;       const bf16x8 b = *(const bf16x8*)(Xs + (wt * (NI * 16) + ni * 16 + lr) * LST + lq * 8);
; #pragma unroll
;       for (int mi = 0; mi < 4; ++mi) acc[mi][ni] = mfma16(a[mi], b, acc[mi][ni]);
;     }
;     __builtin_amdgcn_sched_group_barrier(0x100, 6, 0);
; #pragma unroll
;     for (int ni = 0; ni < NI; ++ni) { __builtin_amdgcn_sched_group_barrier(0x008, 4, 0); if (ni + 2 < NI) __builtin_amdgcn_sched_group_barrier(0x100, 1, 0); }
;     __builtin_amdgcn_s_setprio(0);
;     if (it + 1 < nk) lstore((it + 1) & 1);
;     if (it + 2 < nk) gload(it + 2);
;     __syncthreads();
.LBB0_269:
	s_bitcmp1_b32 s22, 0
	s_cselect_b32 s23, 0, 0x9000
	s_setprio 1
	v_or_b32_e32 v152, s23, v166
	v_lshl_add_u32 v169, v168, 1, v152
	ds_read_b128 v[170:173], v169
	ds_read_b128 v[174:177], v169 offset:1536
	ds_read_b128 v[182:185], v169 offset:3072
	ds_read_b128 v[186:189], v169 offset:4608
	v_lshl_add_u32 v152, v165, 1, v152
	ds_read_b128 v[178:181], v152 offset:12288
	ds_read_b128 v[190:193], v152 offset:13824
	s_xor_b32 s23, s23, 0x9000
	v_add3_u32 v220, v167, s23, v162
	s_waitcnt lgkmcnt(1)
	v_mfma_f32_16x16x32_bf16 v[148:151], v[170:173], v[178:181], v[148:151]
	v_mfma_f32_16x16x32_bf16 v[136:139], v[174:177], v[178:181], v[136:139]
	v_mfma_f32_16x16x32_bf16 v[112:115], v[182:185], v[178:181], v[112:115]
	v_mfma_f32_16x16x32_bf16 v[80:83], v[186:189], v[178:181], v[80:83]
	ds_read_b128 v[178:181], v152 offset:15360
	s_waitcnt vmcnt(5)
	ds_write_b128 v220, v[20:23]
	s_waitcnt lgkmcnt(2)
	v_mfma_f32_16x16x32_bf16 v[144:147], v[170:173], v[190:193], v[144:147]
	v_mfma_f32_16x16x32_bf16 v[128:131], v[174:177], v[190:193], v[128:131]
	v_mfma_f32_16x16x32_bf16 v[100:103], v[182:185], v[190:193], v[100:103]
	v_mfma_f32_16x16x32_bf16 v[68:71], v[186:189], v[190:193], v[68:71]
	ds_read_b128 v[190:193], v152 offset:16896
	s_waitcnt vmcnt(4)
	ds_write_b128 v220, v[16:19] offset:96
	v_add_u32_e32 v220, v220, v167
	global_load_dwordx4 v[20:23], v154, s[98:99]
	global_load_dwordx4 v[16:19], v154, s[98:99] offset:64
	s_waitcnt lgkmcnt(3)
	v_mfma_f32_16x16x32_bf16 v[140:143], v[170:173], v[178:181], v[140:143]
	v_mfma_f32_16x16x32_bf16 v[120:123], v[174:177], v[178:181], v[120:123]
	v_mfma_f32_16x16x32_bf16 v[88:91], v[182:185], v[178:181], v[88:91]
	v_mfma_f32_16x16x32_bf16 v[56:59], v[186:189], v[178:181], v[56:59]
	ds_read_b128 v[178:181], v152 offset:18432
	s_waitcnt vmcnt(5)
	ds_write_b128 v220, v[36:39] offset:12288
	global_load_dwordx4 v[36:39], v156, s[100:101] offset:2048
	s_waitcnt lgkmcnt(3)
	v_mfma_f32_16x16x32_bf16 v[132:135], v[170:173], v[190:193], v[132:135]
	v_mfma_f32_16x16x32_bf16 v[108:111], v[174:177], v[190:193], v[108:111]
	v_mfma_f32_16x16x32_bf16 v[76:79], v[182:185], v[190:193], v[76:79]
	v_mfma_f32_16x16x32_bf16 v[40:43], v[186:189], v[190:193], v[40:43]
	ds_read_b128 v[190:193], v152 offset:19968
	s_waitcnt vmcnt(5)
	ds_write_b128 v220, v[32:35] offset:12384
	global_load_dwordx4 v[32:35], v156, s[100:101] offset:2112
	s_waitcnt lgkmcnt(3)
	v_mfma_f32_16x16x32_bf16 v[124:127], v[170:173], v[178:181], v[124:127]
	v_mfma_f32_16x16x32_bf16 v[96:99], v[174:177], v[178:181], v[96:99]
	v_mfma_f32_16x16x32_bf16 v[64:67], v[182:185], v[178:181], v[64:67]
	v_mfma_f32_16x16x32_bf16 v[12:15], v[186:189], v[178:181], v[12:15]
	ds_read_b128 v[178:181], v152 offset:21504
	s_waitcnt vmcnt(5)
	ds_write_b128 v220, v[28:31] offset:12480
	global_load_dwordx4 v[28:31], v156, s[100:101] offset:2176
	s_waitcnt lgkmcnt(3)
	v_mfma_f32_16x16x32_bf16 v[116:119], v[170:173], v[190:193], v[116:119]
	v_mfma_f32_16x16x32_bf16 v[84:87], v[174:177], v[190:193], v[84:87]
	v_mfma_f32_16x16x32_bf16 v[52:55], v[182:185], v[190:193], v[52:55]
	v_mfma_f32_16x16x32_bf16 v[8:11], v[186:189], v[190:193], v[8:11]
	ds_read_b128 v[190:193], v152 offset:23040
	s_waitcnt vmcnt(5)
	ds_write_b128 v220, v[24:27] offset:12576
	global_load_dwordx4 v[24:27], v156, s[100:101] offset:2240
	s_waitcnt lgkmcnt(3)
	v_mfma_f32_16x16x32_bf16 v[104:107], v[170:173], v[178:181], v[104:107]
	v_mfma_f32_16x16x32_bf16 v[72:75], v[174:177], v[178:181], v[72:75]
	v_mfma_f32_16x16x32_bf16 v[48:51], v[182:185], v[178:181], v[48:51]
	v_mfma_f32_16x16x32_bf16 v[4:7], v[186:189], v[178:181], v[4:7]
	s_add_u32 s98, s98, s4
	s_addc_u32 s99, s99, s5
	s_add_u32 s100, s100, s14
	s_addc_u32 s101, s101, s15
	s_add_i32 s22, s22, 1
	s_waitcnt lgkmcnt(1)
	v_mfma_f32_16x16x32_bf16 v[92:95], v[170:173], v[190:193], v[92:95]
	v_mfma_f32_16x16x32_bf16 v[60:63], v[174:177], v[190:193], v[60:63]
	v_mfma_f32_16x16x32_bf16 v[44:47], v[182:185], v[190:193], v[44:47]
	v_mfma_f32_16x16x32_bf16 v[0:3], v[186:189], v[190:193], v[0:3]
	s_setprio 0
	s_cmp_eq_u32 s22, 31
	s_waitcnt lgkmcnt(0)
	s_barrier
	s_cbranch_scc0 .LBB0_269
	s_setprio 1
	v_lshl_add_u32 v152, v168, 1, v166
	ds_read_b128 v[154:157], v152
	v_lshl_add_u32 v228, v165, 1, v166
	ds_read_b128 v[166:169], v152 offset:1536
	ds_read_b128 v[174:177], v152 offset:3072
	ds_read_b128 v[178:181], v152 offset:4608
	ds_read_b128 v[170:173], v228 offset:12288
	ds_read_b128 v[182:185], v228 offset:13824
	s_waitcnt lgkmcnt(1)
	v_mfma_f32_16x16x32_bf16 v[148:151], v[154:157], v[170:173], v[148:151]
	v_mfma_f32_16x16x32_bf16 v[136:139], v[166:169], v[170:173], v[136:139]
	v_mfma_f32_16x16x32_bf16 v[112:115], v[174:177], v[170:173], v[112:115]
	v_mfma_f32_16x16x32_bf16 v[170:173], v[178:181], v[170:173], v[80:83]
	s_nop 2
	ds_read_b128 v[80:83], v228 offset:15360
	s_waitcnt lgkmcnt(1)
	v_mfma_f32_16x16x32_bf16 v[144:147], v[154:157], v[182:185], v[144:147]
	v_mfma_f32_16x16x32_bf16 v[128:131], v[166:169], v[182:185], v[128:131]
	v_mfma_f32_16x16x32_bf16 v[100:103], v[174:177], v[182:185], v[100:103]
	v_mfma_f32_16x16x32_bf16 v[68:71], v[178:181], v[182:185], v[68:71]
	ds_read_b128 v[182:185], v228 offset:16896
	s_waitcnt lgkmcnt(1)
	v_mfma_f32_16x16x32_bf16 v[140:143], v[154:157], v[80:83], v[140:143]
	v_mfma_f32_16x16x32_bf16 v[186:189], v[166:169], v[80:83], v[120:123]
	v_mfma_f32_16x16x32_bf16 v[88:91], v[174:177], v[80:83], v[88:91]
	v_mfma_f32_16x16x32_bf16 v[56:59], v[178:181], v[80:83], v[56:59]
	ds_read_b128 v[80:83], v228 offset:18432
	s_waitcnt lgkmcnt(1)
; DI f32x4 mfma16(bf16x8 a, bf16x8 b, f32x4 c) { return __builtin_amdgcn_mfma_f32_16x16x32_bf16(a, b, c, 0, 0, 0); }
; template <int NI, class XL, class EP>
; DI void gemm_tile(const u16* __restrict__ W, int ldw, int f0, int t0, int K, XL xl, EP ep, unsigned char* smem) {
;     ...
;   for (int it = 0; it < nk; ++it) {
;     const u16* Ws = S0 + (it & 1) * BUF; const u16* Xs = Ws + 128 * LST;
;     __builtin_amdgcn_s_setprio(1);
;     bf16x8 a[4];
; #pragma unroll
;     for (int mi = 0; mi < 4; ++mi) a[mi] = *(const bf16x8*)(Ws + (wf * 64 + mi * 16 + lr) * LST + lq * 8);
; #pragma unroll
;     for (int ni = 0; ni < NI; ++ni) {
;       const bf16x8 b = *(const bf16x8*)(Xs + (wt * (NI * 16) + ni * 16 + lr) * LST + lq * 8);
; #pragma unroll
;       for (int mi = 0; mi < 4; ++mi) acc[mi][ni] = mfma16(a[mi], b, acc[mi][ni]);
;     }
;     __builtin_amdgcn_sched_group_barrier(0x100, 6, 0);
; #pragma unroll
;     for (int ni = 0; ni < NI; ++ni) { __builtin_amdgcn_sched_group_barrier(0x008, 4, 0); if (ni + 2 < NI) __builtin_amdgcn_sched_group_barrier(0x100, 1, 0); }
;     __builtin_amdgcn_s_setprio(0);
;     if (it + 1 < nk) lstore((it + 1) & 1);
;     if (it + 2 < nk) gload(it + 2);
;     __syncthreads();
;   }
;   ep(acc, f0 + wf * 64, t0 + wt * (NI * 16), lr, lq, wf, wt);
; DI void phase1(const Params& p, const Sched& sched, unsigned char* smem) {
;     ...
;       u16* dst; int ld, cb;
;       if (tn < 8) { dst = (u16*)(p.ws + OFF_QB); ld = 1024; cb = 0; }
;       else if (tn < 12) { dst = (u16*)(p.ws + OFF_KVC); ld = 512; cb = 1024; }
;       else if (tn < 16) { dst = (u16*)(p.ws + OFF_KVS); ld = 512; cb = 1536; }
;       else if (tn < 20) { dst = (u16*)(p.ws + OFF_KVW); ld = 512; cb = 2048; }
;       else if (tn < 22) { dst = (u16*)(p.ws + OFF_MQ); ld = 256; cb = 2560; }
;       else if (tn < 24) { dst = (u16*)(p.ws + OFF_MKV); ld = 256; cb = 2816; }
;       else if (tn < 32) { dst = (u16*)(p.ws + OFF_MA); ld = 1024; cb = 3072; }
;       else { dst = (u16*)(p.ws + OFF_MB); ld = 1024; cb = 4096; }
	v_mfma_f32_16x16x32_bf16 v[132:135], v[154:157], v[182:185], v[132:135]
	v_mfma_f32_16x16x32_bf16 v[108:111], v[166:169], v[182:185], v[108:111]
	v_mfma_f32_16x16x32_bf16 v[76:79], v[174:177], v[182:185], v[76:79]
	v_mfma_f32_16x16x32_bf16 v[182:185], v[178:181], v[182:185], v[40:43]
	s_nop 2
	ds_read_b128 v[40:43], v228 offset:19968
	s_waitcnt lgkmcnt(1)
	v_mfma_f32_16x16x32_bf16 v[190:193], v[154:157], v[80:83], v[124:127]
	v_mfma_f32_16x16x32_bf16 v[96:99], v[166:169], v[80:83], v[96:99]
	v_mfma_f32_16x16x32_bf16 v[194:197], v[174:177], v[80:83], v[64:67]
	v_mfma_f32_16x16x32_bf16 v[198:201], v[178:181], v[80:83], v[12:15]
	s_nop 2
	ds_read_b128 v[12:15], v228 offset:21504
	s_waitcnt lgkmcnt(1)
	v_mfma_f32_16x16x32_bf16 v[202:205], v[154:157], v[40:43], v[116:119]
	v_mfma_f32_16x16x32_bf16 v[84:87], v[166:169], v[40:43], v[84:87]
	v_mfma_f32_16x16x32_bf16 v[52:55], v[174:177], v[40:43], v[52:55]
	v_mfma_f32_16x16x32_bf16 v[206:209], v[178:181], v[40:43], v[8:11]
	s_nop 2
	ds_read_b128 v[8:11], v228 offset:23040
	s_waitcnt lgkmcnt(1)
	v_mfma_f32_16x16x32_bf16 v[210:213], v[154:157], v[12:15], v[104:107]
	v_mfma_f32_16x16x32_bf16 v[214:217], v[166:169], v[12:15], v[72:75]
	v_mfma_f32_16x16x32_bf16 v[220:223], v[174:177], v[12:15], v[48:51]
	v_mfma_f32_16x16x32_bf16 v[224:227], v[178:181], v[12:15], v[4:7]
	s_waitcnt lgkmcnt(0)
	v_mfma_f32_16x16x32_bf16 v[92:95], v[154:157], v[8:11], v[92:95]
	v_mfma_f32_16x16x32_bf16 v[60:63], v[166:169], v[8:11], v[60:63]
	v_mfma_f32_16x16x32_bf16 v[154:157], v[174:177], v[8:11], v[44:47]
	v_mfma_f32_16x16x32_bf16 v[166:169], v[178:181], v[8:11], v[0:3]
	s_setprio 0
	s_waitcnt vmcnt(5)
	ds_write_b128 v163, v[20:23] offset:36864
	s_waitcnt vmcnt(4)
	ds_write_b128 v163, v[16:19] offset:36960
	s_waitcnt vmcnt(3)
	ds_write_b128 v164, v[36:39] offset:49152
	s_waitcnt vmcnt(2)
	ds_write_b128 v164, v[32:35] offset:49248
	s_waitcnt vmcnt(1)
	ds_write_b128 v164, v[28:31] offset:49344
	s_waitcnt vmcnt(0)
	ds_write_b128 v164, v[24:27] offset:49440
	s_waitcnt lgkmcnt(0)
	s_barrier
	s_setprio 1
	ds_read_b128 v[36:39], v152 offset:36864
	ds_read_b128 v[162:165], v152 offset:38400
	ds_read_b128 v[174:177], v152 offset:39936
	ds_read_b128 v[178:181], v152 offset:41472
	ds_read_b128 v[0:3], v228 offset:49152
	ds_read_b128 v[4:7], v228 offset:50688
	s_waitcnt lgkmcnt(1)
	v_mfma_f32_16x16x32_bf16 v[124:127], v[36:39], v[0:3], v[148:151]
	v_mfma_f32_16x16x32_bf16 v[80:83], v[162:165], v[0:3], v[136:139]
	v_mfma_f32_16x16x32_bf16 v[28:31], v[174:177], v[0:3], v[112:115]
	v_mfma_f32_16x16x32_bf16 v[0:3], v[178:181], v[0:3], v[170:173]
	ds_read_b128 v[8:11], v228 offset:52224
	s_waitcnt lgkmcnt(1)
	v_mfma_f32_16x16x32_bf16 v[120:123], v[36:39], v[4:7], v[144:147]
	v_mfma_f32_16x16x32_bf16 v[72:75], v[162:165], v[4:7], v[128:131]
	v_mfma_f32_16x16x32_bf16 v[32:35], v[174:177], v[4:7], v[100:103]
	v_mfma_f32_16x16x32_bf16 v[4:7], v[178:181], v[4:7], v[68:71]
	ds_read_b128 v[12:15], v228 offset:53760
	s_waitcnt lgkmcnt(1)
	v_mfma_f32_16x16x32_bf16 v[116:119], v[36:39], v[8:11], v[140:143]
	v_mfma_f32_16x16x32_bf16 v[64:67], v[162:165], v[8:11], v[186:189]
	v_mfma_f32_16x16x32_bf16 v[40:43], v[174:177], v[8:11], v[88:91]
	v_mfma_f32_16x16x32_bf16 v[8:11], v[178:181], v[8:11], v[56:59]
	ds_read_b128 v[16:19], v228 offset:55296
	s_waitcnt lgkmcnt(1)
	v_mfma_f32_16x16x32_bf16 v[112:115], v[36:39], v[12:15], v[132:135]
	v_mfma_f32_16x16x32_bf16 v[68:71], v[162:165], v[12:15], v[108:111]
	v_mfma_f32_16x16x32_bf16 v[44:47], v[174:177], v[12:15], v[76:79]
	v_mfma_f32_16x16x32_bf16 v[12:15], v[178:181], v[12:15], v[182:185]
	ds_read_b128 v[20:23], v228 offset:56832
	s_waitcnt lgkmcnt(1)
	v_mfma_f32_16x16x32_bf16 v[108:111], v[36:39], v[16:19], v[190:193]
	v_mfma_f32_16x16x32_bf16 v[76:79], v[162:165], v[16:19], v[96:99]
	v_mfma_f32_16x16x32_bf16 v[48:51], v[174:177], v[16:19], v[194:197]
	v_mfma_f32_16x16x32_bf16 v[16:19], v[178:181], v[16:19], v[198:201]
	ds_read_b128 v[24:27], v228 offset:58368
	s_waitcnt lgkmcnt(1)
	v_mfma_f32_16x16x32_bf16 v[104:107], v[36:39], v[20:23], v[202:205]
	v_mfma_f32_16x16x32_bf16 v[84:87], v[162:165], v[20:23], v[84:87]
	v_mfma_f32_16x16x32_bf16 v[52:55], v[174:177], v[20:23], v[52:55]
	v_mfma_f32_16x16x32_bf16 v[20:23], v[178:181], v[20:23], v[206:209]
	ds_read_b128 v[128:131], v228 offset:59904
	s_waitcnt lgkmcnt(1)
	v_mfma_f32_16x16x32_bf16 v[100:103], v[36:39], v[24:27], v[210:213]
	v_mfma_f32_16x16x32_bf16 v[88:91], v[162:165], v[24:27], v[214:217]
	v_mfma_f32_16x16x32_bf16 v[56:59], v[174:177], v[24:27], v[220:223]
	v_mfma_f32_16x16x32_bf16 v[24:27], v[178:181], v[24:27], v[224:227]
	s_waitcnt lgkmcnt(0)
	v_mfma_f32_16x16x32_bf16 v[96:99], v[36:39], v[128:131], v[92:95]
	v_mfma_f32_16x16x32_bf16 v[92:95], v[162:165], v[128:131], v[60:63]
	v_mfma_f32_16x16x32_bf16 v[60:63], v[174:177], v[128:131], v[154:157]
	v_mfma_f32_16x16x32_bf16 v[36:39], v[178:181], v[128:131], v[166:169]
	s_setprio 0
	s_cmp_lt_i32 s61, 8
	s_barrier
	s_cbranch_scc1 .LBB0_275
	s_cmp_lt_u32 s61, 12
	s_cselect_b64 s[22:23], -1, 0
	s_or_b64 s[24:25], s[22:23], s[16:17]
	s_and_b64 s[22:23], s[22:23], exec
	s_cselect_b32 s22, s48, 0x17b00800
	s_cselect_b32 s62, s47, 0xfffffa00
	s_add_u32 s22, s42, s22
	s_addc_u32 s23, s43, 0
	s_and_b64 vcc, exec, s[24:25]
	s_cbranch_vccnz .LBB0_276
	s_cmp_lt_u32 s61, 20
	s_cbranch_scc1 .LBB0_277
	s_cmp_lt_u32 s61, 22
	s_cselect_b64 s[22:23], -1, 0
	s_or_b64 s[24:25], s[22:23], s[18:19]
	s_and_b64 s[22:23], s[22:23], exec
	s_cselect_b32 s22, s50, 0x21b00800
	s_cselect_b32 s62, s49, 0xfffff500
	s_add_u32 s22, s42, s22
	s_addc_u32 s23, s43, 0
	s_and_b64 vcc, exec, s[24:25]
	s_cbranch_vccnz .LBB0_278
	s_mov_b64 s[24:25], 0x400
	s_mov_b64 s[22:23], s[20:21]
	s_mov_b32 s62, s55
	s_branch .LBB0_279

; DI int tidx() { int t = __builtin_amdgcn_workitem_id_x(); asm volatile("" : "+v"(t)); return t; }
;   DI unsigned rowoff(int r, int sch) const { const int g = r & 3, bc = r >> 2, b = bc / NCMP, c = bc - b * NCMP; return (unsigned)(b * Sn + c * 16) * 512u + g * 64 + sch; }
; template <int NI, class XL, class EP>
; DI void gemm_tile(const u16* __restrict__ W, int ldw, int f0, int t0, int K, XL xl, EP ep, unsigned char* smem) {
;   constexpr int LST = 48;
;   constexpr int XR = NI / 2;
;   constexpr int BUF = (128 + NI * 32) * LST;
;   u16* S0 = (u16*)smem;
;   const int tid = tidx(), lane = tid & 63, wave = tid >> 6;
;   const int wf = wave >> 1, wt = wave & 1, lr = lane & 15, lq = lane >> 4;
;   const int srow = tid >> 2, sch = (tid & 3) * 8;
;   f32x4 acc[4][NI];
; #pragma unroll
;   for (int i = 0; i < 4; ++i)
; #pragma unroll
;     for (int j = 0; j < NI; ++j) acc[i][j] = (f32x4){0.f, 0.f, 0.f, 0.f};
;   u32x4 wr[2], xr[XR];
;   const unsigned wbyte = ((unsigned)(f0 + srow * 2) * 32u + sch) * 2u;
;   const unsigned xbyte = xl.rowoff(t0 + srow * XR, sch) * 2u;
;   const int xrs = xl.rstride();
;   const int nk = K >> 5;
;   auto gload = [&](int it) {
;     const int k = it * 32;
;     const char* wb = (const char*)(W + (size_t)(k >> 5) * ldw * 32);
;     const char* xb = (const char*)xl.kbase(k);
; #pragma unroll
;     for (int i = 0; i < 2; ++i) wr[i] = *(const u32x4*)(wb + wbyte + i * 64);
; #pragma unroll
;     for (int i = 0; i < XR; ++i) xr[i] = *(const u32x4*)(xb + xbyte + i * xrs);
;   };
;   auto lstore = [&](int buf) {
;     u16* Ws = S0 + buf * BUF; u16* Xs = Ws + 128 * LST;
; #pragma unroll
;     for (int i = 0; i < 2; ++i) *(u32x4*)(Ws + (srow * 2 + i) * LST + sch) = wr[i];
; #pragma unroll
;     for (int i = 0; i < XR; ++i) *(u32x4*)(Xs + (srow * XR + i) * LST + sch) = xr[i];
;   };
;   gload(0);
;   __syncthreads();
;   lstore(0);
;   __syncthreads();
;   if (nk > 1) gload(1);
; DI void phase6(const Params& p, const Sched& sched, unsigned char* smem) {
;     ...
;   for_tiles_st(256, 8, sched, [&](int tm, int tn) {
;     gemm_tile<8>((const u16*)(p.ws + OFF_WO), 1024, tn * 128, tm * 256, 1024, xl, [&](f32x4 (&acc)[4][8], int fb, int tb, int lr, int lq, int wf, int wt) {
.LBB0_811:
	v_mov_b32_e32 v46, v218
	s_and_b32 s34, s31, 7
	v_ashrrev_i32_e32 v47, 2, v46
	v_lshlrev_b32_e32 v0, 3, v46
	v_lshlrev_b32_e32 v49, 6, v47
	s_ashr_i32 s37, s31, 3
	v_and_b32_e32 v48, 24, v0
	v_lshl_add_u32 v0, s34, 12, v49
	s_add_i32 s35, s37, s29
	v_or_b32_e32 v0, v0, v48
	s_lshl_b32 s33, s35, 8
	v_lshlrev_b32_e32 v50, 1, v0
	v_and_b32_e32 v0, 0x3fffffc, v46
	v_add_u32_e32 v0, s33, v0
	v_lshlrev_b32_e32 v161, 1, v48
	v_lshl_or_b32 v51, v0, 6, v161
	global_load_dwordx4 v[16:19], v50, s[4:5]
	global_load_dwordx4 v[20:23], v50, s[4:5] offset:64
	global_load_dwordx4 v[24:27], v51, s[16:17]
	global_load_dwordx4 v[28:31], v51, s[16:17] offset:64
	global_load_dwordx4 v[32:35], v51, s[16:17] offset:128
	global_load_dwordx4 v[36:39], v51, s[16:17] offset:192
	v_mul_lo_u32 v166, v47, s22
	v_or_b32_e32 v162, v166, v161
	v_add_u32_e32 v163, v162, v166
	s_barrier
	v_bfe_u32 v158, v46, 4, 2
	v_and_b32_e32 v52, 15, v46
	v_ashrrev_i32_e32 v53, 1, v46
	v_lshlrev_b32_e32 v54, 1, v46
	v_lshlrev_b32_e32 v46, 6, v46
	s_and_b32 s44, s30, 7
	s_add_i32 s37, s20, s37
	v_and_b32_e32 v46, 0xffffff00, v46
	v_and_b32_e32 v160, 0xffffffc0, v53
	v_lshl_add_u32 v46, s37, 14, v46
	v_lshl_add_u32 v49, s44, 12, v49
	v_mov_b32_e32 v0, 0
	v_and_or_b32 v159, v54, s23, v52
	v_or_b32_e32 v47, v160, v52
	v_or_b32_e32 v152, v46, v161
	v_or_b32_e32 v46, v49, v48
	s_mov_b32 s36, 1
	v_mov_b32_e32 v155, v153
	v_mov_b32_e32 v1, v0
	v_mov_b32_e32 v2, v0
	v_mov_b32_e32 v3, v0
	v_mov_b32_e32 v4, v0
	v_mov_b32_e32 v5, v0
	v_mov_b32_e32 v6, v0
	v_mov_b32_e32 v7, v0
	v_mov_b32_e32 v8, v0
	v_mov_b32_e32 v9, v0
	v_mov_b32_e32 v10, v0
	v_mov_b32_e32 v11, v0
	v_mov_b32_e32 v12, v0
	v_mov_b32_e32 v13, v0
	v_mov_b32_e32 v14, v0
	v_mov_b32_e32 v15, v0
	v_mov_b32_e32 v40, v0
	v_mov_b32_e32 v41, v0
	v_mov_b32_e32 v42, v0
	v_mov_b32_e32 v43, v0
	v_mov_b32_e32 v44, v0
	v_mov_b32_e32 v45, v0
	v_lshlrev_b32_e32 v164, 4, v158
	v_mul_u32_u24_e32 v165, 48, v159
	v_mul_lo_u32 v167, v47, 48
	v_lshlrev_b32_e32 v154, 1, v46
	v_mov_b64_e32 v[156:157], v[152:153]
	v_mov_b32_e32 v46, v0
	v_mov_b32_e32 v47, v0
	v_mov_b32_e32 v68, v0
	v_mov_b32_e32 v69, v0
	v_mov_b32_e32 v70, v0
	v_mov_b32_e32 v71, v0
	v_mov_b32_e32 v80, v0
	v_mov_b32_e32 v81, v0
	v_mov_b32_e32 v82, v0
	v_mov_b32_e32 v83, v0
	v_mov_b32_e32 v48, v0
	v_mov_b32_e32 v49, v0
	v_mov_b32_e32 v52, v0
	v_mov_b32_e32 v53, v0
	v_mov_b32_e32 v54, v0
	v_mov_b32_e32 v55, v0
	v_mov_b32_e32 v56, v0
	v_mov_b32_e32 v57, v0
	v_mov_b32_e32 v58, v0
	s_waitcnt vmcnt(5)
	ds_write_b128 v162, v[16:19]
	s_waitcnt vmcnt(4)
	ds_write_b128 v162, v[20:23] offset:96
	s_waitcnt vmcnt(3)
	ds_write_b128 v163, v[24:27] offset:12288
	s_waitcnt vmcnt(2)
	ds_write_b128 v163, v[28:31] offset:12384
	s_waitcnt vmcnt(1)
	ds_write_b128 v163, v[32:35] offset:12480
	s_waitcnt vmcnt(0)
	ds_write_b128 v163, v[36:39] offset:12576
	s_waitcnt lgkmcnt(0)
	s_barrier
	global_load_dwordx4 v[20:23], v50, s[8:9]
	global_load_dwordx4 v[16:19], v50, s[8:9] offset:64
	global_load_dwordx4 v[36:39], v51, s[6:7]
	global_load_dwordx4 v[32:35], v51, s[6:7] offset:64
	global_load_dwordx4 v[28:31], v51, s[6:7] offset:128
	global_load_dwordx4 v[24:27], v51, s[6:7] offset:192
	v_mov_b32_e32 v50, v0
	v_mov_b32_e32 v51, v0
	v_mov_b32_e32 v59, v0
	v_mov_b32_e32 v64, v0
	v_mov_b32_e32 v65, v0
	v_mov_b32_e32 v66, v0
	v_mov_b32_e32 v67, v0
	v_mov_b32_e32 v76, v0
	v_mov_b32_e32 v77, v0
	v_mov_b32_e32 v78, v0
	v_mov_b32_e32 v79, v0
	v_mov_b32_e32 v88, v0
	v_mov_b32_e32 v89, v0
	v_mov_b32_e32 v90, v0
	v_mov_b32_e32 v91, v0
	v_mov_b32_e32 v100, v0
	v_mov_b32_e32 v101, v0
	v_mov_b32_e32 v102, v0
	v_mov_b32_e32 v103, v0
	v_mov_b32_e32 v112, v0
	v_mov_b32_e32 v113, v0
	v_mov_b32_e32 v114, v0
	v_mov_b32_e32 v115, v0
	v_mov_b32_e32 v60, v0
	v_mov_b32_e32 v61, v0
	v_mov_b32_e32 v62, v0
	v_mov_b32_e32 v63, v0
	v_mov_b32_e32 v72, v0
	v_mov_b32_e32 v73, v0
	v_mov_b32_e32 v74, v0
	v_mov_b32_e32 v75, v0
	v_mov_b32_e32 v84, v0
	v_mov_b32_e32 v85, v0
	v_mov_b32_e32 v86, v0
	v_mov_b32_e32 v87, v0
	v_mov_b32_e32 v96, v0
	v_mov_b32_e32 v97, v0
	v_mov_b32_e32 v98, v0
	v_mov_b32_e32 v99, v0
	v_mov_b32_e32 v108, v0
	v_mov_b32_e32 v109, v0
	v_mov_b32_e32 v110, v0
	v_mov_b32_e32 v111, v0
	v_mov_b32_e32 v120, v0
	v_mov_b32_e32 v121, v0
	v_mov_b32_e32 v122, v0
	v_mov_b32_e32 v123, v0
	v_mov_b32_e32 v128, v0
	v_mov_b32_e32 v129, v0
	v_mov_b32_e32 v130, v0
	v_mov_b32_e32 v131, v0
	v_mov_b32_e32 v136, v0
	v_mov_b32_e32 v137, v0
	v_mov_b32_e32 v138, v0
	v_mov_b32_e32 v139, v0
	v_mov_b32_e32 v92, v0
	v_mov_b32_e32 v93, v0
	v_mov_b32_e32 v94, v0
	v_mov_b32_e32 v95, v0
	v_mov_b32_e32 v104, v0
	v_mov_b32_e32 v105, v0
	v_mov_b32_e32 v106, v0
	v_mov_b32_e32 v107, v0
	v_mov_b32_e32 v116, v0
	v_mov_b32_e32 v117, v0
	v_mov_b32_e32 v118, v0
	v_mov_b32_e32 v119, v0
	v_mov_b32_e32 v124, v0
	v_mov_b32_e32 v125, v0
	v_mov_b32_e32 v126, v0
	v_mov_b32_e32 v127, v0
	v_mov_b32_e32 v132, v0
	v_mov_b32_e32 v133, v0
	v_mov_b32_e32 v134, v0
	v_mov_b32_e32 v135, v0
	v_mov_b32_e32 v140, v0
	v_mov_b32_e32 v141, v0
	v_mov_b32_e32 v142, v0
	v_mov_b32_e32 v143, v0
	v_mov_b32_e32 v144, v0
	v_mov_b32_e32 v145, v0
	v_mov_b32_e32 v146, v0
	v_mov_b32_e32 v147, v0
	v_mov_b32_e32 v148, v0
	v_mov_b32_e32 v149, v0
	v_mov_b32_e32 v150, v0
	v_mov_b32_e32 v151, v0
	s_add_u32 s98, s42, s24
	s_addc_u32 s99, s43, 0
	s_add_u32 s100, s42, s25
	s_addc_u32 s101, s43, 0
; DI f32x4 mfma16(bf16x8 a, bf16x8 b, f32x4 c) { return __builtin_amdgcn_mfma_f32_16x16x32_bf16(a, b, c, 0, 0, 0); }
; template <int NI, class XL, class EP>
; DI void gemm_tile(const u16* __restrict__ W, int ldw, int f0, int t0, int K, XL xl, EP ep, unsigned char* smem) {
;     ...
;   for (int it = 0; it < nk; ++it) {
;     const u16* Ws = S0 + (it & 1) * BUF; const u16* Xs = Ws + 128 * LST;
;     __builtin_amdgcn_s_setprio(1);
;     bf16x8 a[4];
; #pragma unroll
;     for (int mi = 0; mi < 4; ++mi) a[mi] = *(const bf16x8*)(Ws + (wf * 64 + mi * 16 + lr) * LST + lq * 8);
; #pragma unroll
;     for (int ni = 0; ni < NI; ++ni) {
;       const bf16x8 b = *(const bf16x8*)(Xs + (wt * (NI * 16) + ni * 16 + lr) * LST + lq * 8);
; #pragma unroll
;       for (int mi = 0; mi < 4; ++mi) acc[mi][ni] = mfma16(a[mi], b, acc[mi][ni]);
;     }
;     __builtin_amdgcn_sched_group_barrier(0x100, 6, 0);
; #pragma unroll
;     for (int ni = 0; ni < NI; ++ni) { __builtin_amdgcn_sched_group_barrier(0x008, 4, 0); if (ni + 2 < NI) __builtin_amdgcn_sched_group_barrier(0x100, 1, 0); }
;     __builtin_amdgcn_s_setprio(0);
;     if (it + 1 < nk) lstore((it + 1) & 1);
;     if (it + 2 < nk) gload(it + 2);
;     __syncthreads();
.LBB0_812:
	s_bitcmp1_b32 s36, 0
	s_cselect_b32 s37, 0, 0x9000
	s_setprio 1
	v_or_b32_e32 v152, s37, v164
	v_lshl_add_u32 v184, v167, 1, v152
	ds_read_b128 v[168:171], v184
	ds_read_b128 v[172:175], v184 offset:1536
	ds_read_b128 v[180:183], v184 offset:3072
	ds_read_b128 v[184:187], v184 offset:4608
	v_lshl_add_u32 v152, v165, 1, v152
	ds_read_b128 v[176:179], v152 offset:12288
	ds_read_b128 v[188:191], v152 offset:13824
	s_xor_b32 s37, s37, 0x9000
	v_add3_u32 v220, v166, s37, v161
	s_waitcnt lgkmcnt(1)
	v_mfma_f32_16x16x32_bf16 v[148:151], v[168:171], v[176:179], v[148:151]
	v_mfma_f32_16x16x32_bf16 v[136:139], v[172:175], v[176:179], v[136:139]
	v_mfma_f32_16x16x32_bf16 v[112:115], v[180:183], v[176:179], v[112:115]
	v_mfma_f32_16x16x32_bf16 v[80:83], v[184:187], v[176:179], v[80:83]
	ds_read_b128 v[176:179], v152 offset:15360
	s_waitcnt vmcnt(5)
	ds_write_b128 v220, v[20:23]
	s_waitcnt lgkmcnt(2)
	v_mfma_f32_16x16x32_bf16 v[144:147], v[168:171], v[188:191], v[144:147]
	v_mfma_f32_16x16x32_bf16 v[128:131], v[172:175], v[188:191], v[128:131]
	v_mfma_f32_16x16x32_bf16 v[100:103], v[180:183], v[188:191], v[100:103]
	v_mfma_f32_16x16x32_bf16 v[68:71], v[184:187], v[188:191], v[68:71]
	ds_read_b128 v[188:191], v152 offset:16896
	s_waitcnt vmcnt(4)
	ds_write_b128 v220, v[16:19] offset:96
	v_add_u32_e32 v220, v220, v166
	global_load_dwordx4 v[20:23], v154, s[98:99]
	global_load_dwordx4 v[16:19], v154, s[98:99] offset:64
	s_waitcnt lgkmcnt(3)
	v_mfma_f32_16x16x32_bf16 v[140:143], v[168:171], v[176:179], v[140:143]
	v_mfma_f32_16x16x32_bf16 v[120:123], v[172:175], v[176:179], v[120:123]
	v_mfma_f32_16x16x32_bf16 v[88:91], v[180:183], v[176:179], v[88:91]
	v_mfma_f32_16x16x32_bf16 v[44:47], v[184:187], v[176:179], v[44:47]
	ds_read_b128 v[176:179], v152 offset:18432
	s_waitcnt vmcnt(5)
	ds_write_b128 v220, v[36:39] offset:12288
	global_load_dwordx4 v[36:39], v156, s[100:101] offset:2048
	s_waitcnt lgkmcnt(3)
	v_mfma_f32_16x16x32_bf16 v[132:135], v[168:171], v[188:191], v[132:135]
	v_mfma_f32_16x16x32_bf16 v[108:111], v[172:175], v[188:191], v[108:111]
	v_mfma_f32_16x16x32_bf16 v[76:79], v[180:183], v[188:191], v[76:79]
	v_mfma_f32_16x16x32_bf16 v[40:43], v[184:187], v[188:191], v[40:43]
	ds_read_b128 v[188:191], v152 offset:19968
	s_waitcnt vmcnt(5)
	ds_write_b128 v220, v[32:35] offset:12384
	global_load_dwordx4 v[32:35], v156, s[100:101] offset:2112
	s_waitcnt lgkmcnt(3)
	v_mfma_f32_16x16x32_bf16 v[124:127], v[168:171], v[176:179], v[124:127]
	v_mfma_f32_16x16x32_bf16 v[96:99], v[172:175], v[176:179], v[96:99]
	v_mfma_f32_16x16x32_bf16 v[64:67], v[180:183], v[176:179], v[64:67]
	v_mfma_f32_16x16x32_bf16 v[12:15], v[184:187], v[176:179], v[12:15]
	ds_read_b128 v[176:179], v152 offset:21504
	s_waitcnt vmcnt(5)
	ds_write_b128 v220, v[28:31] offset:12480
	global_load_dwordx4 v[28:31], v156, s[100:101] offset:2176
	s_waitcnt lgkmcnt(3)
	v_mfma_f32_16x16x32_bf16 v[116:119], v[168:171], v[188:191], v[116:119]
	v_mfma_f32_16x16x32_bf16 v[84:87], v[172:175], v[188:191], v[84:87]
	v_mfma_f32_16x16x32_bf16 v[56:59], v[180:183], v[188:191], v[56:59]
	v_mfma_f32_16x16x32_bf16 v[8:11], v[184:187], v[188:191], v[8:11]
	ds_read_b128 v[188:191], v152 offset:23040
	s_waitcnt vmcnt(5)
	ds_write_b128 v220, v[24:27] offset:12576
	global_load_dwordx4 v[24:27], v156, s[100:101] offset:2240
	s_waitcnt lgkmcnt(3)
	v_mfma_f32_16x16x32_bf16 v[104:107], v[168:171], v[176:179], v[104:107]
	v_mfma_f32_16x16x32_bf16 v[72:75], v[172:175], v[176:179], v[72:75]
	v_mfma_f32_16x16x32_bf16 v[52:55], v[180:183], v[176:179], v[52:55]
	v_mfma_f32_16x16x32_bf16 v[4:7], v[184:187], v[176:179], v[4:7]
	s_add_u32 s98, s98, s18
	s_addc_u32 s99, s99, s19
	s_add_u32 s100, s100, s10
	s_addc_u32 s101, s101, s11
	s_add_i32 s36, s36, 1
	s_waitcnt lgkmcnt(1)
	v_mfma_f32_16x16x32_bf16 v[92:95], v[168:171], v[188:191], v[92:95]
	v_mfma_f32_16x16x32_bf16 v[60:63], v[172:175], v[188:191], v[60:63]
	v_mfma_f32_16x16x32_bf16 v[48:51], v[180:183], v[188:191], v[48:51]
	v_mfma_f32_16x16x32_bf16 v[0:3], v[184:187], v[188:191], v[0:3]
	s_setprio 0
	s_cmp_lg_u32 s36, 31
	s_waitcnt lgkmcnt(0)
	s_barrier
	s_cbranch_scc1 .LBB0_812
	s_setprio 1
	v_lshl_add_u32 v152, v167, 1, v164
	ds_read_b128 v[154:157], v152
	v_lshl_add_u32 v161, v165, 1, v164
	ds_read_b128 v[164:167], v152 offset:1536
	ds_read_b128 v[172:175], v152 offset:3072
	ds_read_b128 v[176:179], v152 offset:4608
	ds_read_b128 v[168:171], v161 offset:12288
	ds_read_b128 v[180:183], v161 offset:13824
	s_waitcnt lgkmcnt(1)
	v_mfma_f32_16x16x32_bf16 v[148:151], v[154:157], v[168:171], v[148:151]
	v_mfma_f32_16x16x32_bf16 v[136:139], v[164:167], v[168:171], v[136:139]
	v_mfma_f32_16x16x32_bf16 v[112:115], v[172:175], v[168:171], v[112:115]
	v_mfma_f32_16x16x32_bf16 v[80:83], v[176:179], v[168:171], v[80:83]
	ds_read_b128 v[168:171], v161 offset:15360
	s_waitcnt lgkmcnt(1)
	v_mfma_f32_16x16x32_bf16 v[144:147], v[154:157], v[180:183], v[144:147]
	v_mfma_f32_16x16x32_bf16 v[128:131], v[164:167], v[180:183], v[128:131]
	v_mfma_f32_16x16x32_bf16 v[100:103], v[172:175], v[180:183], v[100:103]
	v_mfma_f32_16x16x32_bf16 v[68:71], v[176:179], v[180:183], v[68:71]
	ds_read_b128 v[180:183], v161 offset:16896
	s_waitcnt lgkmcnt(1)
	v_mfma_f32_16x16x32_bf16 v[140:143], v[154:157], v[168:171], v[140:143]
	v_mfma_f32_16x16x32_bf16 v[120:123], v[164:167], v[168:171], v[120:123]
	v_mfma_f32_16x16x32_bf16 v[184:187], v[172:175], v[168:171], v[88:91]
	v_mfma_f32_16x16x32_bf16 v[44:47], v[176:179], v[168:171], v[44:47]
	s_nop 1
	ds_read_b128 v[88:91], v161 offset:18432
	s_waitcnt lgkmcnt(1)
; DI f32x4 mfma16(bf16x8 a, bf16x8 b, f32x4 c) { return __builtin_amdgcn_mfma_f32_16x16x32_bf16(a, b, c, 0, 0, 0); }
; template <int NI, class XL, class EP>
; DI void gemm_tile(const u16* __restrict__ W, int ldw, int f0, int t0, int K, XL xl, EP ep, unsigned char* smem) {
;     ...
;   for (int it = 0; it < nk; ++it) {
;     const u16* Ws = S0 + (it & 1) * BUF; const u16* Xs = Ws + 128 * LST;
;     __builtin_amdgcn_s_setprio(1);
;     bf16x8 a[4];
; #pragma unroll
;     for (int mi = 0; mi < 4; ++mi) a[mi] = *(const bf16x8*)(Ws + (wf * 64 + mi * 16 + lr) * LST + lq * 8);
; #pragma unroll
;     for (int ni = 0; ni < NI; ++ni) {
;       const bf16x8 b = *(const bf16x8*)(Xs + (wt * (NI * 16) + ni * 16 + lr) * LST + lq * 8);
; #pragma unroll
;       for (int mi = 0; mi < 4; ++mi) acc[mi][ni] = mfma16(a[mi], b, acc[mi][ni]);
;     }
;     __builtin_amdgcn_sched_group_barrier(0x100, 6, 0);
; #pragma unroll
;     for (int ni = 0; ni < NI; ++ni) { __builtin_amdgcn_sched_group_barrier(0x008, 4, 0); if (ni + 2 < NI) __builtin_amdgcn_sched_group_barrier(0x100, 1, 0); }
;     __builtin_amdgcn_s_setprio(0);
;     if (it + 1 < nk) lstore((it + 1) & 1);
;     if (it + 2 < nk) gload(it + 2);
;     __syncthreads();
;   }
;   ep(acc, f0 + wf * 64, t0 + wt * (NI * 16), lr, lq, wf, wt);
; DI void phase6(const Params& p, const Sched& sched, unsigned char* smem) {
;     ...
;       const int b = tb >> 11;
;       __syncthreads();
; #pragma unroll
;       for (int mi = 0; mi < 4; ++mi) {
;         const int f = fb + mi * 16 + lq * 4; const float4 gm = *(const float4*)(mod + (size_t)b * 6144 + 2048 + f);
	v_mfma_f32_16x16x32_bf16 v[132:135], v[154:157], v[180:183], v[132:135]
	v_mfma_f32_16x16x32_bf16 v[168:171], v[164:167], v[180:183], v[108:111]
	v_mfma_f32_16x16x32_bf16 v[188:191], v[172:175], v[180:183], v[76:79]
	v_mfma_f32_16x16x32_bf16 v[180:183], v[176:179], v[180:183], v[40:43]
	s_nop 2
	ds_read_b128 v[40:43], v161 offset:19968
	s_waitcnt lgkmcnt(1)
	v_mfma_f32_16x16x32_bf16 v[124:127], v[154:157], v[88:91], v[124:127]
	v_mfma_f32_16x16x32_bf16 v[192:195], v[164:167], v[88:91], v[96:99]
	v_mfma_f32_16x16x32_bf16 v[196:199], v[172:175], v[88:91], v[64:67]
	v_mfma_f32_16x16x32_bf16 v[200:203], v[176:179], v[88:91], v[12:15]
	s_nop 2
	ds_read_b128 v[12:15], v161 offset:21504
	s_waitcnt lgkmcnt(1)
	v_mfma_f32_16x16x32_bf16 v[116:119], v[154:157], v[40:43], v[116:119]
	v_mfma_f32_16x16x32_bf16 v[204:207], v[164:167], v[40:43], v[84:87]
	v_mfma_f32_16x16x32_bf16 v[56:59], v[172:175], v[40:43], v[56:59]
	v_mfma_f32_16x16x32_bf16 v[208:211], v[176:179], v[40:43], v[8:11]
	s_nop 2
	ds_read_b128 v[8:11], v161 offset:23040
	s_waitcnt lgkmcnt(1)
	v_mfma_f32_16x16x32_bf16 v[212:215], v[154:157], v[12:15], v[104:107]
	v_mfma_f32_16x16x32_bf16 v[72:75], v[164:167], v[12:15], v[72:75]
	v_mfma_f32_16x16x32_bf16 v[220:223], v[172:175], v[12:15], v[52:55]
	v_mfma_f32_16x16x32_bf16 v[224:227], v[176:179], v[12:15], v[4:7]
	s_waitcnt lgkmcnt(0)
	v_mfma_f32_16x16x32_bf16 v[154:157], v[154:157], v[8:11], v[92:95]
	v_mfma_f32_16x16x32_bf16 v[60:63], v[164:167], v[8:11], v[60:63]
	v_mfma_f32_16x16x32_bf16 v[164:167], v[172:175], v[8:11], v[48:51]
	v_mfma_f32_16x16x32_bf16 v[172:175], v[176:179], v[8:11], v[0:3]
	s_setprio 0
	s_waitcnt vmcnt(5)
	ds_write_b128 v162, v[20:23] offset:36864
	s_waitcnt vmcnt(4)
	ds_write_b128 v162, v[16:19] offset:36960
	s_waitcnt vmcnt(3)
	ds_write_b128 v163, v[36:39] offset:49152
	s_waitcnt vmcnt(2)
	ds_write_b128 v163, v[32:35] offset:49248
	s_waitcnt vmcnt(1)
	ds_write_b128 v163, v[28:31] offset:49344
	s_waitcnt vmcnt(0)
	ds_write_b128 v163, v[24:27] offset:49440
	s_waitcnt lgkmcnt(0)
	s_barrier
	s_lshl_b32 s34, s34, 7
	s_setprio 1
	ds_read_b128 v[28:31], v152 offset:36864
	ds_read_b128 v[176:179], v152 offset:38400
	ds_read_b128 v[228:231], v152 offset:39936
	ds_read_b128 v[232:235], v152 offset:41472
	ds_read_b128 v[0:3], v161 offset:49152
	ds_read_b128 v[4:7], v161 offset:50688
	s_waitcnt lgkmcnt(1)
	v_mfma_f32_16x16x32_bf16 v[88:91], v[28:31], v[0:3], v[148:151]
	v_mfma_f32_16x16x32_bf16 v[64:67], v[176:179], v[0:3], v[136:139]
	v_mfma_f32_16x16x32_bf16 v[32:35], v[228:231], v[0:3], v[112:115]
	v_mfma_f32_16x16x32_bf16 v[0:3], v[232:235], v[0:3], v[80:83]
	ds_read_b128 v[8:11], v161 offset:52224
	s_waitcnt lgkmcnt(1)
	v_mfma_f32_16x16x32_bf16 v[96:99], v[28:31], v[4:7], v[144:147]
	v_mfma_f32_16x16x32_bf16 v[76:79], v[176:179], v[4:7], v[128:131]
	v_mfma_f32_16x16x32_bf16 v[36:39], v[228:231], v[4:7], v[100:103]
	v_mfma_f32_16x16x32_bf16 v[4:7], v[232:235], v[4:7], v[68:71]
	ds_read_b128 v[12:15], v161 offset:53760
	s_waitcnt lgkmcnt(1)
	v_mfma_f32_16x16x32_bf16 v[104:107], v[28:31], v[8:11], v[140:143]
	v_mfma_f32_16x16x32_bf16 v[84:87], v[176:179], v[8:11], v[120:123]
	v_mfma_f32_16x16x32_bf16 v[40:43], v[228:231], v[8:11], v[184:187]
	v_mfma_f32_16x16x32_bf16 v[8:11], v[232:235], v[8:11], v[44:47]
	ds_read_b128 v[16:19], v161 offset:55296
	s_waitcnt lgkmcnt(1)
	v_mfma_f32_16x16x32_bf16 v[108:111], v[28:31], v[12:15], v[132:135]
	v_mfma_f32_16x16x32_bf16 v[92:95], v[176:179], v[12:15], v[168:171]
	v_mfma_f32_16x16x32_bf16 v[44:47], v[228:231], v[12:15], v[188:191]
	v_mfma_f32_16x16x32_bf16 v[12:15], v[232:235], v[12:15], v[180:183]
	ds_read_b128 v[20:23], v161 offset:56832
	s_waitcnt lgkmcnt(1)
	v_mfma_f32_16x16x32_bf16 v[112:115], v[28:31], v[16:19], v[124:127]
	v_mfma_f32_16x16x32_bf16 v[100:103], v[176:179], v[16:19], v[192:195]
	v_mfma_f32_16x16x32_bf16 v[48:51], v[228:231], v[16:19], v[196:199]
	v_mfma_f32_16x16x32_bf16 v[16:19], v[232:235], v[16:19], v[200:203]
	ds_read_b128 v[24:27], v161 offset:58368
	s_waitcnt lgkmcnt(1)
	v_mfma_f32_16x16x32_bf16 v[116:119], v[28:31], v[20:23], v[116:119]
	v_mfma_f32_16x16x32_bf16 v[68:71], v[176:179], v[20:23], v[204:207]
	v_mfma_f32_16x16x32_bf16 v[52:55], v[228:231], v[20:23], v[56:59]
	v_mfma_f32_16x16x32_bf16 v[20:23], v[232:235], v[20:23], v[208:211]
	ds_read_b128 v[128:131], v161 offset:59904
	s_waitcnt lgkmcnt(1)
	v_mfma_f32_16x16x32_bf16 v[120:123], v[28:31], v[24:27], v[212:215]
	v_mfma_f32_16x16x32_bf16 v[80:83], v[176:179], v[24:27], v[72:75]
	v_mfma_f32_16x16x32_bf16 v[56:59], v[228:231], v[24:27], v[220:223]
	v_mfma_f32_16x16x32_bf16 v[24:27], v[232:235], v[24:27], v[224:227]
	s_waitcnt lgkmcnt(0)
	v_mfma_f32_16x16x32_bf16 v[124:127], v[28:31], v[128:131], v[154:157]
	v_mfma_f32_16x16x32_bf16 v[72:75], v[176:179], v[128:131], v[60:63]
	v_mfma_f32_16x16x32_bf16 v[60:63], v[228:231], v[128:131], v[164:167]
	v_mfma_f32_16x16x32_bf16 v[28:31], v[232:235], v[128:131], v[172:175]
	s_setprio 0
	s_ashr_i32 s35, s35, 3
	v_add_u32_e32 v128, s34, v160
	s_mul_hi_i32 s37, s35, 0x6000
	s_mulk_i32 s35, 0x6000
	v_lshl_or_b32 v128, v158, 2, v128
	s_add_u32 s36, s72, s35
	s_addc_u32 s37, s73, s37
	v_ashrrev_i32_e32 v129, 31, v128
	v_lshl_add_u64 v[128:129], v[128:129], 2, s[36:37]
	v_add_co_u32_e32 v140, vcc, s26, v128
	v_mul_u32_u24_e32 v138, 0x88, v159
	s_nop 0
	v_addc_co_u32_e32 v141, vcc, 0, v129, vcc
	v_lshlrev_b32_e32 v136, 1, v160
	v_lshlrev_b32_e32 v137, 3, v158
	v_lshlrev_b32_e32 v138, 1, v138
	s_barrier
	s_barrier
; DI void store4(u16* dst, f32x4 v) { uint2 w; w.x = cvtpk(v[0], v[1]); w.y = cvtpk(v[2], v[3]); *(uint2*)dst = w; }
; DI void phase6(const Params& p, const Sched& sched, unsigned char* smem) {
;     ...
; #pragma unroll
;       for (int mi = 0; mi < 4; ++mi) {
;         const int f = fb + mi * 16 + lq * 4; const float4 gm = *(const float4*)(mod + (size_t)b * 6144 + 2048 + f);
; #pragma unroll
;         for (int ni = 0; ni < 8; ++ni) {
;           const f32x4 o = {gm.x * acc[mi][ni][0], gm.y * acc[mi][ni][1], gm.z * acc[mi][ni][2], gm.w * acc[mi][ni][3]};
;           store4(Ls + (wt * 128 + ni * 16 + lr) * EST + wf * 64 + mi * 16 + lq * 4, o);
;         }
;       }
;       __syncthreads();
	global_load_dwordx4 v[128:131], v[140:141], off
	global_load_dwordx4 v[132:135], v[140:141], off offset:64
	v_add3_u32 v144, v136, v137, v138
	global_load_dwordx4 v[136:139], v[140:141], off offset:128
	v_add_u32_e32 v145, 0x1000, v144
	global_load_dwordx4 v[140:143], v[140:141], off offset:192
	v_add_u32_e32 v146, 0x2000, v144
	v_add_u32_e32 v147, 0x3000, v144
	v_add_u32_e32 v148, 0x4000, v144
	s_add_i32 s31, s31, s78
	s_add_i32 s30, s30, s78
	s_cmp_gt_i32 s31, 63
	s_waitcnt vmcnt(3)
	v_pk_mul_f32 v[88:89], v[88:89], v[128:129]
	v_pk_mul_f32 v[90:91], v[90:91], v[130:131]
	v_pk_mul_f32 v[96:97], v[96:97], v[128:129]
	s_waitcnt vmcnt(1)
	v_pk_mul_f32 v[32:33], v[32:33], v[136:137]
	v_pk_mul_f32 v[34:35], v[34:35], v[138:139]
	s_waitcnt vmcnt(0)
	v_pk_mul_f32 v[0:1], v[0:1], v[140:141]
	v_pk_mul_f32 v[2:3], v[2:3], v[142:143]
	v_cvt_pk_bf16_f32 v32, v32, v33
	v_cvt_pk_bf16_f32 v33, v34, v35
	v_cvt_pk_bf16_f32 v0, v0, v1
	v_cvt_pk_bf16_f32 v1, v2, v3
	v_pk_mul_f32 v[34:35], v[36:37], v[136:137]
	v_pk_mul_f32 v[36:37], v[38:39], v[138:139]
	ds_write2_b64 v144, v[32:33], v[0:1] offset0:8 offset1:12
	v_pk_mul_f32 v[0:1], v[4:5], v[140:141]
	v_pk_mul_f32 v[2:3], v[6:7], v[142:143]
	v_cvt_pk_bf16_f32 v34, v34, v35
	v_cvt_pk_bf16_f32 v35, v36, v37
	v_cvt_pk_bf16_f32 v0, v0, v1
	v_cvt_pk_bf16_f32 v1, v2, v3
	v_pk_mul_f32 v[36:37], v[40:41], v[136:137]
	v_pk_mul_f32 v[38:39], v[42:43], v[138:139]
	ds_write2_b64 v145, v[34:35], v[0:1] offset0:40 offset1:44
	v_pk_mul_f32 v[0:1], v[8:9], v[140:141]
	v_pk_mul_f32 v[2:3], v[10:11], v[142:143]
	v_cvt_pk_bf16_f32 v36, v36, v37
	v_cvt_pk_bf16_f32 v37, v38, v39
	v_cvt_pk_bf16_f32 v0, v0, v1
	v_cvt_pk_bf16_f32 v1, v2, v3
	v_pk_mul_f32 v[38:39], v[44:45], v[136:137]
	v_pk_mul_f32 v[40:41], v[46:47], v[138:139]
	ds_write2_b64 v146, v[36:37], v[0:1] offset0:72 offset1:76
	v_pk_mul_f32 v[0:1], v[12:13], v[140:141]
	v_pk_mul_f32 v[2:3], v[14:15], v[142:143]
	v_cvt_pk_bf16_f32 v38, v38, v39
	v_cvt_pk_bf16_f32 v39, v40, v41
	v_cvt_pk_bf16_f32 v0, v0, v1
	v_cvt_pk_bf16_f32 v1, v2, v3
	v_pk_mul_f32 v[98:99], v[98:99], v[130:131]
	v_pk_mul_f32 v[64:65], v[64:65], v[132:133]
	v_pk_mul_f32 v[66:67], v[66:67], v[134:135]
	v_pk_mul_f32 v[76:77], v[76:77], v[132:133]
	v_pk_mul_f32 v[78:79], v[78:79], v[134:135]
	v_pk_mul_f32 v[40:41], v[48:49], v[136:137]
	v_pk_mul_f32 v[42:43], v[50:51], v[138:139]
	ds_write2_b64 v147, v[38:39], v[0:1] offset0:104 offset1:108
	v_pk_mul_f32 v[0:1], v[16:17], v[140:141]
	v_pk_mul_f32 v[2:3], v[18:19], v[142:143]
	v_cvt_pk_bf16_f32 v88, v88, v89
	v_cvt_pk_bf16_f32 v89, v90, v91
	v_cvt_pk_bf16_f32 v90, v96, v97
	v_cvt_pk_bf16_f32 v91, v98, v99
	v_cvt_pk_bf16_f32 v64, v64, v65
	v_cvt_pk_bf16_f32 v65, v66, v67
	v_cvt_pk_bf16_f32 v66, v76, v77
	v_cvt_pk_bf16_f32 v67, v78, v79
	v_cvt_pk_bf16_f32 v40, v40, v41
	v_cvt_pk_bf16_f32 v41, v42, v43
	v_cvt_pk_bf16_f32 v0, v0, v1
	v_cvt_pk_bf16_f32 v1, v2, v3
	v_pk_mul_f32 v[106:107], v[106:107], v[130:131]
	v_pk_mul_f32 v[116:117], v[116:117], v[128:129]
	v_pk_mul_f32 v[118:119], v[118:119], v[130:131]
	ds_write2_b64 v144, v[88:89], v[64:65] offset1:4
	ds_write2_b64 v145, v[90:91], v[66:67] offset0:32 offset1:36
	v_pk_mul_f32 v[64:65], v[68:69], v[132:133]
	v_pk_mul_f32 v[66:67], v[70:71], v[134:135]
	v_pk_mul_f32 v[42:43], v[52:53], v[136:137]
	v_pk_mul_f32 v[44:45], v[54:55], v[138:139]
	ds_write2_b64 v148, v[40:41], v[0:1] offset0:136 offset1:140
	v_pk_mul_f32 v[0:1], v[20:21], v[140:141]
	v_pk_mul_f32 v[2:3], v[22:23], v[142:143]
	v_cvt_pk_bf16_f32 v97, v106, v107
	v_cvt_pk_bf16_f32 v106, v116, v117
	v_cvt_pk_bf16_f32 v107, v118, v119
	v_cvt_pk_bf16_f32 v64, v64, v65
	v_cvt_pk_bf16_f32 v65, v66, v67
	v_add_u32_e32 v68, 0x5000, v144
	v_cvt_pk_bf16_f32 v42, v42, v43
	v_cvt_pk_bf16_f32 v43, v44, v45
	v_cvt_pk_bf16_f32 v0, v0, v1
	v_cvt_pk_bf16_f32 v1, v2, v3
	v_pk_mul_f32 v[108:109], v[108:109], v[128:129]
	v_pk_mul_f32 v[120:121], v[120:121], v[128:129]
	v_pk_mul_f32 v[122:123], v[122:123], v[130:131]
	ds_write2_b64 v68, v[106:107], v[64:65] offset0:160 offset1:164
	v_pk_mul_f32 v[64:65], v[80:81], v[132:133]
	v_pk_mul_f32 v[66:67], v[82:83], v[134:135]
	v_pk_mul_f32 v[44:45], v[56:57], v[136:137]
	v_pk_mul_f32 v[46:47], v[58:59], v[138:139]
	ds_write2_b64 v68, v[42:43], v[0:1] offset0:168 offset1:172
	v_pk_mul_f32 v[0:1], v[24:25], v[140:141]
	v_pk_mul_f32 v[2:3], v[26:27], v[142:143]
	v_cvt_pk_bf16_f32 v98, v108, v109
	v_cvt_pk_bf16_f32 v108, v120, v121
	v_cvt_pk_bf16_f32 v109, v122, v123
	v_cvt_pk_bf16_f32 v64, v64, v65
	v_cvt_pk_bf16_f32 v65, v66, v67
	v_add_u32_e32 v69, 0x6000, v144
	v_cvt_pk_bf16_f32 v44, v44, v45
	v_cvt_pk_bf16_f32 v45, v46, v47
	v_cvt_pk_bf16_f32 v0, v0, v1
	v_cvt_pk_bf16_f32 v1, v2, v3
	v_pk_mul_f32 v[104:105], v[104:105], v[128:129]
	v_pk_mul_f32 v[110:111], v[110:111], v[130:131]
	v_pk_mul_f32 v[112:113], v[112:113], v[128:129]
	v_pk_mul_f32 v[114:115], v[114:115], v[130:131]
	v_pk_mul_f32 v[124:125], v[124:125], v[128:129]
	v_pk_mul_f32 v[126:127], v[126:127], v[130:131]
	v_pk_mul_f32 v[84:85], v[84:85], v[132:133]
	v_pk_mul_f32 v[86:87], v[86:87], v[134:135]
	v_pk_mul_f32 v[92:93], v[92:93], v[132:133]
	v_pk_mul_f32 v[94:95], v[94:95], v[134:135]
	v_pk_mul_f32 v[100:101], v[100:101], v[132:133]
	v_pk_mul_f32 v[102:103], v[102:103], v[134:135]
	ds_write2_b64 v69, v[108:109], v[64:65] offset0:192 offset1:196
	v_pk_mul_f32 v[64:65], v[72:73], v[132:133]
	v_pk_mul_f32 v[66:67], v[74:75], v[134:135]
	v_pk_mul_f32 v[46:47], v[60:61], v[136:137]
	v_pk_mul_f32 v[48:49], v[62:63], v[138:139]
	ds_write2_b64 v69, v[44:45], v[0:1] offset0:200 offset1:204
	v_pk_mul_f32 v[0:1], v[28:29], v[140:141]
	v_pk_mul_f32 v[2:3], v[30:31], v[142:143]
	v_cvt_pk_bf16_f32 v96, v104, v105
	v_cvt_pk_bf16_f32 v99, v110, v111
	v_cvt_pk_bf16_f32 v104, v112, v113
	v_cvt_pk_bf16_f32 v105, v114, v115
	v_cvt_pk_bf16_f32 v110, v124, v125
	v_cvt_pk_bf16_f32 v111, v126, v127
	v_cvt_pk_bf16_f32 v76, v84, v85
	v_cvt_pk_bf16_f32 v77, v86, v87
	v_cvt_pk_bf16_f32 v78, v92, v93
	v_cvt_pk_bf16_f32 v79, v94, v95
	v_cvt_pk_bf16_f32 v84, v100, v101
	v_cvt_pk_bf16_f32 v85, v102, v103
	v_cvt_pk_bf16_f32 v64, v64, v65
	v_cvt_pk_bf16_f32 v65, v66, v67
	v_add_u32_e32 v66, 0x7000, v144
	v_cvt_pk_bf16_f32 v46, v46, v47
	v_cvt_pk_bf16_f32 v47, v48, v49
	v_cvt_pk_bf16_f32 v0, v0, v1
	v_cvt_pk_bf16_f32 v1, v2, v3
	v_mov_b32_e32 v2, v218
	ds_write2_b64 v146, v[96:97], v[76:77] offset0:64 offset1:68
	ds_write2_b64 v147, v[98:99], v[78:79] offset0:96 offset1:100
	ds_write2_b64 v148, v[104:105], v[84:85] offset0:128 offset1:132
	ds_write2_b64 v66, v[110:111], v[64:65] offset0:224 offset1:228
	ds_write2_b64 v66, v[46:47], v[0:1] offset0:232 offset1:236
	s_waitcnt lgkmcnt(0)
	s_barrier
; DI int tidx() { int t = __builtin_amdgcn_workitem_id_x(); asm volatile("" : "+v"(t)); return t; }
; DI unsigned cvtpk(float lo, float hi) { const f32x2_ v = {lo, hi}; return __builtin_bit_cast(unsigned, __builtin_convertvector(v, bf16x2_)); }
; DI float bflo(unsigned w) { return __uint_as_float(w << 16); }
; DI float bfhi(unsigned w) { return __uint_as_float(w & 0xffff0000u); }
; DI void phase6(const Params& p, const Sched& sched, unsigned char* smem) {
;     ...
;       const int tid = tidx();
; #pragma unroll
;       for (int i = 0; i < 16; ++i) {
;         const int c = tid + 256 * i, row = c >> 4, ch = (c & 15) * 8;
;         const size_t gi = (size_t)(tm * 256 + row) * 1024 + tn * 128 + ch;
;         const u32x4 sv = *(const u32x4*)(Ls + row * EST + ch);
;         const f32x4 x0 = *(const f32x4*)(p.x + gi), x1 = *(const f32x4*)(p.x + gi + 4);
;         u32x4 w;
;         w.x = cvtpk(x0[0] + bflo(sv.x), x0[1] + bfhi(sv.x)); w.y = cvtpk(x0[2] + bflo(sv.y), x0[3] + bfhi(sv.y));
;         w.z = cvtpk(x1[0] + bflo(sv.z), x1[1] + bfhi(sv.z)); w.w = cvtpk(x1[2] + bflo(sv.w), x1[3] + bfhi(sv.w));
;         *(u32x4*)(x1b + gi) = w;
;       }
	s_nop 0
	v_ashrrev_i32_e32 v3, 4, v2
	v_add_u32_e32 v4, s33, v3
	v_lshlrev_b32_e32 v0, 3, v2
	v_ashrrev_i32_e32 v5, 31, v4
	v_and_b32_e32 v1, 0x78, v0
	v_lshlrev_b64 v[16:17], 10, v[4:5]
	v_or3_b32 v16, v16, s34, v1
	v_lshl_add_u64 v[8:9], v[16:17], 2, s[76:77]
	global_load_dwordx4 v[4:7], v[8:9], off
	v_lshlrev_b32_e32 v0, 1, v1
	global_load_dwordx4 v[8:11], v[8:9], off offset:16
	v_mad_u64_u32 v[12:13], s[36:37], v3, s27, v[0:1]
	ds_read_b128 v[12:15], v12
	v_add_u32_e32 v3, 0x100, v2
	v_ashrrev_i32_e32 v3, 4, v3
	s_waitcnt lgkmcnt(0)
	v_lshlrev_b32_e32 v18, 16, v12
	v_and_b32_e32 v19, 0xffff0000, v12
	v_lshlrev_b32_e32 v12, 16, v13
	v_and_b32_e32 v13, 0xffff0000, v13
	s_waitcnt vmcnt(1)
	v_pk_add_f32 v[4:5], v[4:5], v[18:19]
	v_pk_add_f32 v[6:7], v[6:7], v[12:13]
	v_cvt_pk_bf16_f32 v4, v4, v5
	v_cvt_pk_bf16_f32 v5, v6, v7
	v_lshlrev_b32_e32 v6, 16, v14
	v_and_b32_e32 v7, 0xffff0000, v14
	s_waitcnt vmcnt(0)
	v_pk_add_f32 v[6:7], v[8:9], v[6:7]
	v_lshlrev_b32_e32 v8, 16, v15
	v_and_b32_e32 v9, 0xffff0000, v15
	v_pk_add_f32 v[8:9], v[10:11], v[8:9]
	v_cvt_pk_bf16_f32 v6, v6, v7
	v_cvt_pk_bf16_f32 v7, v8, v9
	v_lshl_add_u64 v[8:9], v[16:17], 1, s[12:13]
	global_store_dwordx4 v[8:9], v[4:7], off
	v_add_u32_e32 v12, 0x200, v2
	v_ashrrev_i32_e32 v26, 4, v12
	v_add_u32_e32 v4, s33, v3
	v_ashrrev_i32_e32 v5, 31, v4
	v_lshlrev_b64 v[16:17], 10, v[4:5]
	v_or3_b32 v16, v16, s34, v1
	v_lshl_add_u64 v[8:9], v[16:17], 2, s[76:77]
	global_load_dwordx4 v[4:7], v[8:9], off
	v_mad_u64_u32 v[12:13], s[36:37], v3, s27, v[0:1]
	global_load_dwordx4 v[8:11], v[8:9], off offset:16
	ds_read_b128 v[12:15], v12
	v_add_u32_e32 v18, s33, v26
	v_ashrrev_i32_e32 v19, 31, v18
	v_lshlrev_b64 v[18:19], 10, v[18:19]
	v_or3_b32 v18, v18, s34, v1
	s_waitcnt lgkmcnt(0)
	v_lshlrev_b32_e32 v22, 16, v12
	v_and_b32_e32 v23, 0xffff0000, v12
	v_lshlrev_b32_e32 v12, 16, v13
	v_and_b32_e32 v13, 0xffff0000, v13
	v_lshlrev_b32_e32 v24, 16, v14
	v_and_b32_e32 v25, 0xffff0000, v14
	v_lshlrev_b32_e32 v14, 16, v15
	v_and_b32_e32 v15, 0xffff0000, v15
	v_lshl_add_u64 v[16:17], v[16:17], 1, s[12:13]
	v_lshl_add_u64 v[20:21], v[18:19], 2, s[76:77]
	v_add_u32_e32 v3, 0x300, v2
	v_ashrrev_i32_e32 v3, 4, v3
	v_lshl_add_u64 v[18:19], v[18:19], 1, s[12:13]
	s_waitcnt vmcnt(1)
	v_pk_add_f32 v[4:5], v[4:5], v[22:23]
	v_pk_add_f32 v[6:7], v[6:7], v[12:13]
	v_cvt_pk_bf16_f32 v4, v4, v5
	s_waitcnt vmcnt(0)
	v_pk_add_f32 v[8:9], v[8:9], v[24:25]
	v_pk_add_f32 v[10:11], v[10:11], v[14:15]
	v_cvt_pk_bf16_f32 v5, v6, v7
	v_cvt_pk_bf16_f32 v6, v8, v9
	v_cvt_pk_bf16_f32 v7, v10, v11
	global_store_dwordx4 v[16:17], v[4:7], off
	global_load_dwordx4 v[4:7], v[20:21], off
	v_mad_u64_u32 v[12:13], s[36:37], v26, s27, v[0:1]
	global_load_dwordx4 v[8:11], v[20:21], off offset:16
	ds_read_b128 v[12:15], v12
	v_add_u32_e32 v16, s33, v3
	v_ashrrev_i32_e32 v17, 31, v16
	v_lshlrev_b64 v[16:17], 10, v[16:17]
	v_or3_b32 v16, v16, s34, v1
	s_waitcnt lgkmcnt(0)
	v_lshlrev_b32_e32 v22, 16, v12
	v_and_b32_e32 v23, 0xffff0000, v12
	v_lshlrev_b32_e32 v12, 16, v13
	v_and_b32_e32 v13, 0xffff0000, v13
	v_lshlrev_b32_e32 v24, 16, v14
	v_and_b32_e32 v25, 0xffff0000, v14
	v_lshlrev_b32_e32 v14, 16, v15
	v_and_b32_e32 v15, 0xffff0000, v15
	v_lshl_add_u64 v[20:21], v[16:17], 2, s[76:77]
	v_lshl_add_u64 v[16:17], v[16:17], 1, s[12:13]
	s_waitcnt vmcnt(1)
	v_pk_add_f32 v[4:5], v[4:5], v[22:23]
	v_pk_add_f32 v[6:7], v[6:7], v[12:13]
	v_cvt_pk_bf16_f32 v4, v4, v5
	s_waitcnt vmcnt(0)
	v_pk_add_f32 v[8:9], v[8:9], v[24:25]
	v_pk_add_f32 v[10:11], v[10:11], v[14:15]
	v_cvt_pk_bf16_f32 v5, v6, v7
	v_cvt_pk_bf16_f32 v6, v8, v9
	v_cvt_pk_bf16_f32 v7, v10, v11
	global_store_dwordx4 v[18:19], v[4:7], off
	global_load_dwordx4 v[4:7], v[20:21], off
	v_add_u32_e32 v12, 0x400, v2
	global_load_dwordx4 v[8:11], v[20:21], off offset:16
	v_ashrrev_i32_e32 v26, 4, v12
	v_mad_u64_u32 v[12:13], s[36:37], v3, s27, v[0:1]
	ds_read_b128 v[12:15], v12
	v_add_u32_e32 v18, s33, v26
	v_ashrrev_i32_e32 v19, 31, v18
	v_lshlrev_b64 v[18:19], 10, v[18:19]
	v_or3_b32 v18, v18, s34, v1
	s_waitcnt lgkmcnt(0)
	v_lshlrev_b32_e32 v22, 16, v12
	v_and_b32_e32 v23, 0xffff0000, v12
	v_lshlrev_b32_e32 v12, 16, v13
	v_and_b32_e32 v13, 0xffff0000, v13
	v_lshlrev_b32_e32 v24, 16, v14
	v_and_b32_e32 v25, 0xffff0000, v14
	v_lshlrev_b32_e32 v14, 16, v15
	v_and_b32_e32 v15, 0xffff0000, v15
	v_lshl_add_u64 v[20:21], v[18:19], 2, s[76:77]
	v_add_u32_e32 v3, 0x500, v2
	v_ashrrev_i32_e32 v3, 4, v3
	v_lshl_add_u64 v[18:19], v[18:19], 1, s[12:13]
	s_waitcnt vmcnt(1)
	v_pk_add_f32 v[4:5], v[4:5], v[22:23]
	v_pk_add_f32 v[6:7], v[6:7], v[12:13]
	s_waitcnt vmcnt(0)
	v_pk_add_f32 v[8:9], v[8:9], v[24:25]
	v_pk_add_f32 v[10:11], v[10:11], v[14:15]
	v_cvt_pk_bf16_f32 v4, v4, v5
	v_cvt_pk_bf16_f32 v5, v6, v7
	v_cvt_pk_bf16_f32 v6, v8, v9
	v_cvt_pk_bf16_f32 v7, v10, v11
	global_store_dwordx4 v[16:17], v[4:7], off
	global_load_dwordx4 v[4:7], v[20:21], off
	v_mad_u64_u32 v[12:13], s[36:37], v26, s27, v[0:1]
	global_load_dwordx4 v[8:11], v[20:21], off offset:16
	ds_read_b128 v[12:15], v12
	v_add_u32_e32 v16, s33, v3
	v_ashrrev_i32_e32 v17, 31, v16
	v_lshlrev_b64 v[16:17], 10, v[16:17]
	v_or3_b32 v16, v16, s34, v1
	s_waitcnt lgkmcnt(0)
	v_lshlrev_b32_e32 v22, 16, v12
	v_and_b32_e32 v23, 0xffff0000, v12
	v_lshlrev_b32_e32 v12, 16, v13
	v_and_b32_e32 v13, 0xffff0000, v13
	v_lshlrev_b32_e32 v24, 16, v14
	v_and_b32_e32 v25, 0xffff0000, v14
	v_lshlrev_b32_e32 v14, 16, v15
	v_and_b32_e32 v15, 0xffff0000, v15
	v_lshl_add_u64 v[20:21], v[16:17], 2, s[76:77]
	v_lshl_add_u64 v[16:17], v[16:17], 1, s[12:13]
	s_waitcnt vmcnt(1)
	v_pk_add_f32 v[4:5], v[4:5], v[22:23]
	v_pk_add_f32 v[6:7], v[6:7], v[12:13]
	v_cvt_pk_bf16_f32 v4, v4, v5
	s_waitcnt vmcnt(0)
; DI int tidx() { int t = __builtin_amdgcn_workitem_id_x(); asm volatile("" : "+v"(t)); return t; }
; DI unsigned cvtpk(float lo, float hi) { const f32x2_ v = {lo, hi}; return __builtin_bit_cast(unsigned, __builtin_convertvector(v, bf16x2_)); }
; DI float bflo(unsigned w) { return __uint_as_float(w << 16); }
; DI float bfhi(unsigned w) { return __uint_as_float(w & 0xffff0000u); }
; DI void phase6(const Params& p, const Sched& sched, unsigned char* smem) {
;     ...
;       const int tid = tidx();
; #pragma unroll
;       for (int i = 0; i < 16; ++i) {
;         const int c = tid + 256 * i, row = c >> 4, ch = (c & 15) * 8;
;         const size_t gi = (size_t)(tm * 256 + row) * 1024 + tn * 128 + ch;
;         const u32x4 sv = *(const u32x4*)(Ls + row * EST + ch);
;         const f32x4 x0 = *(const f32x4*)(p.x + gi), x1 = *(const f32x4*)(p.x + gi + 4);
;         u32x4 w;
;         w.x = cvtpk(x0[0] + bflo(sv.x), x0[1] + bfhi(sv.x)); w.y = cvtpk(x0[2] + bflo(sv.y), x0[3] + bfhi(sv.y));
;         w.z = cvtpk(x1[0] + bflo(sv.z), x1[1] + bfhi(sv.z)); w.w = cvtpk(x1[2] + bflo(sv.w), x1[3] + bfhi(sv.w));
;         *(u32x4*)(x1b + gi) = w;
;       }
	v_pk_add_f32 v[8:9], v[8:9], v[24:25]
	v_pk_add_f32 v[10:11], v[10:11], v[14:15]
	v_cvt_pk_bf16_f32 v5, v6, v7
	v_cvt_pk_bf16_f32 v6, v8, v9
	v_cvt_pk_bf16_f32 v7, v10, v11
	global_store_dwordx4 v[18:19], v[4:7], off
	global_load_dwordx4 v[4:7], v[20:21], off
	v_add_u32_e32 v12, 0x600, v2
	global_load_dwordx4 v[8:11], v[20:21], off offset:16
	v_ashrrev_i32_e32 v26, 4, v12
	v_mad_u64_u32 v[12:13], s[36:37], v3, s27, v[0:1]
	ds_read_b128 v[12:15], v12
	v_add_u32_e32 v18, s33, v26
	v_ashrrev_i32_e32 v19, 31, v18
	v_lshlrev_b64 v[18:19], 10, v[18:19]
	v_or3_b32 v18, v18, s34, v1
	s_waitcnt lgkmcnt(0)
	v_lshlrev_b32_e32 v22, 16, v12
	v_and_b32_e32 v23, 0xffff0000, v12
	v_lshlrev_b32_e32 v12, 16, v13
	v_and_b32_e32 v13, 0xffff0000, v13
	v_lshlrev_b32_e32 v24, 16, v14
	v_and_b32_e32 v25, 0xffff0000, v14
	v_lshlrev_b32_e32 v14, 16, v15
	v_and_b32_e32 v15, 0xffff0000, v15
	v_lshl_add_u64 v[20:21], v[18:19], 2, s[76:77]
	v_add_u32_e32 v3, 0x700, v2
	v_ashrrev_i32_e32 v3, 4, v3
	v_lshl_add_u64 v[18:19], v[18:19], 1, s[12:13]
	s_waitcnt vmcnt(1)
	v_pk_add_f32 v[4:5], v[4:5], v[22:23]
	v_pk_add_f32 v[6:7], v[6:7], v[12:13]
	s_waitcnt vmcnt(0)
	v_pk_add_f32 v[8:9], v[8:9], v[24:25]
	v_pk_add_f32 v[10:11], v[10:11], v[14:15]
	v_cvt_pk_bf16_f32 v4, v4, v5
	v_cvt_pk_bf16_f32 v5, v6, v7
	v_cvt_pk_bf16_f32 v6, v8, v9
	v_cvt_pk_bf16_f32 v7, v10, v11
	global_store_dwordx4 v[16:17], v[4:7], off
	global_load_dwordx4 v[4:7], v[20:21], off
	v_mad_u64_u32 v[12:13], s[36:37], v26, s27, v[0:1]
	global_load_dwordx4 v[8:11], v[20:21], off offset:16
	ds_read_b128 v[12:15], v12
	v_add_u32_e32 v16, s33, v3
	v_ashrrev_i32_e32 v17, 31, v16
	v_lshlrev_b64 v[16:17], 10, v[16:17]
	v_or3_b32 v16, v16, s34, v1
	s_waitcnt lgkmcnt(0)
	v_lshlrev_b32_e32 v22, 16, v12
	v_and_b32_e32 v23, 0xffff0000, v12
	v_lshlrev_b32_e32 v12, 16, v13
	v_and_b32_e32 v13, 0xffff0000, v13
	v_lshlrev_b32_e32 v24, 16, v14
	v_and_b32_e32 v25, 0xffff0000, v14
	v_lshlrev_b32_e32 v14, 16, v15
	v_and_b32_e32 v15, 0xffff0000, v15
	v_lshl_add_u64 v[20:21], v[16:17], 2, s[76:77]
	v_lshl_add_u64 v[16:17], v[16:17], 1, s[12:13]
	s_waitcnt vmcnt(1)
	v_pk_add_f32 v[4:5], v[4:5], v[22:23]
	v_pk_add_f32 v[6:7], v[6:7], v[12:13]
	v_cvt_pk_bf16_f32 v4, v4, v5
	s_waitcnt vmcnt(0)
	v_pk_add_f32 v[8:9], v[8:9], v[24:25]
	v_pk_add_f32 v[10:11], v[10:11], v[14:15]
	v_cvt_pk_bf16_f32 v5, v6, v7
	v_cvt_pk_bf16_f32 v6, v8, v9
	v_cvt_pk_bf16_f32 v7, v10, v11
	global_store_dwordx4 v[18:19], v[4:7], off
	global_load_dwordx4 v[4:7], v[20:21], off
	v_add_u32_e32 v12, 0x800, v2
	global_load_dwordx4 v[8:11], v[20:21], off offset:16
	v_ashrrev_i32_e32 v26, 4, v12
	v_mad_u64_u32 v[12:13], s[36:37], v3, s27, v[0:1]
	ds_read_b128 v[12:15], v12
	v_add_u32_e32 v18, s33, v26
	v_ashrrev_i32_e32 v19, 31, v18
	v_lshlrev_b64 v[18:19], 10, v[18:19]
	v_or3_b32 v18, v18, s34, v1
	s_waitcnt lgkmcnt(0)
	v_lshlrev_b32_e32 v22, 16, v12
	v_and_b32_e32 v23, 0xffff0000, v12
	v_lshlrev_b32_e32 v12, 16, v13
	v_and_b32_e32 v13, 0xffff0000, v13
	v_lshlrev_b32_e32 v24, 16, v14
	v_and_b32_e32 v25, 0xffff0000, v14
	v_lshlrev_b32_e32 v14, 16, v15
	v_and_b32_e32 v15, 0xffff0000, v15
	v_lshl_add_u64 v[20:21], v[18:19], 2, s[76:77]
	v_add_u32_e32 v3, 0x900, v2
	v_ashrrev_i32_e32 v3, 4, v3
	v_lshl_add_u64 v[18:19], v[18:19], 1, s[12:13]
	s_waitcnt vmcnt(1)
	v_pk_add_f32 v[4:5], v[4:5], v[22:23]
	v_pk_add_f32 v[6:7], v[6:7], v[12:13]
	s_waitcnt vmcnt(0)
	v_pk_add_f32 v[8:9], v[8:9], v[24:25]
	v_pk_add_f32 v[10:11], v[10:11], v[14:15]
	v_cvt_pk_bf16_f32 v4, v4, v5
	v_cvt_pk_bf16_f32 v5, v6, v7
	v_cvt_pk_bf16_f32 v6, v8, v9
	v_cvt_pk_bf16_f32 v7, v10, v11
	global_store_dwordx4 v[16:17], v[4:7], off
	global_load_dwordx4 v[4:7], v[20:21], off
	v_mad_u64_u32 v[12:13], s[36:37], v26, s27, v[0:1]
	global_load_dwordx4 v[8:11], v[20:21], off offset:16
	ds_read_b128 v[12:15], v12
	v_add_u32_e32 v16, s33, v3
	v_ashrrev_i32_e32 v17, 31, v16
	v_lshlrev_b64 v[16:17], 10, v[16:17]
	v_or3_b32 v16, v16, s34, v1
	s_waitcnt lgkmcnt(0)
	v_lshlrev_b32_e32 v22, 16, v12
	v_and_b32_e32 v23, 0xffff0000, v12
	v_lshlrev_b32_e32 v12, 16, v13
	v_and_b32_e32 v13, 0xffff0000, v13
	v_lshlrev_b32_e32 v24, 16, v14
	v_and_b32_e32 v25, 0xffff0000, v14
	v_lshlrev_b32_e32 v14, 16, v15
	v_and_b32_e32 v15, 0xffff0000, v15
	v_lshl_add_u64 v[20:21], v[16:17], 2, s[76:77]
	v_lshl_add_u64 v[16:17], v[16:17], 1, s[12:13]
	s_waitcnt vmcnt(1)
	v_pk_add_f32 v[4:5], v[4:5], v[22:23]
	v_pk_add_f32 v[6:7], v[6:7], v[12:13]
	v_cvt_pk_bf16_f32 v4, v4, v5
	s_waitcnt vmcnt(0)
	v_pk_add_f32 v[8:9], v[8:9], v[24:25]
	v_pk_add_f32 v[10:11], v[10:11], v[14:15]
	v_cvt_pk_bf16_f32 v5, v6, v7
	v_cvt_pk_bf16_f32 v6, v8, v9
	v_cvt_pk_bf16_f32 v7, v10, v11
	global_store_dwordx4 v[18:19], v[4:7], off
	global_load_dwordx4 v[4:7], v[20:21], off
	v_add_u32_e32 v12, 0xa00, v2
	global_load_dwordx4 v[8:11], v[20:21], off offset:16
	v_ashrrev_i32_e32 v26, 4, v12
	v_mad_u64_u32 v[12:13], s[36:37], v3, s27, v[0:1]
	ds_read_b128 v[12:15], v12
	v_add_u32_e32 v18, s33, v26
	v_ashrrev_i32_e32 v19, 31, v18
	v_lshlrev_b64 v[18:19], 10, v[18:19]
	v_or3_b32 v18, v18, s34, v1
	s_waitcnt lgkmcnt(0)
	v_lshlrev_b32_e32 v22, 16, v12
	v_and_b32_e32 v23, 0xffff0000, v12
	v_lshlrev_b32_e32 v12, 16, v13
	v_and_b32_e32 v13, 0xffff0000, v13
	v_lshlrev_b32_e32 v24, 16, v14
	v_and_b32_e32 v25, 0xffff0000, v14
	v_lshlrev_b32_e32 v14, 16, v15
	v_and_b32_e32 v15, 0xffff0000, v15
	v_lshl_add_u64 v[20:21], v[18:19], 2, s[76:77]
	v_add_u32_e32 v3, 0xb00, v2
	v_ashrrev_i32_e32 v3, 4, v3
	v_lshl_add_u64 v[18:19], v[18:19], 1, s[12:13]
	s_waitcnt vmcnt(1)
	v_pk_add_f32 v[4:5], v[4:5], v[22:23]
	v_pk_add_f32 v[6:7], v[6:7], v[12:13]
	s_waitcnt vmcnt(0)
; DI int tidx() { int t = __builtin_amdgcn_workitem_id_x(); asm volatile("" : "+v"(t)); return t; }
; DI unsigned cvtpk(float lo, float hi) { const f32x2_ v = {lo, hi}; return __builtin_bit_cast(unsigned, __builtin_convertvector(v, bf16x2_)); }
; DI float bflo(unsigned w) { return __uint_as_float(w << 16); }
; DI float bfhi(unsigned w) { return __uint_as_float(w & 0xffff0000u); }
; template <class F> DI void for_tiles_st(int ntm, int ntn, const Sched& sc, F f) {
;     ...
;     const int nsn = ntn >> 3, nsuper = (ntm >> 3) * nsn;
;     for (int sp = sc.xd; sp < nsuper; sp += sc.nx) {
;       const int sm = sp / nsn, sn = sp - sm * nsn;
;       for (int qq = sc.rank; qq < 64; qq += sc.nloc) f(sm * 8 + (qq >> 3), sn * 8 + (qq & 7));
; DI void phase6(const Params& p, const Sched& sched, unsigned char* smem) {
;     ...
;       const int tid = tidx();
; #pragma unroll
;       for (int i = 0; i < 16; ++i) {
;         const int c = tid + 256 * i, row = c >> 4, ch = (c & 15) * 8;
;         const size_t gi = (size_t)(tm * 256 + row) * 1024 + tn * 128 + ch;
;         const u32x4 sv = *(const u32x4*)(Ls + row * EST + ch);
;         const f32x4 x0 = *(const f32x4*)(p.x + gi), x1 = *(const f32x4*)(p.x + gi + 4);
;         u32x4 w;
;         w.x = cvtpk(x0[0] + bflo(sv.x), x0[1] + bfhi(sv.x)); w.y = cvtpk(x0[2] + bflo(sv.y), x0[3] + bfhi(sv.y));
;         w.z = cvtpk(x1[0] + bflo(sv.z), x1[1] + bfhi(sv.z)); w.w = cvtpk(x1[2] + bflo(sv.w), x1[3] + bfhi(sv.w));
;         *(u32x4*)(x1b + gi) = w;
;       }
	v_pk_add_f32 v[8:9], v[8:9], v[24:25]
	v_pk_add_f32 v[10:11], v[10:11], v[14:15]
	v_cvt_pk_bf16_f32 v4, v4, v5
	v_cvt_pk_bf16_f32 v5, v6, v7
	v_cvt_pk_bf16_f32 v6, v8, v9
	v_cvt_pk_bf16_f32 v7, v10, v11
	global_store_dwordx4 v[16:17], v[4:7], off
	global_load_dwordx4 v[4:7], v[20:21], off
	v_mad_u64_u32 v[12:13], s[36:37], v26, s27, v[0:1]
	global_load_dwordx4 v[8:11], v[20:21], off offset:16
	ds_read_b128 v[12:15], v12
	v_add_u32_e32 v16, s33, v3
	v_ashrrev_i32_e32 v17, 31, v16
	v_lshlrev_b64 v[16:17], 10, v[16:17]
	v_or3_b32 v16, v16, s34, v1
	s_waitcnt lgkmcnt(0)
	v_lshlrev_b32_e32 v22, 16, v12
	v_and_b32_e32 v23, 0xffff0000, v12
	v_lshlrev_b32_e32 v12, 16, v13
	v_and_b32_e32 v13, 0xffff0000, v13
	v_lshlrev_b32_e32 v24, 16, v14
	v_and_b32_e32 v25, 0xffff0000, v14
	v_lshlrev_b32_e32 v14, 16, v15
	v_and_b32_e32 v15, 0xffff0000, v15
	v_lshl_add_u64 v[20:21], v[16:17], 2, s[76:77]
	v_lshl_add_u64 v[16:17], v[16:17], 1, s[12:13]
	s_waitcnt vmcnt(1)
	v_pk_add_f32 v[4:5], v[4:5], v[22:23]
	v_pk_add_f32 v[6:7], v[6:7], v[12:13]
	v_cvt_pk_bf16_f32 v4, v4, v5
	s_waitcnt vmcnt(0)
	v_pk_add_f32 v[8:9], v[8:9], v[24:25]
	v_pk_add_f32 v[10:11], v[10:11], v[14:15]
	v_cvt_pk_bf16_f32 v5, v6, v7
	v_cvt_pk_bf16_f32 v6, v8, v9
	v_cvt_pk_bf16_f32 v7, v10, v11
	global_store_dwordx4 v[18:19], v[4:7], off
	global_load_dwordx4 v[4:7], v[20:21], off
	v_add_u32_e32 v12, 0xc00, v2
	global_load_dwordx4 v[8:11], v[20:21], off offset:16
	v_ashrrev_i32_e32 v26, 4, v12
	v_mad_u64_u32 v[12:13], s[36:37], v3, s27, v[0:1]
	ds_read_b128 v[12:15], v12
	v_add_u32_e32 v18, s33, v26
	v_ashrrev_i32_e32 v19, 31, v18
	v_lshlrev_b64 v[18:19], 10, v[18:19]
	v_or3_b32 v18, v18, s34, v1
	s_waitcnt lgkmcnt(0)
	v_lshlrev_b32_e32 v22, 16, v12
	v_and_b32_e32 v23, 0xffff0000, v12
	v_lshlrev_b32_e32 v12, 16, v13
	v_and_b32_e32 v13, 0xffff0000, v13
	v_lshlrev_b32_e32 v24, 16, v14
	v_and_b32_e32 v25, 0xffff0000, v14
	v_lshlrev_b32_e32 v14, 16, v15
	v_and_b32_e32 v15, 0xffff0000, v15
	v_lshl_add_u64 v[20:21], v[18:19], 2, s[76:77]
	v_add_u32_e32 v3, 0xd00, v2
	v_ashrrev_i32_e32 v3, 4, v3
	v_lshl_add_u64 v[18:19], v[18:19], 1, s[12:13]
	s_waitcnt vmcnt(1)
	v_pk_add_f32 v[4:5], v[4:5], v[22:23]
	v_pk_add_f32 v[6:7], v[6:7], v[12:13]
	s_waitcnt vmcnt(0)
	v_pk_add_f32 v[8:9], v[8:9], v[24:25]
	v_pk_add_f32 v[10:11], v[10:11], v[14:15]
	v_cvt_pk_bf16_f32 v4, v4, v5
	v_cvt_pk_bf16_f32 v5, v6, v7
	v_cvt_pk_bf16_f32 v6, v8, v9
	v_cvt_pk_bf16_f32 v7, v10, v11
	global_store_dwordx4 v[16:17], v[4:7], off
	global_load_dwordx4 v[4:7], v[20:21], off
	v_mad_u64_u32 v[12:13], s[36:37], v26, s27, v[0:1]
	global_load_dwordx4 v[8:11], v[20:21], off offset:16
	ds_read_b128 v[12:15], v12
	v_add_u32_e32 v16, s33, v3
	v_ashrrev_i32_e32 v17, 31, v16
	v_lshlrev_b64 v[16:17], 10, v[16:17]
	v_or3_b32 v16, v16, s34, v1
	s_waitcnt lgkmcnt(0)
	v_lshlrev_b32_e32 v22, 16, v12
	v_and_b32_e32 v23, 0xffff0000, v12
	v_lshlrev_b32_e32 v12, 16, v13
	v_and_b32_e32 v13, 0xffff0000, v13
	v_lshlrev_b32_e32 v24, 16, v14
	v_and_b32_e32 v25, 0xffff0000, v14
	v_lshlrev_b32_e32 v14, 16, v15
	v_and_b32_e32 v15, 0xffff0000, v15
	v_lshl_add_u64 v[20:21], v[16:17], 2, s[76:77]
	v_lshl_add_u64 v[16:17], v[16:17], 1, s[12:13]
	s_waitcnt vmcnt(1)
	v_pk_add_f32 v[4:5], v[4:5], v[22:23]
	v_pk_add_f32 v[6:7], v[6:7], v[12:13]
	v_cvt_pk_bf16_f32 v4, v4, v5
	s_waitcnt vmcnt(0)
	v_pk_add_f32 v[8:9], v[8:9], v[24:25]
	v_pk_add_f32 v[10:11], v[10:11], v[14:15]
	v_cvt_pk_bf16_f32 v5, v6, v7
	v_cvt_pk_bf16_f32 v6, v8, v9
	v_cvt_pk_bf16_f32 v7, v10, v11
	global_store_dwordx4 v[18:19], v[4:7], off
	global_load_dwordx4 v[4:7], v[20:21], off
	v_add_u32_e32 v12, 0xe00, v2
	global_load_dwordx4 v[8:11], v[20:21], off offset:16
	v_ashrrev_i32_e32 v26, 4, v12
	v_mad_u64_u32 v[12:13], s[36:37], v3, s27, v[0:1]
	ds_read_b128 v[12:15], v12
	v_add_u32_e32 v18, s33, v26
	v_ashrrev_i32_e32 v19, 31, v18
	v_lshlrev_b64 v[18:19], 10, v[18:19]
	v_or3_b32 v18, v18, s34, v1
	s_waitcnt lgkmcnt(0)
	v_lshlrev_b32_e32 v22, 16, v12
	v_and_b32_e32 v23, 0xffff0000, v12
	v_lshlrev_b32_e32 v12, 16, v13
	v_and_b32_e32 v13, 0xffff0000, v13
	v_lshlrev_b32_e32 v24, 16, v14
	v_and_b32_e32 v25, 0xffff0000, v14
	v_lshlrev_b32_e32 v14, 16, v15
	v_and_b32_e32 v15, 0xffff0000, v15
	v_lshl_add_u64 v[20:21], v[18:19], 2, s[76:77]
	v_add_u32_e32 v2, 0xf00, v2
	v_lshl_add_u64 v[18:19], v[18:19], 1, s[12:13]
	s_waitcnt vmcnt(1)
	v_pk_add_f32 v[4:5], v[4:5], v[22:23]
	v_pk_add_f32 v[6:7], v[6:7], v[12:13]
	s_waitcnt vmcnt(0)
	v_pk_add_f32 v[8:9], v[8:9], v[24:25]
	v_pk_add_f32 v[10:11], v[10:11], v[14:15]
	v_cvt_pk_bf16_f32 v4, v4, v5
	v_cvt_pk_bf16_f32 v5, v6, v7
	v_cvt_pk_bf16_f32 v6, v8, v9
	v_cvt_pk_bf16_f32 v7, v10, v11
	global_store_dwordx4 v[16:17], v[4:7], off
	global_load_dwordx4 v[4:7], v[20:21], off
	v_mad_u64_u32 v[12:13], s[36:37], v26, s27, v[0:1]
	global_load_dwordx4 v[8:11], v[20:21], off offset:16
	ds_read_b128 v[12:15], v12
	v_ashrrev_i32_e32 v24, 4, v2
	v_add_u32_e32 v2, s33, v24
	v_ashrrev_i32_e32 v3, 31, v2
	v_lshlrev_b64 v[16:17], 10, v[2:3]
	s_waitcnt lgkmcnt(0)
	v_lshlrev_b32_e32 v2, 16, v12
	v_and_b32_e32 v3, 0xffff0000, v12
	v_lshlrev_b32_e32 v12, 16, v13
	v_and_b32_e32 v13, 0xffff0000, v13
	v_lshlrev_b32_e32 v22, 16, v14
	v_and_b32_e32 v23, 0xffff0000, v14
	v_lshlrev_b32_e32 v14, 16, v15
	v_and_b32_e32 v15, 0xffff0000, v15
	v_or3_b32 v16, v16, s34, v1
	v_lshl_add_u64 v[20:21], v[16:17], 2, s[76:77]
	v_mad_u64_u32 v[0:1], s[34:35], v24, s27, v[0:1]
	s_waitcnt vmcnt(1)
	v_pk_add_f32 v[2:3], v[4:5], v[2:3]
	v_pk_add_f32 v[4:5], v[6:7], v[12:13]
	v_cvt_pk_bf16_f32 v2, v2, v3
	s_waitcnt vmcnt(0)
	v_pk_add_f32 v[6:7], v[8:9], v[22:23]
	v_pk_add_f32 v[8:9], v[10:11], v[14:15]
	v_cvt_pk_bf16_f32 v3, v4, v5
	v_cvt_pk_bf16_f32 v4, v6, v7
	v_cvt_pk_bf16_f32 v5, v8, v9
	global_store_dwordx4 v[18:19], v[2:5], off
	global_load_dwordx4 v[2:5], v[20:21], off
	ds_read_b128 v[10:13], v0
	global_load_dwordx4 v[6:9], v[20:21], off offset:16
	v_lshl_add_u64 v[14:15], v[16:17], 1, s[12:13]
	s_waitcnt lgkmcnt(0)
	v_lshlrev_b32_e32 v0, 16, v10
	v_and_b32_e32 v1, 0xffff0000, v10
	v_lshlrev_b32_e32 v10, 16, v11
	v_and_b32_e32 v11, 0xffff0000, v11
	v_lshlrev_b32_e32 v16, 16, v12
	v_and_b32_e32 v17, 0xffff0000, v12
	v_lshlrev_b32_e32 v12, 16, v13
	v_and_b32_e32 v13, 0xffff0000, v13
	s_waitcnt vmcnt(1)
	v_pk_add_f32 v[0:1], v[2:3], v[0:1]
	v_pk_add_f32 v[2:3], v[4:5], v[10:11]
	s_waitcnt vmcnt(0)
	v_pk_add_f32 v[4:5], v[6:7], v[16:17]
	v_pk_add_f32 v[6:7], v[8:9], v[12:13]
	v_cvt_pk_bf16_f32 v0, v0, v1
	v_cvt_pk_bf16_f32 v1, v2, v3
	v_cvt_pk_bf16_f32 v2, v4, v5
	v_cvt_pk_bf16_f32 v3, v6, v7
	global_store_dwordx4 v[14:15], v[0:3], off
	s_cbranch_scc0 .LBB0_811
	s_branch .LBB0_808

; DI int tidx() { int t = __builtin_amdgcn_workitem_id_x(); asm volatile("" : "+v"(t)); return t; }
;   DI unsigned rowoff(int r, int sch) const { const int g = r & 3, bc = r >> 2, b = bc / NCMP, c = bc - b * NCMP; return (unsigned)(b * Sn + c * 16) * 512u + g * 64 + sch; }
; template <int NI, class XL, class EP>
; DI void gemm_tile(const u16* __restrict__ W, int ldw, int f0, int t0, int K, XL xl, EP ep, unsigned char* smem) {
;   constexpr int LST = 48;
;   constexpr int XR = NI / 2;
;   constexpr int BUF = (128 + NI * 32) * LST;
;   u16* S0 = (u16*)smem;
;   const int tid = tidx(), lane = tid & 63, wave = tid >> 6;
;   const int wf = wave >> 1, wt = wave & 1, lr = lane & 15, lq = lane >> 4;
;   const int srow = tid >> 2, sch = (tid & 3) * 8;
;   f32x4 acc[4][NI];
; #pragma unroll
;   for (int i = 0; i < 4; ++i)
; #pragma unroll
;     for (int j = 0; j < NI; ++j) acc[i][j] = (f32x4){0.f, 0.f, 0.f, 0.f};
;   u32x4 wr[2], xr[XR];
;   const unsigned wbyte = ((unsigned)(f0 + srow * 2) * 32u + sch) * 2u;
;   const unsigned xbyte = xl.rowoff(t0 + srow * XR, sch) * 2u;
;   const int xrs = xl.rstride();
;   const int nk = K >> 5;
;   auto gload = [&](int it) {
;     const int k = it * 32;
;     const char* wb = (const char*)(W + (size_t)(k >> 5) * ldw * 32);
;     const char* xb = (const char*)xl.kbase(k);
; #pragma unroll
;     for (int i = 0; i < 2; ++i) wr[i] = *(const u32x4*)(wb + wbyte + i * 64);
; #pragma unroll
;     for (int i = 0; i < XR; ++i) xr[i] = *(const u32x4*)(xb + xbyte + i * xrs);
;   };
;   auto lstore = [&](int buf) {
;     u16* Ws = S0 + buf * BUF; u16* Xs = Ws + 128 * LST;
; #pragma unroll
;     for (int i = 0; i < 2; ++i) *(u32x4*)(Ws + (srow * 2 + i) * LST + sch) = wr[i];
; #pragma unroll
;     for (int i = 0; i < XR; ++i) *(u32x4*)(Xs + (srow * XR + i) * LST + sch) = xr[i];
;   };
;   gload(0);
;   __syncthreads();
;   lstore(0);
;   __syncthreads();
;   if (nk > 1) gload(1);
; DI void phase8(const Params& p, const Sched& sched, unsigned char* smem) {
;     ...
;   for_tiles_st(256, 44, sched, [&](int tm, int tn) {
;     gemm_tile<8>((const u16*)(p.ws + OFF_WGU), 5632, tn * 128, tm * 256, 1024, xl, [&](f32x4 (&acc)[4][8], int fb, int tb, int lr, int lq, int wf, int wt) {
.LBB0_944:
	s_ashr_i32 s4, s55, 2
	v_mov_b32_e32 v48, v218
	s_add_i32 s30, s4, s51
	s_and_b32 s4, s55, 3
	s_or_b32 s56, s4, s52
	v_ashrrev_i32_e32 v49, 2, v48
	v_lshlrev_b32_e32 v0, 3, v48
	v_lshlrev_b32_e32 v51, 6, v49
	v_and_b32_e32 v50, 24, v0
	v_lshl_add_u32 v0, s56, 12, v51
	v_or_b32_e32 v0, v0, v50
	v_lshlrev_b32_e32 v54, 1, v0
	v_lshlrev_b32_e32 v0, 6, v48
	v_and_b32_e32 v0, 0xffffff00, v0
	v_lshl_add_u32 v0, s30, 14, v0
	v_lshlrev_b32_e32 v171, 1, v50
	v_readlane_b32 s4, v245, 25
	v_or_b32_e32 v152, v0, v171
	v_readlane_b32 s5, v245, 26
	global_load_dwordx4 v[16:19], v54, s[60:61]
	global_load_dwordx4 v[20:23], v54, s[60:61] offset:64
	s_nop 2
	global_load_dwordx4 v[24:27], v152, s[4:5]
	global_load_dwordx4 v[28:31], v152, s[4:5] offset:64
	global_load_dwordx4 v[32:35], v152, s[4:5] offset:128
	global_load_dwordx4 v[36:39], v152, s[4:5] offset:192
	v_mul_lo_u32 v174, v49, s37
	v_or_b32_e32 v170, v174, v171
	v_add_u32_e32 v169, v170, v174
	s_barrier
	s_and_b32 s5, s54, 3
	s_add_i32 s5, s53, s5
	v_bfe_u32 v168, v48, 4, 2
	v_ashrrev_i32_e32 v155, 7, v48
	v_and_b32_e32 v55, 15, v48
	v_lshlrev_b32_e32 v48, 1, v48
	v_and_or_b32 v154, v48, s44, v55
	v_lshl_add_u32 v48, s5, 12, v51
	v_mov_b32_e32 v0, 0
	v_lshl_or_b32 v49, v155, 6, v55
	v_or_b32_e32 v48, v48, v50
	s_mov_b32 s4, 1
	v_mov_b32_e32 v157, v153
	v_mov_b32_e32 v1, v0
	v_mov_b32_e32 v2, v0
	v_mov_b32_e32 v3, v0
	v_mov_b32_e32 v4, v0
	v_mov_b32_e32 v5, v0
	v_mov_b32_e32 v6, v0
	v_mov_b32_e32 v7, v0
	v_mov_b32_e32 v8, v0
	v_mov_b32_e32 v9, v0
	v_mov_b32_e32 v10, v0
	v_mov_b32_e32 v11, v0
	v_mov_b32_e32 v12, v0
	v_mov_b32_e32 v13, v0
	v_mov_b32_e32 v14, v0
	v_mov_b32_e32 v15, v0
	v_mov_b32_e32 v40, v0
	v_mov_b32_e32 v41, v0
	v_mov_b32_e32 v42, v0
	v_mov_b32_e32 v43, v0
	v_mov_b32_e32 v44, v0
	v_mov_b32_e32 v45, v0
	v_mov_b32_e32 v46, v0
	v_mov_b32_e32 v47, v0
	v_mov_b32_e32 v52, v0
	v_mov_b32_e32 v53, v0
	v_lshlrev_b32_e32 v172, 4, v168
	v_mul_lo_u32 v175, v49, 48
	v_mul_u32_u24_e32 v173, 48, v154
	v_lshlrev_b32_e32 v156, 1, v48
	v_mov_b64_e32 v[158:159], v[152:153]
	v_mov_b32_e32 v55, v0
	v_mov_b32_e32 v80, v0
	v_mov_b32_e32 v81, v0
	v_mov_b32_e32 v82, v0
	v_mov_b32_e32 v83, v0
	v_mov_b32_e32 v48, v0
	v_mov_b32_e32 v49, v0
	v_mov_b32_e32 v50, v0
	v_mov_b32_e32 v51, v0
	v_mov_b32_e32 v56, v0
	v_mov_b32_e32 v57, v0
	v_mov_b32_e32 v58, v0
	v_mov_b32_e32 v59, v0
	v_mov_b32_e32 v60, v0
	v_mov_b32_e32 v61, v0
	v_mov_b32_e32 v62, v0
	v_mov_b32_e32 v63, v0
	v_mov_b32_e32 v68, v0
	s_waitcnt vmcnt(5)
	ds_write_b128 v170, v[16:19]
	s_waitcnt vmcnt(4)
	ds_write_b128 v170, v[20:23] offset:96
	s_waitcnt vmcnt(3)
	ds_write_b128 v169, v[24:27] offset:12288
	s_waitcnt vmcnt(2)
	ds_write_b128 v169, v[28:31] offset:12384
	s_waitcnt vmcnt(1)
	ds_write_b128 v169, v[32:35] offset:12480
	s_waitcnt vmcnt(0)
	ds_write_b128 v169, v[36:39] offset:12576
	s_waitcnt lgkmcnt(0)
	s_barrier
	global_load_dwordx4 v[20:23], v54, s[20:21]
	global_load_dwordx4 v[16:19], v54, s[20:21] offset:64
	global_load_dwordx4 v[36:39], v152, s[18:19]
	global_load_dwordx4 v[32:35], v152, s[18:19] offset:64
	global_load_dwordx4 v[28:31], v152, s[18:19] offset:128
	global_load_dwordx4 v[24:27], v152, s[18:19] offset:192
	v_mov_b32_e32 v54, v0
	v_mov_b32_e32 v69, v0
	v_mov_b32_e32 v70, v0
	v_mov_b32_e32 v71, v0
	v_mov_b32_e32 v76, v0
	v_mov_b32_e32 v77, v0
	v_mov_b32_e32 v78, v0
	v_mov_b32_e32 v79, v0
	v_mov_b32_e32 v88, v0
	v_mov_b32_e32 v89, v0
	v_mov_b32_e32 v90, v0
	v_mov_b32_e32 v91, v0
	v_mov_b32_e32 v100, v0
	v_mov_b32_e32 v101, v0
	v_mov_b32_e32 v102, v0
	v_mov_b32_e32 v103, v0
	v_mov_b32_e32 v112, v0
	v_mov_b32_e32 v113, v0
	v_mov_b32_e32 v114, v0
	v_mov_b32_e32 v115, v0
	v_mov_b32_e32 v64, v0
	v_mov_b32_e32 v65, v0
	v_mov_b32_e32 v66, v0
	v_mov_b32_e32 v67, v0
	v_mov_b32_e32 v72, v0
	v_mov_b32_e32 v73, v0
	v_mov_b32_e32 v74, v0
	v_mov_b32_e32 v75, v0
	v_mov_b32_e32 v84, v0
	v_mov_b32_e32 v85, v0
	v_mov_b32_e32 v86, v0
	v_mov_b32_e32 v87, v0
	v_mov_b32_e32 v96, v0
	v_mov_b32_e32 v97, v0
	v_mov_b32_e32 v98, v0
	v_mov_b32_e32 v99, v0
	v_mov_b32_e32 v108, v0
	v_mov_b32_e32 v109, v0
	v_mov_b32_e32 v110, v0
	v_mov_b32_e32 v111, v0
	v_mov_b32_e32 v120, v0
	v_mov_b32_e32 v121, v0
	v_mov_b32_e32 v122, v0
	v_mov_b32_e32 v123, v0
	v_mov_b32_e32 v128, v0
	v_mov_b32_e32 v129, v0
	v_mov_b32_e32 v130, v0
	v_mov_b32_e32 v131, v0
	v_mov_b32_e32 v136, v0
	v_mov_b32_e32 v137, v0
	v_mov_b32_e32 v138, v0
	v_mov_b32_e32 v139, v0
	v_mov_b32_e32 v92, v0
	v_mov_b32_e32 v93, v0
	v_mov_b32_e32 v94, v0
	v_mov_b32_e32 v95, v0
	v_mov_b32_e32 v104, v0
	v_mov_b32_e32 v105, v0
	v_mov_b32_e32 v106, v0
	v_mov_b32_e32 v107, v0
	v_mov_b32_e32 v116, v0
	v_mov_b32_e32 v117, v0
	v_mov_b32_e32 v118, v0
	v_mov_b32_e32 v119, v0
	v_mov_b32_e32 v124, v0
	v_mov_b32_e32 v125, v0
	v_mov_b32_e32 v126, v0
	v_mov_b32_e32 v127, v0
	v_mov_b32_e32 v132, v0
	v_mov_b32_e32 v133, v0
	v_mov_b32_e32 v134, v0
	v_mov_b32_e32 v135, v0
	v_mov_b32_e32 v140, v0
	v_mov_b32_e32 v141, v0
	v_mov_b32_e32 v142, v0
	v_mov_b32_e32 v143, v0
	v_mov_b32_e32 v144, v0
	v_mov_b32_e32 v145, v0
	v_mov_b32_e32 v146, v0
	v_mov_b32_e32 v147, v0
	v_mov_b32_e32 v148, v0
	v_mov_b32_e32 v149, v0
	v_mov_b32_e32 v150, v0
	v_mov_b32_e32 v151, v0
	s_add_u32 s98, s42, s45
	s_addc_u32 s99, s43, 0
	s_add_u32 s100, s42, s46
	s_addc_u32 s101, s43, 0
; DI f32x4 mfma16(bf16x8 a, bf16x8 b, f32x4 c) { return __builtin_amdgcn_mfma_f32_16x16x32_bf16(a, b, c, 0, 0, 0); }
; template <int NI, class XL, class EP>
; DI void gemm_tile(const u16* __restrict__ W, int ldw, int f0, int t0, int K, XL xl, EP ep, unsigned char* smem) {
;     ...
;   for (int it = 0; it < nk; ++it) {
;     const u16* Ws = S0 + (it & 1) * BUF; const u16* Xs = Ws + 128 * LST;
;     __builtin_amdgcn_s_setprio(1);
;     bf16x8 a[4];
; #pragma unroll
;     for (int mi = 0; mi < 4; ++mi) a[mi] = *(const bf16x8*)(Ws + (wf * 64 + mi * 16 + lr) * LST + lq * 8);
; #pragma unroll
;     for (int ni = 0; ni < NI; ++ni) {
;       const bf16x8 b = *(const bf16x8*)(Xs + (wt * (NI * 16) + ni * 16 + lr) * LST + lq * 8);
; #pragma unroll
;       for (int mi = 0; mi < 4; ++mi) acc[mi][ni] = mfma16(a[mi], b, acc[mi][ni]);
;     }
;     __builtin_amdgcn_sched_group_barrier(0x100, 6, 0);
; #pragma unroll
;     for (int ni = 0; ni < NI; ++ni) { __builtin_amdgcn_sched_group_barrier(0x008, 4, 0); if (ni + 2 < NI) __builtin_amdgcn_sched_group_barrier(0x100, 1, 0); }
;     __builtin_amdgcn_s_setprio(0);
;     if (it + 1 < nk) lstore((it + 1) & 1);
;     if (it + 2 < nk) gload(it + 2);
;     __syncthreads();
.LBB0_945:
	s_bitcmp1_b32 s4, 0
	s_cselect_b32 s5, 0, 0x9000
	s_setprio 1
	v_or_b32_e32 v152, s5, v172
	v_lshl_add_u32 v192, v175, 1, v152
	ds_read_b128 v[176:179], v192
	ds_read_b128 v[180:183], v192 offset:1536
	ds_read_b128 v[188:191], v192 offset:3072
	ds_read_b128 v[192:195], v192 offset:4608
	v_lshl_add_u32 v152, v173, 1, v152
	ds_read_b128 v[184:187], v152 offset:12288
	ds_read_b128 v[196:199], v152 offset:13824
	s_xor_b32 s5, s5, 0x9000
	v_add3_u32 v220, v174, s5, v171
	s_waitcnt lgkmcnt(1)
	v_mfma_f32_16x16x32_bf16 v[148:151], v[176:179], v[184:187], v[148:151]
	v_mfma_f32_16x16x32_bf16 v[136:139], v[180:183], v[184:187], v[136:139]
	v_mfma_f32_16x16x32_bf16 v[112:115], v[188:191], v[184:187], v[112:115]
	v_mfma_f32_16x16x32_bf16 v[80:83], v[192:195], v[184:187], v[80:83]
	ds_read_b128 v[184:187], v152 offset:15360
	s_waitcnt vmcnt(5)
	ds_write_b128 v220, v[20:23]
	s_waitcnt lgkmcnt(2)
	v_mfma_f32_16x16x32_bf16 v[144:147], v[176:179], v[196:199], v[144:147]
	v_mfma_f32_16x16x32_bf16 v[128:131], v[180:183], v[196:199], v[128:131]
	v_mfma_f32_16x16x32_bf16 v[100:103], v[188:191], v[196:199], v[100:103]
	v_mfma_f32_16x16x32_bf16 v[52:55], v[192:195], v[196:199], v[52:55]
	ds_read_b128 v[196:199], v152 offset:16896
	s_waitcnt vmcnt(4)
	ds_write_b128 v220, v[16:19] offset:96
	v_add_u32_e32 v220, v220, v174
	global_load_dwordx4 v[20:23], v156, s[98:99]
	global_load_dwordx4 v[16:19], v156, s[98:99] offset:64
	s_waitcnt lgkmcnt(3)
	v_mfma_f32_16x16x32_bf16 v[140:143], v[176:179], v[184:187], v[140:143]
	v_mfma_f32_16x16x32_bf16 v[120:123], v[180:183], v[184:187], v[120:123]
	v_mfma_f32_16x16x32_bf16 v[88:91], v[188:191], v[184:187], v[88:91]
	v_mfma_f32_16x16x32_bf16 v[44:47], v[192:195], v[184:187], v[44:47]
	ds_read_b128 v[184:187], v152 offset:18432
	s_waitcnt vmcnt(5)
	ds_write_b128 v220, v[36:39] offset:12288
	global_load_dwordx4 v[36:39], v158, s[100:101] offset:2048
	s_waitcnt lgkmcnt(3)
	v_mfma_f32_16x16x32_bf16 v[132:135], v[176:179], v[196:199], v[132:135]
	v_mfma_f32_16x16x32_bf16 v[108:111], v[180:183], v[196:199], v[108:111]
	v_mfma_f32_16x16x32_bf16 v[76:79], v[188:191], v[196:199], v[76:79]
	v_mfma_f32_16x16x32_bf16 v[40:43], v[192:195], v[196:199], v[40:43]
	ds_read_b128 v[196:199], v152 offset:19968
	s_waitcnt vmcnt(5)
	ds_write_b128 v220, v[32:35] offset:12384
	global_load_dwordx4 v[32:35], v158, s[100:101] offset:2112
	s_waitcnt lgkmcnt(3)
	v_mfma_f32_16x16x32_bf16 v[124:127], v[176:179], v[184:187], v[124:127]
	v_mfma_f32_16x16x32_bf16 v[96:99], v[180:183], v[184:187], v[96:99]
	v_mfma_f32_16x16x32_bf16 v[68:71], v[188:191], v[184:187], v[68:71]
	v_mfma_f32_16x16x32_bf16 v[12:15], v[192:195], v[184:187], v[12:15]
	ds_read_b128 v[184:187], v152 offset:21504
	s_waitcnt vmcnt(5)
	ds_write_b128 v220, v[28:31] offset:12480
	global_load_dwordx4 v[28:31], v158, s[100:101] offset:2176
	s_waitcnt lgkmcnt(3)
	v_mfma_f32_16x16x32_bf16 v[116:119], v[176:179], v[196:199], v[116:119]
	v_mfma_f32_16x16x32_bf16 v[84:87], v[180:183], v[196:199], v[84:87]
	v_mfma_f32_16x16x32_bf16 v[60:63], v[188:191], v[196:199], v[60:63]
	v_mfma_f32_16x16x32_bf16 v[8:11], v[192:195], v[196:199], v[8:11]
	ds_read_b128 v[196:199], v152 offset:23040
	s_waitcnt vmcnt(5)
	ds_write_b128 v220, v[24:27] offset:12576
	global_load_dwordx4 v[24:27], v158, s[100:101] offset:2240
	s_waitcnt lgkmcnt(3)
	v_mfma_f32_16x16x32_bf16 v[104:107], v[176:179], v[184:187], v[104:107]
	v_mfma_f32_16x16x32_bf16 v[72:75], v[180:183], v[184:187], v[72:75]
	v_mfma_f32_16x16x32_bf16 v[56:59], v[188:191], v[184:187], v[56:59]
	v_mfma_f32_16x16x32_bf16 v[4:7], v[192:195], v[184:187], v[4:7]
	s_add_u32 s98, s98, s28
	s_addc_u32 s99, s99, s29
	s_add_u32 s100, s100, s26
	s_addc_u32 s101, s101, s27
	s_add_i32 s4, s4, 1
	s_waitcnt lgkmcnt(1)
	v_mfma_f32_16x16x32_bf16 v[92:95], v[176:179], v[196:199], v[92:95]
	v_mfma_f32_16x16x32_bf16 v[64:67], v[180:183], v[196:199], v[64:67]
	v_mfma_f32_16x16x32_bf16 v[48:51], v[188:191], v[196:199], v[48:51]
	v_mfma_f32_16x16x32_bf16 v[0:3], v[192:195], v[196:199], v[0:3]
	s_setprio 0
	s_cmp_eq_u32 s4, 31
	s_waitcnt lgkmcnt(0)
	s_barrier
	s_cbranch_scc0 .LBB0_945
	s_setprio 1
	v_lshl_add_u32 v152, v175, 1, v172
	ds_read_b128 v[156:159], v152
	v_lshl_add_u32 v171, v173, 1, v172
	ds_read_b128 v[172:175], v152 offset:1536
	ds_read_b128 v[180:183], v152 offset:3072
	ds_read_b128 v[184:187], v152 offset:4608
	ds_read_b128 v[176:179], v171 offset:12288
	ds_read_b128 v[188:191], v171 offset:13824
	s_waitcnt lgkmcnt(1)
	v_mfma_f32_16x16x32_bf16 v[148:151], v[156:159], v[176:179], v[148:151]
	v_mfma_f32_16x16x32_bf16 v[136:139], v[172:175], v[176:179], v[136:139]
	v_mfma_f32_16x16x32_bf16 v[112:115], v[180:183], v[176:179], v[112:115]
	v_mfma_f32_16x16x32_bf16 v[80:83], v[184:187], v[176:179], v[80:83]
	ds_read_b128 v[176:179], v171 offset:15360
	s_waitcnt lgkmcnt(1)
	v_mfma_f32_16x16x32_bf16 v[144:147], v[156:159], v[188:191], v[144:147]
	v_mfma_f32_16x16x32_bf16 v[128:131], v[172:175], v[188:191], v[128:131]
	v_mfma_f32_16x16x32_bf16 v[100:103], v[180:183], v[188:191], v[100:103]
	v_mfma_f32_16x16x32_bf16 v[188:191], v[184:187], v[188:191], v[52:55]
	s_nop 2
	ds_read_b128 v[52:55], v171 offset:16896
	s_waitcnt lgkmcnt(1)
	v_mfma_f32_16x16x32_bf16 v[192:195], v[156:159], v[176:179], v[140:143]
	v_mfma_f32_16x16x32_bf16 v[120:123], v[172:175], v[176:179], v[120:123]
	v_mfma_f32_16x16x32_bf16 v[88:91], v[180:183], v[176:179], v[88:91]
	v_mfma_f32_16x16x32_bf16 v[176:179], v[184:187], v[176:179], v[44:47]
	s_nop 2
	ds_read_b128 v[44:47], v171 offset:18432
	s_waitcnt lgkmcnt(1)
; template <int NI, class XL, class EP>
; DI void gemm_tile(const u16* __restrict__ W, int ldw, int f0, int t0, int K, XL xl, EP ep, unsigned char* smem) {
;     ...
;     __builtin_amdgcn_sched_group_barrier(0x100, 6, 0);
; #pragma unroll
;     for (int ni = 0; ni < NI; ++ni) { __builtin_amdgcn_sched_group_barrier(0x008, 4, 0); if (ni + 2 < NI) __builtin_amdgcn_sched_group_barrier(0x100, 1, 0); }
;     __builtin_amdgcn_s_setprio(0);
;     if (it + 1 < nk) lstore((it + 1) & 1);
;     if (it + 2 < nk) gload(it + 2);
;     __syncthreads();
	v_mfma_f32_16x16x32_bf16 v[196:199], v[156:159], v[52:55], v[132:135]
	v_mfma_f32_16x16x32_bf16 v[108:111], v[172:175], v[52:55], v[108:111]
	v_mfma_f32_16x16x32_bf16 v[76:79], v[180:183], v[52:55], v[76:79]
	v_mfma_f32_16x16x32_bf16 v[200:203], v[184:187], v[52:55], v[40:43]
	s_nop 2
	ds_read_b128 v[40:43], v171 offset:19968
	s_waitcnt lgkmcnt(1)
	v_mfma_f32_16x16x32_bf16 v[204:207], v[156:159], v[44:47], v[124:127]
	v_mfma_f32_16x16x32_bf16 v[96:99], v[172:175], v[44:47], v[96:99]
	v_mfma_f32_16x16x32_bf16 v[68:71], v[180:183], v[44:47], v[68:71]
	v_mfma_f32_16x16x32_bf16 v[12:15], v[184:187], v[44:47], v[12:15]
	ds_read_b128 v[44:47], v171 offset:21504
	s_waitcnt lgkmcnt(1)
	v_mfma_f32_16x16x32_bf16 v[208:211], v[156:159], v[40:43], v[116:119]
	v_mfma_f32_16x16x32_bf16 v[84:87], v[172:175], v[40:43], v[84:87]
	v_mfma_f32_16x16x32_bf16 v[212:215], v[180:183], v[40:43], v[60:63]
	v_mfma_f32_16x16x32_bf16 v[8:11], v[184:187], v[40:43], v[8:11]
	ds_read_b128 v[40:43], v171 offset:23040
	s_waitcnt lgkmcnt(1)
	v_mfma_f32_16x16x32_bf16 v[220:223], v[156:159], v[44:47], v[104:107]
	v_mfma_f32_16x16x32_bf16 v[72:75], v[172:175], v[44:47], v[72:75]
	v_mfma_f32_16x16x32_bf16 v[224:227], v[180:183], v[44:47], v[56:59]
	v_mfma_f32_16x16x32_bf16 v[4:7], v[184:187], v[44:47], v[4:7]
	s_waitcnt lgkmcnt(0)
	v_mfma_f32_16x16x32_bf16 v[156:159], v[156:159], v[40:43], v[92:95]
	v_mfma_f32_16x16x32_bf16 v[172:175], v[172:175], v[40:43], v[64:67]
	v_mfma_f32_16x16x32_bf16 v[180:183], v[180:183], v[40:43], v[48:51]
	v_mfma_f32_16x16x32_bf16 v[184:187], v[184:187], v[40:43], v[0:3]
	s_setprio 0
	s_waitcnt vmcnt(5)
	ds_write_b128 v170, v[20:23] offset:36864
	s_waitcnt vmcnt(4)
	ds_write_b128 v170, v[16:19] offset:36960
	s_waitcnt vmcnt(3)
	ds_write_b128 v169, v[36:39] offset:49152
	s_waitcnt vmcnt(2)
	ds_write_b128 v169, v[32:35] offset:49248
	s_waitcnt vmcnt(1)
	ds_write_b128 v169, v[28:31] offset:49344
	s_waitcnt vmcnt(0)
	ds_write_b128 v169, v[24:27] offset:49440
	s_waitcnt lgkmcnt(0)
	s_barrier
; template <int NI, class XL, class EP>
; DI void gemm_tile(const u16* __restrict__ W, int ldw, int f0, int t0, int K, XL xl, EP ep, unsigned char* smem) {
;     ...
;   for (int it = 0; it < nk; ++it) {
;     const u16* Ws = S0 + (it & 1) * BUF; const u16* Xs = Ws + 128 * LST;
;     __builtin_amdgcn_s_setprio(1);
;     bf16x8 a[4];
; #pragma unroll
;     for (int mi = 0; mi < 4; ++mi) a[mi] = *(const bf16x8*)(Ws + (wf * 64 + mi * 16 + lr) * LST + lq * 8);
; #pragma unroll
;     for (int ni = 0; ni < NI; ++ni) {
;       const bf16x8 b = *(const bf16x8*)(Xs + (wt * (NI * 16) + ni * 16 + lr) * LST + lq * 8);
; #pragma unroll
;       for (int mi = 0; mi < 4; ++mi) acc[mi][ni] = mfma16(a[mi], b, acc[mi][ni]);
;     }
;     __builtin_amdgcn_sched_group_barrier(0x100, 6, 0);
; #pragma unroll
;     for (int ni = 0; ni < NI; ++ni) { __builtin_amdgcn_sched_group_barrier(0x008, 4, 0); if (ni + 2 < NI) __builtin_amdgcn_sched_group_barrier(0x100, 1, 0); }
;     __builtin_amdgcn_s_setprio(0);
;     if (it + 1 < nk) lstore((it + 1) & 1);
;     if (it + 2 < nk) gload(it + 2);
;     __syncthreads();
;   }
;   ep(acc, f0 + wf * 64, t0 + wt * (NI * 16), lr, lq, wf, wt);
; DI void phase8(const Params& p, const Sched& sched, unsigned char* smem) {
;     ...
;       u16* Ls = (u16*)(smem + 36864);
; #pragma unroll
;       for (int h2 = 0; h2 < 2; ++h2) {
;         const int fl = wf * 16 + lq * 4, fc = (2 * wf + h2) * 16 + lq * 4, F = tn * 64 + fc;
;         __syncthreads();
; #pragma unroll
;         for (int ni = 0; ni < 8; ++ni) *(f32x4*)(gl + (wt * 128 + ni * 16 + lr) * 36 + fl) = acc[2 * h2][ni];
;         __syncthreads();
;         const float4 w0 = *(const float4*)(p.conv_w + F), w1 = *(const float4*)(p.conv_w + FF + F), w2 = *(const float4*)(p.conv_w + 2 * FF + F), cb = *(const float4*)(p.conv_b + F);
; #pragma unroll
;         for (int ni = 0; ni < 8; ++ni) {
;           const int row = wt * 128 + ni * 16 + lr;
;           const f32x4 gv = acc[2 * h2][ni], uv = acc[2 * h2 + 1][ni];
;           if (row >= 2) {
;             const f32x4 g1 = *(const f32x4*)(gl + (row - 1) * 36 + fl), g2 = *(const f32x4*)(gl + (row - 2) * 36 + fl);
;             f32x4 o;
;             o[0] = cb.x + w0.x * g2[0] + w1.x * g1[0] + w2.x * gv[0];
;             o[1] = cb.y + w0.y * g2[1] + w1.y * g1[1] + w2.y * gv[1];
;             o[2] = cb.z + w0.z * g2[2] + w1.z * g1[2] + w2.z * gv[2];
	s_setprio 1
	ds_read_b128 v[0:3], v152 offset:36864
	ds_read_b128 v[228:231], v152 offset:38400
	ds_read_b128 v[232:235], v152 offset:39936
	ds_read_b128 v[236:239], v152 offset:41472
	ds_read_b128 v[16:19], v171 offset:49152
	ds_read_b128 v[20:23], v171 offset:50688
	s_waitcnt lgkmcnt(1)
	v_mfma_f32_16x16x32_bf16 v[140:143], v[0:3], v[16:19], v[148:151]
	v_mfma_f32_16x16x32_bf16 v[136:139], v[228:231], v[16:19], v[136:139]
	v_mfma_f32_16x16x32_bf16 v[60:63], v[232:235], v[16:19], v[112:115]
	v_mfma_f32_16x16x32_bf16 v[56:59], v[236:239], v[16:19], v[80:83]
	ds_read_b128 v[16:19], v171 offset:52224
	s_waitcnt lgkmcnt(1)
	v_mfma_f32_16x16x32_bf16 v[132:135], v[0:3], v[20:23], v[144:147]
	v_mfma_f32_16x16x32_bf16 v[128:131], v[228:231], v[20:23], v[128:131]
	v_mfma_f32_16x16x32_bf16 v[52:55], v[232:235], v[20:23], v[100:103]
	v_mfma_f32_16x16x32_bf16 v[48:51], v[236:239], v[20:23], v[188:191]
	ds_read_b128 v[20:23], v171 offset:53760
	s_waitcnt lgkmcnt(1)
	v_mfma_f32_16x16x32_bf16 v[124:127], v[0:3], v[16:19], v[192:195]
	v_mfma_f32_16x16x32_bf16 v[120:123], v[228:231], v[16:19], v[120:123]
	v_mfma_f32_16x16x32_bf16 v[44:47], v[232:235], v[16:19], v[88:91]
	v_mfma_f32_16x16x32_bf16 v[40:43], v[236:239], v[16:19], v[176:179]
	ds_read_b128 v[16:19], v171 offset:55296
	s_waitcnt lgkmcnt(1)
	v_mfma_f32_16x16x32_bf16 v[116:119], v[0:3], v[20:23], v[196:199]
	v_mfma_f32_16x16x32_bf16 v[112:115], v[228:231], v[20:23], v[108:111]
	v_mfma_f32_16x16x32_bf16 v[36:39], v[232:235], v[20:23], v[76:79]
	v_mfma_f32_16x16x32_bf16 v[32:35], v[236:239], v[20:23], v[200:203]
	ds_read_b128 v[64:67], v171 offset:56832
	s_waitcnt lgkmcnt(1)
	v_mfma_f32_16x16x32_bf16 v[108:111], v[0:3], v[16:19], v[204:207]
	v_mfma_f32_16x16x32_bf16 v[104:107], v[228:231], v[16:19], v[96:99]
	v_mfma_f32_16x16x32_bf16 v[28:31], v[232:235], v[16:19], v[68:71]
	v_mfma_f32_16x16x32_bf16 v[24:27], v[236:239], v[16:19], v[12:15]
	s_nop 1
	ds_read_b128 v[68:71], v171 offset:58368
	s_waitcnt lgkmcnt(1)
	v_mfma_f32_16x16x32_bf16 v[100:103], v[0:3], v[64:67], v[208:211]
	v_mfma_f32_16x16x32_bf16 v[96:99], v[228:231], v[64:67], v[84:87]
	v_mfma_f32_16x16x32_bf16 v[20:23], v[232:235], v[64:67], v[212:215]
	v_mfma_f32_16x16x32_bf16 v[16:19], v[236:239], v[64:67], v[8:11]
	ds_read_b128 v[76:79], v171 offset:59904
	s_waitcnt lgkmcnt(1)
	v_mfma_f32_16x16x32_bf16 v[92:95], v[0:3], v[68:71], v[220:223]
	v_mfma_f32_16x16x32_bf16 v[72:75], v[228:231], v[68:71], v[72:75]
	v_mfma_f32_16x16x32_bf16 v[12:15], v[232:235], v[68:71], v[224:227]
	v_mfma_f32_16x16x32_bf16 v[8:11], v[236:239], v[68:71], v[4:7]
	s_waitcnt lgkmcnt(0)
	v_mfma_f32_16x16x32_bf16 v[64:67], v[0:3], v[76:79], v[156:159]
	v_mfma_f32_16x16x32_bf16 v[68:71], v[228:231], v[76:79], v[172:175]
	v_mfma_f32_16x16x32_bf16 v[0:3], v[232:235], v[76:79], v[180:183]
	v_mfma_f32_16x16x32_bf16 v[4:7], v[236:239], v[76:79], v[184:187]
	s_setprio 0
	v_lshlrev_b32_e32 v76, 2, v168
	v_lshl_or_b32 v152, v155, 4, v76
	v_lshl_or_b32 v156, v155, 5, v76
	v_lshlrev_b32_e32 v76, 2, v152
	v_mad_u32_u24 v77, v154, s47, v160
	v_add_u32_e32 v159, v77, v76
	v_mad_u32_u24 v77, v154, s47, v161
	v_add_u32_e32 v168, v77, v76
	v_mad_u32_u24 v77, v154, s47, v162
	s_lshl_b32 s57, s56, 6
	v_add_u32_e32 v169, v77, v76
	v_mad_u32_u24 v77, v154, s47, v163
	v_add_u32_e32 v170, v77, v76
	v_mad_u32_u24 v77, v154, s47, v164
	v_add_u32_e32 v144, s57, v156
	v_add_u32_e32 v171, v77, v76
	v_mad_u32_u24 v77, v154, s47, v165
	v_ashrrev_i32_e32 v145, 31, v144
	v_add_u32_e32 v172, v77, v76
	v_mad_u32_u24 v77, v154, s47, v166
	v_lshlrev_b64 v[146:147], 2, v[144:145]
	v_mad_u32_u24 v158, v154, s47, v76
	v_add_u32_e32 v173, v77, v76
	v_lshl_add_u64 v[148:149], s[68:69], 0, v[146:147]
	v_lshl_add_u64 v[76:77], s[22:23], 0, v[146:147]
	v_lshl_add_u64 v[78:79], s[24:25], 0, v[146:147]
	v_lshl_add_u64 v[150:151], s[70:71], 0, v[146:147]
	s_barrier
	s_barrier
	ds_write_b128 v158, v[140:143]
	ds_write_b128 v159, v[132:135]
	ds_write_b128 v168, v[124:127]
	ds_write_b128 v169, v[116:119]
	ds_write_b128 v170, v[108:111]
	ds_write_b128 v171, v[100:103]
	ds_write_b128 v172, v[92:95]
	ds_write_b128 v173, v[64:67]
	s_waitcnt lgkmcnt(0)
	s_barrier
	global_load_dwordx4 v[84:87], v[148:149], off
	global_load_dwordx4 v[80:83], v[76:77], off
	global_load_dwordx4 v[88:91], v[150:151], off
	v_cmp_gt_u32_e64 s[4:5], 2, v154
	global_load_dwordx4 v[76:79], v[78:79], off
	v_lshl_or_b32 v157, s30, 1, v154
	s_and_saveexec_b64 s[6:7], s[4:5]
	s_xor_b64 s[6:7], exec, s[6:7]
	s_cbranch_execz .LBB0_948
	s_ashr_i32 s31, s30, 31
	s_lshl_b64 s[34:35], s[30:31], 2
	v_or_b32_e32 v155, s34, v154
	v_mov_b64_e32 v[174:175], s[16:17]
	v_mad_u64_u32 v[174:175], s[58:59], v155, s48, v[174:175]
	v_mad_i32_i24 v175, s35, v167, v175
	v_lshl_add_u64 v[174:175], v[174:175], 0, v[146:147]
	global_store_dwordx4 v[174:175], v[140:143], off
	s_nop 1
	v_mov_b64_e32 v[140:141], s[10:11]
	v_mad_u64_u32 v[140:141], s[34:35], v157, s48, v[140:141]
	v_mad_i32_i24 v141, s31, v167, v141
	v_lshl_add_u64 v[140:141], v[140:141], 0, v[146:147]
	global_store_dwordx4 v[140:141], v[136:139], off

; DI int tidx() { int t = __builtin_amdgcn_workitem_id_x(); asm volatile("" : "+v"(t)); return t; }
;   DI unsigned rowoff(int r, int sch) const { const int g = r & 3, bc = r >> 2, b = bc / NCMP, c = bc - b * NCMP; return (unsigned)(b * Sn + c * 16) * 512u + g * 64 + sch; }
; template <int NI, class XL, class EP>
; DI void gemm_tile(const u16* __restrict__ W, int ldw, int f0, int t0, int K, XL xl, EP ep, unsigned char* smem) {
;   constexpr int LST = 48;
;   constexpr int XR = NI / 2;
;   constexpr int BUF = (128 + NI * 32) * LST;
;   u16* S0 = (u16*)smem;
;   const int tid = tidx(), lane = tid & 63, wave = tid >> 6;
;   const int wf = wave >> 1, wt = wave & 1, lr = lane & 15, lq = lane >> 4;
;   const int srow = tid >> 2, sch = (tid & 3) * 8;
;   f32x4 acc[4][NI];
; #pragma unroll
;   for (int i = 0; i < 4; ++i)
; #pragma unroll
;     for (int j = 0; j < NI; ++j) acc[i][j] = (f32x4){0.f, 0.f, 0.f, 0.f};
;   u32x4 wr[2], xr[XR];
;   const unsigned wbyte = ((unsigned)(f0 + srow * 2) * 32u + sch) * 2u;
;   const unsigned xbyte = xl.rowoff(t0 + srow * XR, sch) * 2u;
;   const int xrs = xl.rstride();
;   const int nk = K >> 5;
;   auto gload = [&](int it) {
;     const int k = it * 32;
;     const char* wb = (const char*)(W + (size_t)(k >> 5) * ldw * 32);
;     const char* xb = (const char*)xl.kbase(k);
; #pragma unroll
;     for (int i = 0; i < 2; ++i) wr[i] = *(const u32x4*)(wb + wbyte + i * 64);
; #pragma unroll
;     for (int i = 0; i < XR; ++i) xr[i] = *(const u32x4*)(xb + xbyte + i * xrs);
;   };
;   auto lstore = [&](int buf) {
;     u16* Ws = S0 + buf * BUF; u16* Xs = Ws + 128 * LST;
; #pragma unroll
;     for (int i = 0; i < 2; ++i) *(u32x4*)(Ws + (srow * 2 + i) * LST + sch) = wr[i];
; #pragma unroll
;     for (int i = 0; i < XR; ++i) *(u32x4*)(Xs + (srow * XR + i) * LST + sch) = xr[i];
;   };
;   gload(0);
;   __syncthreads();
;   lstore(0);
;   __syncthreads();
;   if (nk > 1) gload(1);
; DI void phase9(const Params& p, const Sched& sched, unsigned char* smem) {
;     ...
;   for_tiles_st(256, 8, sched, [&](int tm, int tn) {
;     gemm_tile<8>((const u16*)(p.ws + OFF_WDN), 1024, tn * 128, tm * 256, FF, xl, [&](f32x4 (&acc)[4][8], int fb, int tb, int lr, int lq, int wf, int wt) {
.LBB0_1094:
	v_mov_b32_e32 v46, v218
	s_and_b32 s30, s28, 7
	v_ashrrev_i32_e32 v47, 2, v46
	v_lshlrev_b32_e32 v0, 3, v46
	v_lshlrev_b32_e32 v49, 6, v47
	s_ashr_i32 s34, s28, 3
	v_and_b32_e32 v48, 24, v0
	v_lshl_add_u32 v0, s30, 12, v49
	s_add_i32 s31, s34, s26
	v_or_b32_e32 v0, v0, v48
	s_lshl_b32 s29, s31, 8
	v_lshlrev_b32_e32 v50, 1, v0
	v_and_b32_e32 v0, 0x3fffffc, v46
	v_add_u32_e32 v0, s29, v0
	v_lshlrev_b32_e32 v161, 1, v48
	v_lshl_or_b32 v51, v0, 6, v161
	global_load_dwordx4 v[16:19], v50, s[4:5]
	global_load_dwordx4 v[20:23], v50, s[4:5] offset:64
	global_load_dwordx4 v[24:27], v51, s[8:9]
	global_load_dwordx4 v[28:31], v51, s[8:9] offset:64
	global_load_dwordx4 v[32:35], v51, s[8:9] offset:128
	global_load_dwordx4 v[36:39], v51, s[8:9] offset:192
	v_mul_lo_u32 v166, v47, s20
	v_or_b32_e32 v162, v166, v161
	v_add_u32_e32 v163, v162, v166
	s_barrier
	v_bfe_u32 v158, v46, 4, 2
	v_and_b32_e32 v52, 15, v46
	v_ashrrev_i32_e32 v53, 1, v46
	v_lshlrev_b32_e32 v54, 1, v46
	v_lshlrev_b32_e32 v46, 6, v46
	s_and_b32 s35, s27, 7
	s_add_i32 s34, s18, s34
	v_and_b32_e32 v46, 0xffffff00, v46
	v_and_b32_e32 v160, 0xffffffc0, v53
	v_lshl_add_u32 v46, s34, 14, v46
	v_lshl_add_u32 v49, s35, 12, v49
	v_mov_b32_e32 v0, 0
	v_and_or_b32 v159, v54, s21, v52
	v_or_b32_e32 v47, v160, v52
	v_or_b32_e32 v152, v46, v161
	v_or_b32_e32 v46, v49, v48
	s_mov_b32 s33, 1
	v_mov_b32_e32 v155, v153
	v_mov_b32_e32 v1, v0
	v_mov_b32_e32 v2, v0
	v_mov_b32_e32 v3, v0
	v_mov_b32_e32 v4, v0
	v_mov_b32_e32 v5, v0
	v_mov_b32_e32 v6, v0
	v_mov_b32_e32 v7, v0
	v_mov_b32_e32 v8, v0
	v_mov_b32_e32 v9, v0
	v_mov_b32_e32 v10, v0
	v_mov_b32_e32 v11, v0
	v_mov_b32_e32 v12, v0
	v_mov_b32_e32 v13, v0
	v_mov_b32_e32 v14, v0
	v_mov_b32_e32 v15, v0
	v_mov_b32_e32 v40, v0
	v_mov_b32_e32 v41, v0
	v_mov_b32_e32 v42, v0
	v_mov_b32_e32 v43, v0
	v_mov_b32_e32 v44, v0
	v_mov_b32_e32 v45, v0
	v_lshlrev_b32_e32 v164, 4, v158
	v_mul_u32_u24_e32 v165, 48, v159
	v_mul_lo_u32 v167, v47, 48
	v_lshlrev_b32_e32 v154, 1, v46
	v_mov_b64_e32 v[156:157], v[152:153]
	v_mov_b32_e32 v46, v0
	v_mov_b32_e32 v47, v0
	v_mov_b32_e32 v68, v0
	v_mov_b32_e32 v69, v0
	v_mov_b32_e32 v70, v0
	v_mov_b32_e32 v71, v0
	v_mov_b32_e32 v80, v0
	v_mov_b32_e32 v81, v0
	v_mov_b32_e32 v82, v0
	v_mov_b32_e32 v83, v0
	v_mov_b32_e32 v48, v0
	v_mov_b32_e32 v49, v0
	v_mov_b32_e32 v52, v0
	v_mov_b32_e32 v53, v0
	v_mov_b32_e32 v54, v0
	v_mov_b32_e32 v55, v0
	v_mov_b32_e32 v56, v0
	v_mov_b32_e32 v57, v0
	v_mov_b32_e32 v58, v0
	s_waitcnt vmcnt(5)
	ds_write_b128 v162, v[16:19]
	s_waitcnt vmcnt(4)
	ds_write_b128 v162, v[20:23] offset:96
	s_waitcnt vmcnt(3)
	ds_write_b128 v163, v[24:27] offset:12288
	s_waitcnt vmcnt(2)
	ds_write_b128 v163, v[28:31] offset:12384
	s_waitcnt vmcnt(1)
	ds_write_b128 v163, v[32:35] offset:12480
	s_waitcnt vmcnt(0)
	ds_write_b128 v163, v[36:39] offset:12576
	s_waitcnt lgkmcnt(0)
	s_barrier
	global_load_dwordx4 v[20:23], v50, s[10:11]
	global_load_dwordx4 v[16:19], v50, s[10:11] offset:64
	global_load_dwordx4 v[36:39], v51, s[6:7]
	global_load_dwordx4 v[32:35], v51, s[6:7] offset:64
	global_load_dwordx4 v[28:31], v51, s[6:7] offset:128
	global_load_dwordx4 v[24:27], v51, s[6:7] offset:192
	v_mov_b32_e32 v50, v0
	v_mov_b32_e32 v51, v0
	v_mov_b32_e32 v59, v0
	v_mov_b32_e32 v64, v0
	v_mov_b32_e32 v65, v0
	v_mov_b32_e32 v66, v0
	v_mov_b32_e32 v67, v0
	v_mov_b32_e32 v76, v0
	v_mov_b32_e32 v77, v0
	v_mov_b32_e32 v78, v0
	v_mov_b32_e32 v79, v0
	v_mov_b32_e32 v88, v0
	v_mov_b32_e32 v89, v0
	v_mov_b32_e32 v90, v0
	v_mov_b32_e32 v91, v0
	v_mov_b32_e32 v100, v0
	v_mov_b32_e32 v101, v0
	v_mov_b32_e32 v102, v0
	v_mov_b32_e32 v103, v0
	v_mov_b32_e32 v112, v0
	v_mov_b32_e32 v113, v0
	v_mov_b32_e32 v114, v0
	v_mov_b32_e32 v115, v0
	v_mov_b32_e32 v60, v0
	v_mov_b32_e32 v61, v0
	v_mov_b32_e32 v62, v0
	v_mov_b32_e32 v63, v0
	v_mov_b32_e32 v72, v0
	v_mov_b32_e32 v73, v0
	v_mov_b32_e32 v74, v0
	v_mov_b32_e32 v75, v0
	v_mov_b32_e32 v84, v0
	v_mov_b32_e32 v85, v0
	v_mov_b32_e32 v86, v0
	v_mov_b32_e32 v87, v0
	v_mov_b32_e32 v96, v0
	v_mov_b32_e32 v97, v0
	v_mov_b32_e32 v98, v0
	v_mov_b32_e32 v99, v0
	v_mov_b32_e32 v108, v0
	v_mov_b32_e32 v109, v0
	v_mov_b32_e32 v110, v0
	v_mov_b32_e32 v111, v0
	v_mov_b32_e32 v120, v0
	v_mov_b32_e32 v121, v0
	v_mov_b32_e32 v122, v0
	v_mov_b32_e32 v123, v0
	v_mov_b32_e32 v128, v0
	v_mov_b32_e32 v129, v0
	v_mov_b32_e32 v130, v0
	v_mov_b32_e32 v131, v0
	v_mov_b32_e32 v136, v0
	v_mov_b32_e32 v137, v0
	v_mov_b32_e32 v138, v0
	v_mov_b32_e32 v139, v0
	v_mov_b32_e32 v92, v0
	v_mov_b32_e32 v93, v0
	v_mov_b32_e32 v94, v0
	v_mov_b32_e32 v95, v0
	v_mov_b32_e32 v104, v0
	v_mov_b32_e32 v105, v0
	v_mov_b32_e32 v106, v0
	v_mov_b32_e32 v107, v0
	v_mov_b32_e32 v116, v0
	v_mov_b32_e32 v117, v0
	v_mov_b32_e32 v118, v0
	v_mov_b32_e32 v119, v0
	v_mov_b32_e32 v124, v0
	v_mov_b32_e32 v125, v0
	v_mov_b32_e32 v126, v0
	v_mov_b32_e32 v127, v0
	v_mov_b32_e32 v132, v0
	v_mov_b32_e32 v133, v0
	v_mov_b32_e32 v134, v0
	v_mov_b32_e32 v135, v0
	v_mov_b32_e32 v140, v0
	v_mov_b32_e32 v141, v0
	v_mov_b32_e32 v142, v0
	v_mov_b32_e32 v143, v0
	v_mov_b32_e32 v144, v0
	v_mov_b32_e32 v145, v0
	v_mov_b32_e32 v146, v0
	v_mov_b32_e32 v147, v0
	v_mov_b32_e32 v148, v0
	v_mov_b32_e32 v149, v0
	v_mov_b32_e32 v150, v0
	v_mov_b32_e32 v151, v0
	s_add_u32 s98, s42, s22
	s_addc_u32 s99, s43, 0
	s_add_u32 s100, s42, s23
	s_addc_u32 s101, s43, 0
; DI f32x4 mfma16(bf16x8 a, bf16x8 b, f32x4 c) { return __builtin_amdgcn_mfma_f32_16x16x32_bf16(a, b, c, 0, 0, 0); }
; template <int NI, class XL, class EP>
; DI void gemm_tile(const u16* __restrict__ W, int ldw, int f0, int t0, int K, XL xl, EP ep, unsigned char* smem) {
;     ...
;   for (int it = 0; it < nk; ++it) {
;     const u16* Ws = S0 + (it & 1) * BUF; const u16* Xs = Ws + 128 * LST;
;     __builtin_amdgcn_s_setprio(1);
;     bf16x8 a[4];
; #pragma unroll
;     for (int mi = 0; mi < 4; ++mi) a[mi] = *(const bf16x8*)(Ws + (wf * 64 + mi * 16 + lr) * LST + lq * 8);
; #pragma unroll
;     for (int ni = 0; ni < NI; ++ni) {
;       const bf16x8 b = *(const bf16x8*)(Xs + (wt * (NI * 16) + ni * 16 + lr) * LST + lq * 8);
; #pragma unroll
;       for (int mi = 0; mi < 4; ++mi) acc[mi][ni] = mfma16(a[mi], b, acc[mi][ni]);
;     }
;     __builtin_amdgcn_sched_group_barrier(0x100, 6, 0);
; #pragma unroll
;     for (int ni = 0; ni < NI; ++ni) { __builtin_amdgcn_sched_group_barrier(0x008, 4, 0); if (ni + 2 < NI) __builtin_amdgcn_sched_group_barrier(0x100, 1, 0); }
;     __builtin_amdgcn_s_setprio(0);
;     if (it + 1 < nk) lstore((it + 1) & 1);
;     if (it + 2 < nk) gload(it + 2);
;     __syncthreads();
.LBB0_1095:
	s_bitcmp1_b32 s33, 0
	s_cselect_b32 s34, 0, 0x9000
	s_setprio 1
	v_or_b32_e32 v152, s34, v164
	v_lshl_add_u32 v184, v167, 1, v152
	ds_read_b128 v[168:171], v184
	ds_read_b128 v[172:175], v184 offset:1536
	ds_read_b128 v[180:183], v184 offset:3072
	ds_read_b128 v[184:187], v184 offset:4608
	v_lshl_add_u32 v152, v165, 1, v152
	ds_read_b128 v[176:179], v152 offset:12288
	ds_read_b128 v[188:191], v152 offset:13824
	s_xor_b32 s34, s34, 0x9000
	v_add3_u32 v220, v166, s34, v161
	s_waitcnt lgkmcnt(1)
	v_mfma_f32_16x16x32_bf16 v[148:151], v[168:171], v[176:179], v[148:151]
	v_mfma_f32_16x16x32_bf16 v[136:139], v[172:175], v[176:179], v[136:139]
	v_mfma_f32_16x16x32_bf16 v[112:115], v[180:183], v[176:179], v[112:115]
	v_mfma_f32_16x16x32_bf16 v[80:83], v[184:187], v[176:179], v[80:83]
	ds_read_b128 v[176:179], v152 offset:15360
	s_waitcnt vmcnt(5)
	ds_write_b128 v220, v[20:23]
	s_waitcnt lgkmcnt(2)
	v_mfma_f32_16x16x32_bf16 v[144:147], v[168:171], v[188:191], v[144:147]
	v_mfma_f32_16x16x32_bf16 v[128:131], v[172:175], v[188:191], v[128:131]
	v_mfma_f32_16x16x32_bf16 v[100:103], v[180:183], v[188:191], v[100:103]
	v_mfma_f32_16x16x32_bf16 v[68:71], v[184:187], v[188:191], v[68:71]
	ds_read_b128 v[188:191], v152 offset:16896
	s_waitcnt vmcnt(4)
	ds_write_b128 v220, v[16:19] offset:96
	v_add_u32_e32 v220, v220, v166
	global_load_dwordx4 v[20:23], v154, s[98:99]
	global_load_dwordx4 v[16:19], v154, s[98:99] offset:64
	s_waitcnt lgkmcnt(3)
	v_mfma_f32_16x16x32_bf16 v[140:143], v[168:171], v[176:179], v[140:143]
	v_mfma_f32_16x16x32_bf16 v[120:123], v[172:175], v[176:179], v[120:123]
	v_mfma_f32_16x16x32_bf16 v[88:91], v[180:183], v[176:179], v[88:91]
	v_mfma_f32_16x16x32_bf16 v[44:47], v[184:187], v[176:179], v[44:47]
	ds_read_b128 v[176:179], v152 offset:18432
	s_waitcnt vmcnt(5)
	ds_write_b128 v220, v[36:39] offset:12288
	global_load_dwordx4 v[36:39], v156, s[100:101] offset:2048
	s_waitcnt lgkmcnt(3)
	v_mfma_f32_16x16x32_bf16 v[132:135], v[168:171], v[188:191], v[132:135]
	v_mfma_f32_16x16x32_bf16 v[108:111], v[172:175], v[188:191], v[108:111]
	v_mfma_f32_16x16x32_bf16 v[76:79], v[180:183], v[188:191], v[76:79]
	v_mfma_f32_16x16x32_bf16 v[40:43], v[184:187], v[188:191], v[40:43]
	ds_read_b128 v[188:191], v152 offset:19968
	s_waitcnt vmcnt(5)
	ds_write_b128 v220, v[32:35] offset:12384
	global_load_dwordx4 v[32:35], v156, s[100:101] offset:2112
	s_waitcnt lgkmcnt(3)
	v_mfma_f32_16x16x32_bf16 v[124:127], v[168:171], v[176:179], v[124:127]
	v_mfma_f32_16x16x32_bf16 v[96:99], v[172:175], v[176:179], v[96:99]
	v_mfma_f32_16x16x32_bf16 v[64:67], v[180:183], v[176:179], v[64:67]
	v_mfma_f32_16x16x32_bf16 v[12:15], v[184:187], v[176:179], v[12:15]
	ds_read_b128 v[176:179], v152 offset:21504
	s_waitcnt vmcnt(5)
	ds_write_b128 v220, v[28:31] offset:12480
	global_load_dwordx4 v[28:31], v156, s[100:101] offset:2176
	s_waitcnt lgkmcnt(3)
	v_mfma_f32_16x16x32_bf16 v[116:119], v[168:171], v[188:191], v[116:119]
	v_mfma_f32_16x16x32_bf16 v[84:87], v[172:175], v[188:191], v[84:87]
	v_mfma_f32_16x16x32_bf16 v[56:59], v[180:183], v[188:191], v[56:59]
	v_mfma_f32_16x16x32_bf16 v[8:11], v[184:187], v[188:191], v[8:11]
	ds_read_b128 v[188:191], v152 offset:23040
	s_waitcnt vmcnt(5)
	ds_write_b128 v220, v[24:27] offset:12576
	global_load_dwordx4 v[24:27], v156, s[100:101] offset:2240
	s_waitcnt lgkmcnt(3)
	v_mfma_f32_16x16x32_bf16 v[104:107], v[168:171], v[176:179], v[104:107]
	v_mfma_f32_16x16x32_bf16 v[72:75], v[172:175], v[176:179], v[72:75]
	v_mfma_f32_16x16x32_bf16 v[52:55], v[180:183], v[176:179], v[52:55]
	v_mfma_f32_16x16x32_bf16 v[4:7], v[184:187], v[176:179], v[4:7]
	s_add_u32 s98, s98, s16
	s_addc_u32 s99, s99, s17
	s_add_u32 s100, s100, s14
	s_addc_u32 s101, s101, s15
	s_add_i32 s33, s33, 1
	s_waitcnt lgkmcnt(1)
	v_mfma_f32_16x16x32_bf16 v[92:95], v[168:171], v[188:191], v[92:95]
	v_mfma_f32_16x16x32_bf16 v[60:63], v[172:175], v[188:191], v[60:63]
	v_mfma_f32_16x16x32_bf16 v[48:51], v[180:183], v[188:191], v[48:51]
	v_mfma_f32_16x16x32_bf16 v[0:3], v[184:187], v[188:191], v[0:3]
	s_setprio 0
	s_cmpk_lg_i32 s33, 0x57
	s_waitcnt lgkmcnt(0)
	s_barrier
	s_cbranch_scc1 .LBB0_1095
	s_setprio 1
	v_lshl_add_u32 v152, v167, 1, v164
	ds_read_b128 v[154:157], v152
	v_lshl_add_u32 v161, v165, 1, v164
	ds_read_b128 v[164:167], v152 offset:1536
	ds_read_b128 v[172:175], v152 offset:3072
	ds_read_b128 v[176:179], v152 offset:4608
	ds_read_b128 v[168:171], v161 offset:12288
	ds_read_b128 v[180:183], v161 offset:13824
	s_waitcnt lgkmcnt(1)
	v_mfma_f32_16x16x32_bf16 v[148:151], v[154:157], v[168:171], v[148:151]
	v_mfma_f32_16x16x32_bf16 v[136:139], v[164:167], v[168:171], v[136:139]
	v_mfma_f32_16x16x32_bf16 v[112:115], v[172:175], v[168:171], v[112:115]
	v_mfma_f32_16x16x32_bf16 v[80:83], v[176:179], v[168:171], v[80:83]
	ds_read_b128 v[168:171], v161 offset:15360
	s_waitcnt lgkmcnt(1)
	v_mfma_f32_16x16x32_bf16 v[144:147], v[154:157], v[180:183], v[144:147]
	v_mfma_f32_16x16x32_bf16 v[128:131], v[164:167], v[180:183], v[128:131]
	v_mfma_f32_16x16x32_bf16 v[100:103], v[172:175], v[180:183], v[100:103]
	v_mfma_f32_16x16x32_bf16 v[68:71], v[176:179], v[180:183], v[68:71]
	ds_read_b128 v[180:183], v161 offset:16896
	s_waitcnt lgkmcnt(1)
	v_mfma_f32_16x16x32_bf16 v[140:143], v[154:157], v[168:171], v[140:143]
	v_mfma_f32_16x16x32_bf16 v[120:123], v[164:167], v[168:171], v[120:123]
	v_mfma_f32_16x16x32_bf16 v[184:187], v[172:175], v[168:171], v[88:91]
	v_mfma_f32_16x16x32_bf16 v[44:47], v[176:179], v[168:171], v[44:47]
	s_nop 1
	ds_read_b128 v[88:91], v161 offset:18432
	s_waitcnt lgkmcnt(1)
; DI f32x4 mfma16(bf16x8 a, bf16x8 b, f32x4 c) { return __builtin_amdgcn_mfma_f32_16x16x32_bf16(a, b, c, 0, 0, 0); }
; template <int NI, class XL, class EP>
; DI void gemm_tile(const u16* __restrict__ W, int ldw, int f0, int t0, int K, XL xl, EP ep, unsigned char* smem) {
;     ...
;   for (int it = 0; it < nk; ++it) {
;     const u16* Ws = S0 + (it & 1) * BUF; const u16* Xs = Ws + 128 * LST;
;     __builtin_amdgcn_s_setprio(1);
;     bf16x8 a[4];
; #pragma unroll
;     for (int mi = 0; mi < 4; ++mi) a[mi] = *(const bf16x8*)(Ws + (wf * 64 + mi * 16 + lr) * LST + lq * 8);
; #pragma unroll
;     for (int ni = 0; ni < NI; ++ni) {
;       const bf16x8 b = *(const bf16x8*)(Xs + (wt * (NI * 16) + ni * 16 + lr) * LST + lq * 8);
; #pragma unroll
;       for (int mi = 0; mi < 4; ++mi) acc[mi][ni] = mfma16(a[mi], b, acc[mi][ni]);
;     }
;     __builtin_amdgcn_sched_group_barrier(0x100, 6, 0);
; #pragma unroll
;     for (int ni = 0; ni < NI; ++ni) { __builtin_amdgcn_sched_group_barrier(0x008, 4, 0); if (ni + 2 < NI) __builtin_amdgcn_sched_group_barrier(0x100, 1, 0); }
;     __builtin_amdgcn_s_setprio(0);
;     if (it + 1 < nk) lstore((it + 1) & 1);
;     if (it + 2 < nk) gload(it + 2);
;     __syncthreads();
;   }
;   ep(acc, f0 + wf * 64, t0 + wt * (NI * 16), lr, lq, wf, wt);
; DI void phase9(const Params& p, const Sched& sched, unsigned char* smem) {
;     ...
;       constexpr int EST = 136;
;       u16* Ls = (u16*)smem;
;       const int b = tb >> 11;
;       __syncthreads();
; #pragma unroll
;       for (int mi = 0; mi < 4; ++mi) {
;         const int f = fb + mi * 16 + lq * 4; const float4 gm = *(const float4*)(mod + (size_t)b * 6144 + 5120 + f);
	v_mfma_f32_16x16x32_bf16 v[132:135], v[154:157], v[180:183], v[132:135]
	v_mfma_f32_16x16x32_bf16 v[168:171], v[164:167], v[180:183], v[108:111]
	v_mfma_f32_16x16x32_bf16 v[188:191], v[172:175], v[180:183], v[76:79]
	v_mfma_f32_16x16x32_bf16 v[180:183], v[176:179], v[180:183], v[40:43]
	s_nop 2
	ds_read_b128 v[40:43], v161 offset:19968
	s_waitcnt lgkmcnt(1)
	v_mfma_f32_16x16x32_bf16 v[124:127], v[154:157], v[88:91], v[124:127]
	v_mfma_f32_16x16x32_bf16 v[192:195], v[164:167], v[88:91], v[96:99]
	v_mfma_f32_16x16x32_bf16 v[196:199], v[172:175], v[88:91], v[64:67]
	v_mfma_f32_16x16x32_bf16 v[200:203], v[176:179], v[88:91], v[12:15]
	s_nop 2
	ds_read_b128 v[12:15], v161 offset:21504
	s_waitcnt lgkmcnt(1)
	v_mfma_f32_16x16x32_bf16 v[116:119], v[154:157], v[40:43], v[116:119]
	v_mfma_f32_16x16x32_bf16 v[204:207], v[164:167], v[40:43], v[84:87]
	v_mfma_f32_16x16x32_bf16 v[56:59], v[172:175], v[40:43], v[56:59]
	v_mfma_f32_16x16x32_bf16 v[208:211], v[176:179], v[40:43], v[8:11]
	s_nop 2
	ds_read_b128 v[8:11], v161 offset:23040
	s_waitcnt lgkmcnt(1)
	v_mfma_f32_16x16x32_bf16 v[212:215], v[154:157], v[12:15], v[104:107]
	v_mfma_f32_16x16x32_bf16 v[72:75], v[164:167], v[12:15], v[72:75]
	v_mfma_f32_16x16x32_bf16 v[220:223], v[172:175], v[12:15], v[52:55]
	v_mfma_f32_16x16x32_bf16 v[224:227], v[176:179], v[12:15], v[4:7]
	s_waitcnt lgkmcnt(0)
	v_mfma_f32_16x16x32_bf16 v[154:157], v[154:157], v[8:11], v[92:95]
	v_mfma_f32_16x16x32_bf16 v[60:63], v[164:167], v[8:11], v[60:63]
	v_mfma_f32_16x16x32_bf16 v[164:167], v[172:175], v[8:11], v[48:51]
	v_mfma_f32_16x16x32_bf16 v[172:175], v[176:179], v[8:11], v[0:3]
	s_setprio 0
	s_waitcnt vmcnt(5)
	ds_write_b128 v162, v[20:23] offset:36864
	s_waitcnt vmcnt(4)
	ds_write_b128 v162, v[16:19] offset:36960
	s_waitcnt vmcnt(3)
	ds_write_b128 v163, v[36:39] offset:49152
	s_waitcnt vmcnt(2)
	ds_write_b128 v163, v[32:35] offset:49248
	s_waitcnt vmcnt(1)
	ds_write_b128 v163, v[28:31] offset:49344
	s_waitcnt vmcnt(0)
	ds_write_b128 v163, v[24:27] offset:49440
	s_waitcnt lgkmcnt(0)
	s_barrier
	s_lshl_b32 s30, s30, 7
	s_setprio 1
	ds_read_b128 v[28:31], v152 offset:36864
	ds_read_b128 v[176:179], v152 offset:38400
	ds_read_b128 v[228:231], v152 offset:39936
	ds_read_b128 v[232:235], v152 offset:41472
	ds_read_b128 v[0:3], v161 offset:49152
	ds_read_b128 v[4:7], v161 offset:50688
	s_waitcnt lgkmcnt(1)
	v_mfma_f32_16x16x32_bf16 v[88:91], v[28:31], v[0:3], v[148:151]
	v_mfma_f32_16x16x32_bf16 v[64:67], v[176:179], v[0:3], v[136:139]
	v_mfma_f32_16x16x32_bf16 v[32:35], v[228:231], v[0:3], v[112:115]
	v_mfma_f32_16x16x32_bf16 v[0:3], v[232:235], v[0:3], v[80:83]
	ds_read_b128 v[8:11], v161 offset:52224
	s_waitcnt lgkmcnt(1)
	v_mfma_f32_16x16x32_bf16 v[96:99], v[28:31], v[4:7], v[144:147]
	v_mfma_f32_16x16x32_bf16 v[76:79], v[176:179], v[4:7], v[128:131]
	v_mfma_f32_16x16x32_bf16 v[36:39], v[228:231], v[4:7], v[100:103]
	v_mfma_f32_16x16x32_bf16 v[4:7], v[232:235], v[4:7], v[68:71]
	ds_read_b128 v[12:15], v161 offset:53760
	s_waitcnt lgkmcnt(1)
	v_mfma_f32_16x16x32_bf16 v[104:107], v[28:31], v[8:11], v[140:143]
	v_mfma_f32_16x16x32_bf16 v[84:87], v[176:179], v[8:11], v[120:123]
	v_mfma_f32_16x16x32_bf16 v[40:43], v[228:231], v[8:11], v[184:187]
	v_mfma_f32_16x16x32_bf16 v[8:11], v[232:235], v[8:11], v[44:47]
	ds_read_b128 v[16:19], v161 offset:55296
	s_waitcnt lgkmcnt(1)
	v_mfma_f32_16x16x32_bf16 v[108:111], v[28:31], v[12:15], v[132:135]
	v_mfma_f32_16x16x32_bf16 v[92:95], v[176:179], v[12:15], v[168:171]
	v_mfma_f32_16x16x32_bf16 v[44:47], v[228:231], v[12:15], v[188:191]
	v_mfma_f32_16x16x32_bf16 v[12:15], v[232:235], v[12:15], v[180:183]
	ds_read_b128 v[20:23], v161 offset:56832
	s_waitcnt lgkmcnt(1)
	v_mfma_f32_16x16x32_bf16 v[112:115], v[28:31], v[16:19], v[124:127]
	v_mfma_f32_16x16x32_bf16 v[100:103], v[176:179], v[16:19], v[192:195]
	v_mfma_f32_16x16x32_bf16 v[48:51], v[228:231], v[16:19], v[196:199]
	v_mfma_f32_16x16x32_bf16 v[16:19], v[232:235], v[16:19], v[200:203]
	ds_read_b128 v[24:27], v161 offset:58368
	s_waitcnt lgkmcnt(1)
	v_mfma_f32_16x16x32_bf16 v[116:119], v[28:31], v[20:23], v[116:119]
	v_mfma_f32_16x16x32_bf16 v[68:71], v[176:179], v[20:23], v[204:207]
	v_mfma_f32_16x16x32_bf16 v[52:55], v[228:231], v[20:23], v[56:59]
	v_mfma_f32_16x16x32_bf16 v[20:23], v[232:235], v[20:23], v[208:211]
	ds_read_b128 v[128:131], v161 offset:59904
	s_waitcnt lgkmcnt(1)
	v_mfma_f32_16x16x32_bf16 v[120:123], v[28:31], v[24:27], v[212:215]
	v_mfma_f32_16x16x32_bf16 v[80:83], v[176:179], v[24:27], v[72:75]
	v_mfma_f32_16x16x32_bf16 v[56:59], v[228:231], v[24:27], v[220:223]
	v_mfma_f32_16x16x32_bf16 v[24:27], v[232:235], v[24:27], v[224:227]
	s_waitcnt lgkmcnt(0)
	v_mfma_f32_16x16x32_bf16 v[124:127], v[28:31], v[128:131], v[154:157]
	v_mfma_f32_16x16x32_bf16 v[72:75], v[176:179], v[128:131], v[60:63]
	v_mfma_f32_16x16x32_bf16 v[60:63], v[228:231], v[128:131], v[164:167]
	v_mfma_f32_16x16x32_bf16 v[28:31], v[232:235], v[128:131], v[172:175]
	s_setprio 0
	s_ashr_i32 s31, s31, 3
	v_add_u32_e32 v128, s30, v160
	s_mul_hi_i32 s33, s31, 0x6000
	s_mulk_i32 s31, 0x6000
	v_lshl_or_b32 v128, v158, 2, v128
	s_add_u32 s34, s72, s31
	s_addc_u32 s35, s73, s33
	v_ashrrev_i32_e32 v129, 31, v128
	v_lshl_add_u64 v[128:129], v[128:129], 2, s[34:35]
	v_add_co_u32_e32 v140, vcc, s24, v128
	v_mul_u32_u24_e32 v138, 0x88, v159
	s_nop 0
	v_addc_co_u32_e32 v141, vcc, 0, v129, vcc
	v_lshlrev_b32_e32 v136, 1, v160
	v_lshlrev_b32_e32 v137, 3, v158
	v_lshlrev_b32_e32 v138, 1, v138
	s_barrier
	s_barrier
; DI void store4(u16* dst, f32x4 v) { uint2 w; w.x = cvtpk(v[0], v[1]); w.y = cvtpk(v[2], v[3]); *(uint2*)dst = w; }
; DI void phase9(const Params& p, const Sched& sched, unsigned char* smem) {
;     ...
;       const int b = tb >> 11;
;       __syncthreads();
; #pragma unroll
;       for (int mi = 0; mi < 4; ++mi) {
;         const int f = fb + mi * 16 + lq * 4; const float4 gm = *(const float4*)(mod + (size_t)b * 6144 + 5120 + f);
; #pragma unroll
;         for (int ni = 0; ni < 8; ++ni) {
;           const f32x4 o = {gm.x * acc[mi][ni][0], gm.y * acc[mi][ni][1], gm.z * acc[mi][ni][2], gm.w * acc[mi][ni][3]};
;           store4(Ls + (wt * 128 + ni * 16 + lr) * EST + wf * 64 + mi * 16 + lq * 4, o);
;         }
;       }
;       __syncthreads();
	global_load_dwordx4 v[128:131], v[140:141], off
	global_load_dwordx4 v[132:135], v[140:141], off offset:64
	v_add3_u32 v144, v136, v137, v138
	global_load_dwordx4 v[136:139], v[140:141], off offset:128
	v_add_u32_e32 v145, 0x1000, v144
	global_load_dwordx4 v[140:143], v[140:141], off offset:192
	v_add_u32_e32 v146, 0x2000, v144
	v_add_u32_e32 v147, 0x3000, v144
	v_add_u32_e32 v148, 0x4000, v144
	s_add_i32 s28, s28, s78
	s_add_i32 s27, s27, s78
	s_cmp_gt_i32 s28, 63
	s_waitcnt vmcnt(3)
	v_pk_mul_f32 v[88:89], v[88:89], v[128:129]
	v_pk_mul_f32 v[90:91], v[90:91], v[130:131]
	v_pk_mul_f32 v[96:97], v[96:97], v[128:129]
	s_waitcnt vmcnt(1)
	v_pk_mul_f32 v[32:33], v[32:33], v[136:137]
	v_pk_mul_f32 v[34:35], v[34:35], v[138:139]
	s_waitcnt vmcnt(0)
	v_pk_mul_f32 v[0:1], v[0:1], v[140:141]
	v_pk_mul_f32 v[2:3], v[2:3], v[142:143]
	v_cvt_pk_bf16_f32 v32, v32, v33
	v_cvt_pk_bf16_f32 v33, v34, v35
	v_cvt_pk_bf16_f32 v0, v0, v1
	v_cvt_pk_bf16_f32 v1, v2, v3
	v_pk_mul_f32 v[34:35], v[36:37], v[136:137]
	v_pk_mul_f32 v[36:37], v[38:39], v[138:139]
	ds_write2_b64 v144, v[32:33], v[0:1] offset0:8 offset1:12
	v_pk_mul_f32 v[0:1], v[4:5], v[140:141]
	v_pk_mul_f32 v[2:3], v[6:7], v[142:143]
	v_cvt_pk_bf16_f32 v34, v34, v35
	v_cvt_pk_bf16_f32 v35, v36, v37
	v_cvt_pk_bf16_f32 v0, v0, v1
	v_cvt_pk_bf16_f32 v1, v2, v3
	v_pk_mul_f32 v[36:37], v[40:41], v[136:137]
	v_pk_mul_f32 v[38:39], v[42:43], v[138:139]
	ds_write2_b64 v145, v[34:35], v[0:1] offset0:40 offset1:44
	v_pk_mul_f32 v[0:1], v[8:9], v[140:141]
	v_pk_mul_f32 v[2:3], v[10:11], v[142:143]
	v_cvt_pk_bf16_f32 v36, v36, v37
	v_cvt_pk_bf16_f32 v37, v38, v39
	v_cvt_pk_bf16_f32 v0, v0, v1
	v_cvt_pk_bf16_f32 v1, v2, v3
	v_pk_mul_f32 v[38:39], v[44:45], v[136:137]
	v_pk_mul_f32 v[40:41], v[46:47], v[138:139]
	ds_write2_b64 v146, v[36:37], v[0:1] offset0:72 offset1:76
	v_pk_mul_f32 v[0:1], v[12:13], v[140:141]
	v_pk_mul_f32 v[2:3], v[14:15], v[142:143]
	v_cvt_pk_bf16_f32 v38, v38, v39
	v_cvt_pk_bf16_f32 v39, v40, v41
	v_cvt_pk_bf16_f32 v0, v0, v1
	v_cvt_pk_bf16_f32 v1, v2, v3
	v_pk_mul_f32 v[98:99], v[98:99], v[130:131]
	v_pk_mul_f32 v[64:65], v[64:65], v[132:133]
	v_pk_mul_f32 v[66:67], v[66:67], v[134:135]
	v_pk_mul_f32 v[76:77], v[76:77], v[132:133]
	v_pk_mul_f32 v[78:79], v[78:79], v[134:135]
	v_pk_mul_f32 v[40:41], v[48:49], v[136:137]
	v_pk_mul_f32 v[42:43], v[50:51], v[138:139]
	ds_write2_b64 v147, v[38:39], v[0:1] offset0:104 offset1:108
	v_pk_mul_f32 v[0:1], v[16:17], v[140:141]
	v_pk_mul_f32 v[2:3], v[18:19], v[142:143]
	v_cvt_pk_bf16_f32 v88, v88, v89
	v_cvt_pk_bf16_f32 v89, v90, v91
	v_cvt_pk_bf16_f32 v90, v96, v97
	v_cvt_pk_bf16_f32 v91, v98, v99
	v_cvt_pk_bf16_f32 v64, v64, v65
	v_cvt_pk_bf16_f32 v65, v66, v67
	v_cvt_pk_bf16_f32 v66, v76, v77
	v_cvt_pk_bf16_f32 v67, v78, v79
	v_cvt_pk_bf16_f32 v40, v40, v41
	v_cvt_pk_bf16_f32 v41, v42, v43
	v_cvt_pk_bf16_f32 v0, v0, v1
	v_cvt_pk_bf16_f32 v1, v2, v3
	v_pk_mul_f32 v[106:107], v[106:107], v[130:131]
	v_pk_mul_f32 v[116:117], v[116:117], v[128:129]
	v_pk_mul_f32 v[118:119], v[118:119], v[130:131]
	ds_write2_b64 v144, v[88:89], v[64:65] offset1:4
	ds_write2_b64 v145, v[90:91], v[66:67] offset0:32 offset1:36
	v_pk_mul_f32 v[64:65], v[68:69], v[132:133]
	v_pk_mul_f32 v[66:67], v[70:71], v[134:135]
	v_pk_mul_f32 v[42:43], v[52:53], v[136:137]
	v_pk_mul_f32 v[44:45], v[54:55], v[138:139]
	ds_write2_b64 v148, v[40:41], v[0:1] offset0:136 offset1:140
	v_pk_mul_f32 v[0:1], v[20:21], v[140:141]
	v_pk_mul_f32 v[2:3], v[22:23], v[142:143]
	v_cvt_pk_bf16_f32 v97, v106, v107
	v_cvt_pk_bf16_f32 v106, v116, v117
	v_cvt_pk_bf16_f32 v107, v118, v119
	v_cvt_pk_bf16_f32 v64, v64, v65
	v_cvt_pk_bf16_f32 v65, v66, v67
	v_add_u32_e32 v68, 0x5000, v144
	v_cvt_pk_bf16_f32 v42, v42, v43
	v_cvt_pk_bf16_f32 v43, v44, v45
	v_cvt_pk_bf16_f32 v0, v0, v1
	v_cvt_pk_bf16_f32 v1, v2, v3
	v_pk_mul_f32 v[108:109], v[108:109], v[128:129]
	v_pk_mul_f32 v[120:121], v[120:121], v[128:129]
	v_pk_mul_f32 v[122:123], v[122:123], v[130:131]
	ds_write2_b64 v68, v[106:107], v[64:65] offset0:160 offset1:164
	v_pk_mul_f32 v[64:65], v[80:81], v[132:133]
	v_pk_mul_f32 v[66:67], v[82:83], v[134:135]
	v_pk_mul_f32 v[44:45], v[56:57], v[136:137]
	v_pk_mul_f32 v[46:47], v[58:59], v[138:139]
	ds_write2_b64 v68, v[42:43], v[0:1] offset0:168 offset1:172
	v_pk_mul_f32 v[0:1], v[24:25], v[140:141]
	v_pk_mul_f32 v[2:3], v[26:27], v[142:143]
	v_cvt_pk_bf16_f32 v98, v108, v109
	v_cvt_pk_bf16_f32 v108, v120, v121
	v_cvt_pk_bf16_f32 v109, v122, v123
	v_cvt_pk_bf16_f32 v64, v64, v65
	v_cvt_pk_bf16_f32 v65, v66, v67
	v_add_u32_e32 v69, 0x6000, v144
	v_cvt_pk_bf16_f32 v44, v44, v45
	v_cvt_pk_bf16_f32 v45, v46, v47
	v_cvt_pk_bf16_f32 v0, v0, v1
	v_cvt_pk_bf16_f32 v1, v2, v3
	v_pk_mul_f32 v[104:105], v[104:105], v[128:129]
	v_pk_mul_f32 v[110:111], v[110:111], v[130:131]
	v_pk_mul_f32 v[112:113], v[112:113], v[128:129]
	v_pk_mul_f32 v[114:115], v[114:115], v[130:131]
	v_pk_mul_f32 v[124:125], v[124:125], v[128:129]
	v_pk_mul_f32 v[126:127], v[126:127], v[130:131]
	v_pk_mul_f32 v[84:85], v[84:85], v[132:133]
	v_pk_mul_f32 v[86:87], v[86:87], v[134:135]
	v_pk_mul_f32 v[92:93], v[92:93], v[132:133]
	v_pk_mul_f32 v[94:95], v[94:95], v[134:135]
	v_pk_mul_f32 v[100:101], v[100:101], v[132:133]
	v_pk_mul_f32 v[102:103], v[102:103], v[134:135]
	ds_write2_b64 v69, v[108:109], v[64:65] offset0:192 offset1:196
	v_pk_mul_f32 v[64:65], v[72:73], v[132:133]
	v_pk_mul_f32 v[66:67], v[74:75], v[134:135]
	v_pk_mul_f32 v[46:47], v[60:61], v[136:137]
	v_pk_mul_f32 v[48:49], v[62:63], v[138:139]
	ds_write2_b64 v69, v[44:45], v[0:1] offset0:200 offset1:204
	v_pk_mul_f32 v[0:1], v[28:29], v[140:141]
	v_pk_mul_f32 v[2:3], v[30:31], v[142:143]
	v_cvt_pk_bf16_f32 v96, v104, v105
	v_cvt_pk_bf16_f32 v99, v110, v111
	v_cvt_pk_bf16_f32 v104, v112, v113
	v_cvt_pk_bf16_f32 v105, v114, v115
	v_cvt_pk_bf16_f32 v110, v124, v125
	v_cvt_pk_bf16_f32 v111, v126, v127
	v_cvt_pk_bf16_f32 v76, v84, v85
	v_cvt_pk_bf16_f32 v77, v86, v87
	v_cvt_pk_bf16_f32 v78, v92, v93
	v_cvt_pk_bf16_f32 v79, v94, v95
	v_cvt_pk_bf16_f32 v84, v100, v101
	v_cvt_pk_bf16_f32 v85, v102, v103
	v_cvt_pk_bf16_f32 v64, v64, v65
	v_cvt_pk_bf16_f32 v65, v66, v67
	v_add_u32_e32 v66, 0x7000, v144
	v_cvt_pk_bf16_f32 v46, v46, v47
	v_cvt_pk_bf16_f32 v47, v48, v49
	v_cvt_pk_bf16_f32 v0, v0, v1
	v_cvt_pk_bf16_f32 v1, v2, v3
	v_mov_b32_e32 v2, v218
	ds_write2_b64 v146, v[96:97], v[76:77] offset0:64 offset1:68
	ds_write2_b64 v147, v[98:99], v[78:79] offset0:96 offset1:100
	ds_write2_b64 v148, v[104:105], v[84:85] offset0:128 offset1:132
	ds_write2_b64 v66, v[110:111], v[64:65] offset0:224 offset1:228
	ds_write2_b64 v66, v[46:47], v[0:1] offset0:232 offset1:236
	s_waitcnt lgkmcnt(0)
	s_barrier
; DI int tidx() { int t = __builtin_amdgcn_workitem_id_x(); asm volatile("" : "+v"(t)); return t; }
; DI unsigned cvtpk(float lo, float hi) { const f32x2_ v = {lo, hi}; return __builtin_bit_cast(unsigned, __builtin_convertvector(v, bf16x2_)); }
; DI float bflo(unsigned w) { return __uint_as_float(w << 16); }
; DI float bfhi(unsigned w) { return __uint_as_float(w & 0xffff0000u); }
; DI void phase9(const Params& p, const Sched& sched, unsigned char* smem) {
;     ...
;       const int tid = tidx();
; #pragma unroll
;       for (int i = 0; i < 16; ++i) {
;         const int c = tid + 256 * i, row = c >> 4, ch = (c & 15) * 8;
;         const size_t gi = (size_t)(tm * 256 + row) * 1024 + tn * 128 + ch;
;         const u32x4 sv = *(const u32x4*)(Ls + row * EST + ch), xv = *(const u32x4*)(x1b + gi);
;         u32x4 w;
;         w.x = cvtpk(bflo(xv.x) + bflo(sv.x), bfhi(xv.x) + bfhi(sv.x)); w.y = cvtpk(bflo(xv.y) + bflo(sv.y), bfhi(xv.y) + bfhi(sv.y));
;         w.z = cvtpk(bflo(xv.z) + bflo(sv.z), bfhi(xv.z) + bfhi(sv.z)); w.w = cvtpk(bflo(xv.w) + bflo(sv.w), bfhi(xv.w) + bfhi(sv.w));
;         *(u32x4*)(x2b + gi) = w;
;       }
	s_nop 0
	v_ashrrev_i32_e32 v3, 4, v2
	v_add_u32_e32 v4, s29, v3
	v_lshlrev_b32_e32 v0, 3, v2
	v_ashrrev_i32_e32 v5, 31, v4
	v_and_b32_e32 v1, 0x78, v0
	v_lshlrev_b64 v[4:5], 10, v[4:5]
	v_or3_b32 v4, v4, s30, v1
	v_lshlrev_b64 v[12:13], 1, v[4:5]
	v_lshl_add_u64 v[4:5], s[12:13], 0, v[12:13]
	global_load_dwordx4 v[4:7], v[4:5], off
	v_lshlrev_b32_e32 v0, 1, v1
	v_mad_u64_u32 v[8:9], s[34:35], v3, s25, v[0:1]
	ds_read_b128 v[8:11], v8
	v_add_u32_e32 v3, 0x100, v2
	v_ashrrev_i32_e32 v3, 4, v3
	s_waitcnt lgkmcnt(0)
	v_lshlrev_b32_e32 v16, 16, v8
	v_and_b32_e32 v17, 0xffff0000, v8
	v_lshlrev_b32_e32 v8, 16, v9
	v_and_b32_e32 v9, 0xffff0000, v9
	s_waitcnt vmcnt(0)
	v_lshlrev_b32_e32 v14, 16, v4
	v_and_b32_e32 v15, 0xffff0000, v4
	v_pk_add_f32 v[14:15], v[16:17], v[14:15]
	s_nop 0
	v_cvt_pk_bf16_f32 v4, v14, v15
	v_lshlrev_b32_e32 v14, 16, v5
	v_and_b32_e32 v15, 0xffff0000, v5
	v_pk_add_f32 v[8:9], v[8:9], v[14:15]
	v_lshlrev_b32_e32 v14, 16, v10
	v_cvt_pk_bf16_f32 v5, v8, v9
	v_lshlrev_b32_e32 v8, 16, v6
	v_and_b32_e32 v9, 0xffff0000, v6
	v_and_b32_e32 v15, 0xffff0000, v10
	v_pk_add_f32 v[8:9], v[14:15], v[8:9]
	v_lshlrev_b32_e32 v10, 16, v11
	v_cvt_pk_bf16_f32 v6, v8, v9
	v_lshlrev_b32_e32 v8, 16, v7
	v_and_b32_e32 v9, 0xffff0000, v7
	v_and_b32_e32 v11, 0xffff0000, v11
	v_pk_add_f32 v[8:9], v[10:11], v[8:9]
	s_nop 0
	v_cvt_pk_bf16_f32 v7, v8, v9
	v_lshl_add_u64 v[8:9], s[2:3], 0, v[12:13]
	global_store_dwordx4 v[8:9], v[4:7], off
	v_mad_u64_u32 v[8:9], s[34:35], v3, s25, v[0:1]
	s_nop 0
	v_add_u32_e32 v4, s29, v3
	v_ashrrev_i32_e32 v5, 31, v4
	v_lshlrev_b64 v[4:5], 10, v[4:5]
	v_or3_b32 v4, v4, s30, v1
	v_lshlrev_b64 v[12:13], 1, v[4:5]
	v_lshl_add_u64 v[4:5], s[12:13], 0, v[12:13]
	global_load_dwordx4 v[4:7], v[4:5], off
	ds_read_b128 v[8:11], v8
	v_add_u32_e32 v3, 0x200, v2
	v_ashrrev_i32_e32 v3, 4, v3
	v_lshl_add_u64 v[12:13], s[2:3], 0, v[12:13]
	s_waitcnt lgkmcnt(0)
	v_lshlrev_b32_e32 v14, 16, v8
	v_and_b32_e32 v15, 0xffff0000, v8
	v_lshlrev_b32_e32 v8, 16, v9
	v_and_b32_e32 v9, 0xffff0000, v9
	v_lshlrev_b32_e32 v16, 16, v10
	v_and_b32_e32 v17, 0xffff0000, v10
	v_lshlrev_b32_e32 v10, 16, v11
	v_and_b32_e32 v11, 0xffff0000, v11
	s_waitcnt vmcnt(0)
	v_lshlrev_b32_e32 v18, 16, v4
	v_and_b32_e32 v19, 0xffff0000, v4
	v_lshlrev_b32_e32 v4, 16, v5
	v_and_b32_e32 v5, 0xffff0000, v5
	v_lshlrev_b32_e32 v20, 16, v6
	v_and_b32_e32 v21, 0xffff0000, v6
	v_lshlrev_b32_e32 v6, 16, v7
	v_and_b32_e32 v7, 0xffff0000, v7
	v_pk_add_f32 v[14:15], v[14:15], v[18:19]
	v_pk_add_f32 v[8:9], v[8:9], v[4:5]
	v_pk_add_f32 v[16:17], v[16:17], v[20:21]
	v_pk_add_f32 v[10:11], v[10:11], v[6:7]
	v_cvt_pk_bf16_f32 v4, v14, v15
	v_cvt_pk_bf16_f32 v5, v8, v9
	v_cvt_pk_bf16_f32 v6, v16, v17
	v_cvt_pk_bf16_f32 v7, v10, v11
	global_store_dwordx4 v[12:13], v[4:7], off
	v_add_u32_e32 v8, 0x300, v2
	v_ashrrev_i32_e32 v26, 4, v8
	v_add_u32_e32 v4, s29, v3
	v_ashrrev_i32_e32 v5, 31, v4
	v_lshlrev_b64 v[4:5], 10, v[4:5]
	v_or3_b32 v4, v4, s30, v1
	v_lshlrev_b64 v[12:13], 1, v[4:5]
	v_lshl_add_u64 v[4:5], s[12:13], 0, v[12:13]
	global_load_dwordx4 v[4:7], v[4:5], off
	v_mad_u64_u32 v[8:9], s[34:35], v3, s25, v[0:1]
	ds_read_b128 v[8:11], v8
	v_add_u32_e32 v14, s29, v26
	v_ashrrev_i32_e32 v15, 31, v14
	v_lshlrev_b64 v[14:15], 10, v[14:15]
	v_or3_b32 v14, v14, s30, v1
	s_waitcnt lgkmcnt(0)
	v_lshlrev_b32_e32 v18, 16, v8
	v_and_b32_e32 v19, 0xffff0000, v8
	v_lshlrev_b32_e32 v8, 16, v9
	v_and_b32_e32 v9, 0xffff0000, v9
	v_lshlrev_b32_e32 v20, 16, v10
	v_and_b32_e32 v21, 0xffff0000, v10
	v_lshlrev_b32_e32 v10, 16, v11
	v_and_b32_e32 v11, 0xffff0000, v11
	v_lshlrev_b64 v[14:15], 1, v[14:15]
	v_lshl_add_u64 v[12:13], s[2:3], 0, v[12:13]
	v_lshl_add_u64 v[16:17], s[12:13], 0, v[14:15]
	v_add_u32_e32 v3, 0x400, v2
	v_ashrrev_i32_e32 v3, 4, v3
	v_lshl_add_u64 v[14:15], s[2:3], 0, v[14:15]
	s_waitcnt vmcnt(0)
	v_lshlrev_b32_e32 v22, 16, v4
	v_and_b32_e32 v23, 0xffff0000, v4
	v_lshlrev_b32_e32 v4, 16, v5
	v_and_b32_e32 v5, 0xffff0000, v5
	v_lshlrev_b32_e32 v24, 16, v6
	v_and_b32_e32 v25, 0xffff0000, v6
	v_lshlrev_b32_e32 v6, 16, v7
	v_and_b32_e32 v7, 0xffff0000, v7
	v_pk_add_f32 v[18:19], v[18:19], v[22:23]
	v_pk_add_f32 v[8:9], v[8:9], v[4:5]
	v_pk_add_f32 v[20:21], v[20:21], v[24:25]
	v_pk_add_f32 v[10:11], v[10:11], v[6:7]
	v_cvt_pk_bf16_f32 v4, v18, v19
	v_cvt_pk_bf16_f32 v5, v8, v9
	v_cvt_pk_bf16_f32 v6, v20, v21
	v_cvt_pk_bf16_f32 v7, v10, v11
	global_store_dwordx4 v[12:13], v[4:7], off
	global_load_dwordx4 v[4:7], v[16:17], off
	v_mad_u64_u32 v[8:9], s[34:35], v26, s25, v[0:1]
	ds_read_b128 v[8:11], v8
	v_add_u32_e32 v12, s29, v3
	v_ashrrev_i32_e32 v13, 31, v12
	v_lshlrev_b64 v[12:13], 10, v[12:13]
	v_or3_b32 v12, v12, s30, v1
	s_waitcnt lgkmcnt(0)
	v_lshlrev_b32_e32 v18, 16, v8
	v_and_b32_e32 v19, 0xffff0000, v8
	v_lshlrev_b32_e32 v8, 16, v9
	v_and_b32_e32 v9, 0xffff0000, v9
	v_lshlrev_b32_e32 v20, 16, v10
	v_and_b32_e32 v21, 0xffff0000, v10
	v_lshlrev_b32_e32 v10, 16, v11
	v_and_b32_e32 v11, 0xffff0000, v11
	v_lshlrev_b64 v[12:13], 1, v[12:13]
	v_lshl_add_u64 v[16:17], s[12:13], 0, v[12:13]
	v_lshl_add_u64 v[12:13], s[2:3], 0, v[12:13]
	s_waitcnt vmcnt(0)
	v_lshlrev_b32_e32 v22, 16, v4
	v_and_b32_e32 v23, 0xffff0000, v4
	v_lshlrev_b32_e32 v4, 16, v5
	v_and_b32_e32 v5, 0xffff0000, v5
	v_lshlrev_b32_e32 v24, 16, v6
	v_and_b32_e32 v25, 0xffff0000, v6
	v_lshlrev_b32_e32 v6, 16, v7
	v_and_b32_e32 v7, 0xffff0000, v7
	v_pk_add_f32 v[18:19], v[18:19], v[22:23]
	v_pk_add_f32 v[8:9], v[8:9], v[4:5]
	v_pk_add_f32 v[20:21], v[20:21], v[24:25]
	v_pk_add_f32 v[10:11], v[10:11], v[6:7]
	v_cvt_pk_bf16_f32 v4, v18, v19
	v_cvt_pk_bf16_f32 v5, v8, v9
	v_cvt_pk_bf16_f32 v6, v20, v21
	v_cvt_pk_bf16_f32 v7, v10, v11
	global_store_dwordx4 v[14:15], v[4:7], off
	global_load_dwordx4 v[4:7], v[16:17], off
	v_add_u32_e32 v8, 0x500, v2
	v_ashrrev_i32_e32 v26, 4, v8
	v_mad_u64_u32 v[8:9], s[34:35], v3, s25, v[0:1]
	ds_read_b128 v[8:11], v8
	v_add_u32_e32 v14, s29, v26
	v_ashrrev_i32_e32 v15, 31, v14
	v_lshlrev_b64 v[14:15], 10, v[14:15]
	v_or3_b32 v14, v14, s30, v1
	s_waitcnt lgkmcnt(0)
; DI int tidx() { int t = __builtin_amdgcn_workitem_id_x(); asm volatile("" : "+v"(t)); return t; }
; DI unsigned cvtpk(float lo, float hi) { const f32x2_ v = {lo, hi}; return __builtin_bit_cast(unsigned, __builtin_convertvector(v, bf16x2_)); }
; DI float bflo(unsigned w) { return __uint_as_float(w << 16); }
; DI float bfhi(unsigned w) { return __uint_as_float(w & 0xffff0000u); }
; DI void phase9(const Params& p, const Sched& sched, unsigned char* smem) {
;     ...
;       const int tid = tidx();
; #pragma unroll
;       for (int i = 0; i < 16; ++i) {
;         const int c = tid + 256 * i, row = c >> 4, ch = (c & 15) * 8;
;         const size_t gi = (size_t)(tm * 256 + row) * 1024 + tn * 128 + ch;
;         const u32x4 sv = *(const u32x4*)(Ls + row * EST + ch), xv = *(const u32x4*)(x1b + gi);
;         u32x4 w;
;         w.x = cvtpk(bflo(xv.x) + bflo(sv.x), bfhi(xv.x) + bfhi(sv.x)); w.y = cvtpk(bflo(xv.y) + bflo(sv.y), bfhi(xv.y) + bfhi(sv.y));
;         w.z = cvtpk(bflo(xv.z) + bflo(sv.z), bfhi(xv.z) + bfhi(sv.z)); w.w = cvtpk(bflo(xv.w) + bflo(sv.w), bfhi(xv.w) + bfhi(sv.w));
;         *(u32x4*)(x2b + gi) = w;
;       }
	v_lshlrev_b32_e32 v18, 16, v8
	v_and_b32_e32 v19, 0xffff0000, v8
	v_lshlrev_b32_e32 v8, 16, v9
	v_and_b32_e32 v9, 0xffff0000, v9
	v_lshlrev_b32_e32 v20, 16, v10
	v_and_b32_e32 v21, 0xffff0000, v10
	v_lshlrev_b32_e32 v10, 16, v11
	v_and_b32_e32 v11, 0xffff0000, v11
	v_lshlrev_b64 v[14:15], 1, v[14:15]
	v_lshl_add_u64 v[16:17], s[12:13], 0, v[14:15]
	v_add_u32_e32 v3, 0x600, v2
	v_ashrrev_i32_e32 v3, 4, v3
	v_lshl_add_u64 v[14:15], s[2:3], 0, v[14:15]
	s_waitcnt vmcnt(0)
	v_lshlrev_b32_e32 v22, 16, v4
	v_and_b32_e32 v23, 0xffff0000, v4
	v_lshlrev_b32_e32 v4, 16, v5
	v_and_b32_e32 v5, 0xffff0000, v5
	v_lshlrev_b32_e32 v24, 16, v6
	v_and_b32_e32 v25, 0xffff0000, v6
	v_lshlrev_b32_e32 v6, 16, v7
	v_and_b32_e32 v7, 0xffff0000, v7
	v_pk_add_f32 v[18:19], v[18:19], v[22:23]
	v_pk_add_f32 v[8:9], v[8:9], v[4:5]
	v_pk_add_f32 v[20:21], v[20:21], v[24:25]
	v_pk_add_f32 v[10:11], v[10:11], v[6:7]
	v_cvt_pk_bf16_f32 v4, v18, v19
	v_cvt_pk_bf16_f32 v5, v8, v9
	v_cvt_pk_bf16_f32 v6, v20, v21
	v_cvt_pk_bf16_f32 v7, v10, v11
	global_store_dwordx4 v[12:13], v[4:7], off
	global_load_dwordx4 v[4:7], v[16:17], off
	v_mad_u64_u32 v[8:9], s[34:35], v26, s25, v[0:1]
	ds_read_b128 v[8:11], v8
	v_add_u32_e32 v12, s29, v3
	v_ashrrev_i32_e32 v13, 31, v12
	v_lshlrev_b64 v[12:13], 10, v[12:13]
	v_or3_b32 v12, v12, s30, v1
	s_waitcnt lgkmcnt(0)
	v_lshlrev_b32_e32 v18, 16, v8
	v_and_b32_e32 v19, 0xffff0000, v8
	v_lshlrev_b32_e32 v8, 16, v9
	v_and_b32_e32 v9, 0xffff0000, v9
	v_lshlrev_b32_e32 v20, 16, v10
	v_and_b32_e32 v21, 0xffff0000, v10
	v_lshlrev_b32_e32 v10, 16, v11
	v_and_b32_e32 v11, 0xffff0000, v11
	v_lshlrev_b64 v[12:13], 1, v[12:13]
	v_lshl_add_u64 v[16:17], s[12:13], 0, v[12:13]
	v_lshl_add_u64 v[12:13], s[2:3], 0, v[12:13]
	s_waitcnt vmcnt(0)
	v_lshlrev_b32_e32 v22, 16, v4
	v_and_b32_e32 v23, 0xffff0000, v4
	v_lshlrev_b32_e32 v4, 16, v5
	v_and_b32_e32 v5, 0xffff0000, v5
	v_lshlrev_b32_e32 v24, 16, v6
	v_and_b32_e32 v25, 0xffff0000, v6
	v_lshlrev_b32_e32 v6, 16, v7
	v_and_b32_e32 v7, 0xffff0000, v7
	v_pk_add_f32 v[18:19], v[18:19], v[22:23]
	v_pk_add_f32 v[8:9], v[8:9], v[4:5]
	v_pk_add_f32 v[20:21], v[20:21], v[24:25]
	v_pk_add_f32 v[10:11], v[10:11], v[6:7]
	v_cvt_pk_bf16_f32 v4, v18, v19
	v_cvt_pk_bf16_f32 v5, v8, v9
	v_cvt_pk_bf16_f32 v6, v20, v21
	v_cvt_pk_bf16_f32 v7, v10, v11
	global_store_dwordx4 v[14:15], v[4:7], off
	global_load_dwordx4 v[4:7], v[16:17], off
	v_add_u32_e32 v8, 0x700, v2
	v_ashrrev_i32_e32 v26, 4, v8
	v_mad_u64_u32 v[8:9], s[34:35], v3, s25, v[0:1]
	ds_read_b128 v[8:11], v8
	v_add_u32_e32 v14, s29, v26
	v_ashrrev_i32_e32 v15, 31, v14
	v_lshlrev_b64 v[14:15], 10, v[14:15]
	v_or3_b32 v14, v14, s30, v1
	s_waitcnt lgkmcnt(0)
	v_lshlrev_b32_e32 v18, 16, v8
	v_and_b32_e32 v19, 0xffff0000, v8
	v_lshlrev_b32_e32 v8, 16, v9
	v_and_b32_e32 v9, 0xffff0000, v9
	v_lshlrev_b32_e32 v20, 16, v10
	v_and_b32_e32 v21, 0xffff0000, v10
	v_lshlrev_b32_e32 v10, 16, v11
	v_and_b32_e32 v11, 0xffff0000, v11
	v_lshlrev_b64 v[14:15], 1, v[14:15]
	v_lshl_add_u64 v[16:17], s[12:13], 0, v[14:15]
	v_add_u32_e32 v3, 0x800, v2
	v_ashrrev_i32_e32 v3, 4, v3
	v_lshl_add_u64 v[14:15], s[2:3], 0, v[14:15]
	s_waitcnt vmcnt(0)
	v_lshlrev_b32_e32 v22, 16, v4
	v_and_b32_e32 v23, 0xffff0000, v4
	v_lshlrev_b32_e32 v4, 16, v5
	v_and_b32_e32 v5, 0xffff0000, v5
	v_lshlrev_b32_e32 v24, 16, v6
	v_and_b32_e32 v25, 0xffff0000, v6
	v_lshlrev_b32_e32 v6, 16, v7
	v_and_b32_e32 v7, 0xffff0000, v7
	v_pk_add_f32 v[18:19], v[18:19], v[22:23]
	v_pk_add_f32 v[8:9], v[8:9], v[4:5]
	v_pk_add_f32 v[20:21], v[20:21], v[24:25]
	v_pk_add_f32 v[10:11], v[10:11], v[6:7]
	v_cvt_pk_bf16_f32 v4, v18, v19
	v_cvt_pk_bf16_f32 v5, v8, v9
	v_cvt_pk_bf16_f32 v6, v20, v21
	v_cvt_pk_bf16_f32 v7, v10, v11
	global_store_dwordx4 v[12:13], v[4:7], off
	global_load_dwordx4 v[4:7], v[16:17], off
	v_mad_u64_u32 v[8:9], s[34:35], v26, s25, v[0:1]
	ds_read_b128 v[8:11], v8
	v_add_u32_e32 v12, s29, v3
	v_ashrrev_i32_e32 v13, 31, v12
	v_lshlrev_b64 v[12:13], 10, v[12:13]
	v_or3_b32 v12, v12, s30, v1
	s_waitcnt lgkmcnt(0)
	v_lshlrev_b32_e32 v18, 16, v8
	v_and_b32_e32 v19, 0xffff0000, v8
	v_lshlrev_b32_e32 v8, 16, v9
	v_and_b32_e32 v9, 0xffff0000, v9
	v_lshlrev_b32_e32 v20, 16, v10
	v_and_b32_e32 v21, 0xffff0000, v10
	v_lshlrev_b32_e32 v10, 16, v11
	v_and_b32_e32 v11, 0xffff0000, v11
	v_lshlrev_b64 v[12:13], 1, v[12:13]
	v_lshl_add_u64 v[16:17], s[12:13], 0, v[12:13]
	v_lshl_add_u64 v[12:13], s[2:3], 0, v[12:13]
	s_waitcnt vmcnt(0)
	v_lshlrev_b32_e32 v22, 16, v4
	v_and_b32_e32 v23, 0xffff0000, v4
	v_lshlrev_b32_e32 v4, 16, v5
	v_and_b32_e32 v5, 0xffff0000, v5
	v_lshlrev_b32_e32 v24, 16, v6
	v_and_b32_e32 v25, 0xffff0000, v6
	v_lshlrev_b32_e32 v6, 16, v7
	v_and_b32_e32 v7, 0xffff0000, v7
	v_pk_add_f32 v[18:19], v[18:19], v[22:23]
	v_pk_add_f32 v[8:9], v[8:9], v[4:5]
	v_pk_add_f32 v[20:21], v[20:21], v[24:25]
	v_pk_add_f32 v[10:11], v[10:11], v[6:7]
	v_cvt_pk_bf16_f32 v4, v18, v19
	v_cvt_pk_bf16_f32 v5, v8, v9
	v_cvt_pk_bf16_f32 v6, v20, v21
	v_cvt_pk_bf16_f32 v7, v10, v11
	global_store_dwordx4 v[14:15], v[4:7], off
	global_load_dwordx4 v[4:7], v[16:17], off
	v_add_u32_e32 v8, 0x900, v2
	v_ashrrev_i32_e32 v26, 4, v8
	v_mad_u64_u32 v[8:9], s[34:35], v3, s25, v[0:1]
	ds_read_b128 v[8:11], v8
	v_add_u32_e32 v14, s29, v26
	v_ashrrev_i32_e32 v15, 31, v14
	v_lshlrev_b64 v[14:15], 10, v[14:15]
	v_or3_b32 v14, v14, s30, v1
	s_waitcnt lgkmcnt(0)
	v_lshlrev_b32_e32 v18, 16, v8
	v_and_b32_e32 v19, 0xffff0000, v8
	v_lshlrev_b32_e32 v8, 16, v9
	v_and_b32_e32 v9, 0xffff0000, v9
	v_lshlrev_b32_e32 v20, 16, v10
	v_and_b32_e32 v21, 0xffff0000, v10
	v_lshlrev_b32_e32 v10, 16, v11
	v_and_b32_e32 v11, 0xffff0000, v11
	v_lshlrev_b64 v[14:15], 1, v[14:15]
	v_lshl_add_u64 v[16:17], s[12:13], 0, v[14:15]
	v_add_u32_e32 v3, 0xa00, v2
	v_ashrrev_i32_e32 v3, 4, v3
	v_lshl_add_u64 v[14:15], s[2:3], 0, v[14:15]
	s_waitcnt vmcnt(0)
; DI int tidx() { int t = __builtin_amdgcn_workitem_id_x(); asm volatile("" : "+v"(t)); return t; }
; DI unsigned cvtpk(float lo, float hi) { const f32x2_ v = {lo, hi}; return __builtin_bit_cast(unsigned, __builtin_convertvector(v, bf16x2_)); }
; DI float bflo(unsigned w) { return __uint_as_float(w << 16); }
; DI float bfhi(unsigned w) { return __uint_as_float(w & 0xffff0000u); }
; DI void phase9(const Params& p, const Sched& sched, unsigned char* smem) {
;     ...
;       const int tid = tidx();
; #pragma unroll
;       for (int i = 0; i < 16; ++i) {
;         const int c = tid + 256 * i, row = c >> 4, ch = (c & 15) * 8;
;         const size_t gi = (size_t)(tm * 256 + row) * 1024 + tn * 128 + ch;
;         const u32x4 sv = *(const u32x4*)(Ls + row * EST + ch), xv = *(const u32x4*)(x1b + gi);
;         u32x4 w;
;         w.x = cvtpk(bflo(xv.x) + bflo(sv.x), bfhi(xv.x) + bfhi(sv.x)); w.y = cvtpk(bflo(xv.y) + bflo(sv.y), bfhi(xv.y) + bfhi(sv.y));
;         w.z = cvtpk(bflo(xv.z) + bflo(sv.z), bfhi(xv.z) + bfhi(sv.z)); w.w = cvtpk(bflo(xv.w) + bflo(sv.w), bfhi(xv.w) + bfhi(sv.w));
;         *(u32x4*)(x2b + gi) = w;
;       }
	v_lshlrev_b32_e32 v22, 16, v4
	v_and_b32_e32 v23, 0xffff0000, v4
	v_lshlrev_b32_e32 v4, 16, v5
	v_and_b32_e32 v5, 0xffff0000, v5
	v_lshlrev_b32_e32 v24, 16, v6
	v_and_b32_e32 v25, 0xffff0000, v6
	v_lshlrev_b32_e32 v6, 16, v7
	v_and_b32_e32 v7, 0xffff0000, v7
	v_pk_add_f32 v[18:19], v[18:19], v[22:23]
	v_pk_add_f32 v[8:9], v[8:9], v[4:5]
	v_pk_add_f32 v[20:21], v[20:21], v[24:25]
	v_pk_add_f32 v[10:11], v[10:11], v[6:7]
	v_cvt_pk_bf16_f32 v4, v18, v19
	v_cvt_pk_bf16_f32 v5, v8, v9
	v_cvt_pk_bf16_f32 v6, v20, v21
	v_cvt_pk_bf16_f32 v7, v10, v11
	global_store_dwordx4 v[12:13], v[4:7], off
	global_load_dwordx4 v[4:7], v[16:17], off
	v_mad_u64_u32 v[8:9], s[34:35], v26, s25, v[0:1]
	ds_read_b128 v[8:11], v8
	v_add_u32_e32 v12, s29, v3
	v_ashrrev_i32_e32 v13, 31, v12
	v_lshlrev_b64 v[12:13], 10, v[12:13]
	v_or3_b32 v12, v12, s30, v1
	s_waitcnt lgkmcnt(0)
	v_lshlrev_b32_e32 v18, 16, v8
	v_and_b32_e32 v19, 0xffff0000, v8
	v_lshlrev_b32_e32 v8, 16, v9
	v_and_b32_e32 v9, 0xffff0000, v9
	v_lshlrev_b32_e32 v20, 16, v10
	v_and_b32_e32 v21, 0xffff0000, v10
	v_lshlrev_b32_e32 v10, 16, v11
	v_and_b32_e32 v11, 0xffff0000, v11
	v_lshlrev_b64 v[12:13], 1, v[12:13]
	v_lshl_add_u64 v[16:17], s[12:13], 0, v[12:13]
	v_lshl_add_u64 v[12:13], s[2:3], 0, v[12:13]
	s_waitcnt vmcnt(0)
	v_lshlrev_b32_e32 v22, 16, v4
	v_and_b32_e32 v23, 0xffff0000, v4
	v_lshlrev_b32_e32 v4, 16, v5
	v_and_b32_e32 v5, 0xffff0000, v5
	v_lshlrev_b32_e32 v24, 16, v6
	v_and_b32_e32 v25, 0xffff0000, v6
	v_lshlrev_b32_e32 v6, 16, v7
	v_and_b32_e32 v7, 0xffff0000, v7
	v_pk_add_f32 v[18:19], v[18:19], v[22:23]
	v_pk_add_f32 v[8:9], v[8:9], v[4:5]
	v_pk_add_f32 v[20:21], v[20:21], v[24:25]
	v_pk_add_f32 v[10:11], v[10:11], v[6:7]
	v_cvt_pk_bf16_f32 v4, v18, v19
	v_cvt_pk_bf16_f32 v5, v8, v9
	v_cvt_pk_bf16_f32 v6, v20, v21
	v_cvt_pk_bf16_f32 v7, v10, v11
	global_store_dwordx4 v[14:15], v[4:7], off
	global_load_dwordx4 v[4:7], v[16:17], off
	v_add_u32_e32 v8, 0xb00, v2
	v_ashrrev_i32_e32 v26, 4, v8
	v_mad_u64_u32 v[8:9], s[34:35], v3, s25, v[0:1]
	ds_read_b128 v[8:11], v8
	v_add_u32_e32 v14, s29, v26
	v_ashrrev_i32_e32 v15, 31, v14
	v_lshlrev_b64 v[14:15], 10, v[14:15]
	v_or3_b32 v14, v14, s30, v1
	s_waitcnt lgkmcnt(0)
	v_lshlrev_b32_e32 v18, 16, v8
	v_and_b32_e32 v19, 0xffff0000, v8
	v_lshlrev_b32_e32 v8, 16, v9
	v_and_b32_e32 v9, 0xffff0000, v9
	v_lshlrev_b32_e32 v20, 16, v10
	v_and_b32_e32 v21, 0xffff0000, v10
	v_lshlrev_b32_e32 v10, 16, v11
	v_and_b32_e32 v11, 0xffff0000, v11
	v_lshlrev_b64 v[14:15], 1, v[14:15]
	v_lshl_add_u64 v[16:17], s[12:13], 0, v[14:15]
	v_add_u32_e32 v3, 0xc00, v2
	v_ashrrev_i32_e32 v3, 4, v3
	v_lshl_add_u64 v[14:15], s[2:3], 0, v[14:15]
	s_waitcnt vmcnt(0)
	v_lshlrev_b32_e32 v22, 16, v4
	v_and_b32_e32 v23, 0xffff0000, v4
	v_lshlrev_b32_e32 v4, 16, v5
	v_and_b32_e32 v5, 0xffff0000, v5
	v_lshlrev_b32_e32 v24, 16, v6
	v_and_b32_e32 v25, 0xffff0000, v6
	v_lshlrev_b32_e32 v6, 16, v7
	v_and_b32_e32 v7, 0xffff0000, v7
	v_pk_add_f32 v[18:19], v[18:19], v[22:23]
	v_pk_add_f32 v[8:9], v[8:9], v[4:5]
	v_pk_add_f32 v[20:21], v[20:21], v[24:25]
	v_pk_add_f32 v[10:11], v[10:11], v[6:7]
	v_cvt_pk_bf16_f32 v4, v18, v19
	v_cvt_pk_bf16_f32 v5, v8, v9
	v_cvt_pk_bf16_f32 v6, v20, v21
	v_cvt_pk_bf16_f32 v7, v10, v11
	global_store_dwordx4 v[12:13], v[4:7], off
	global_load_dwordx4 v[4:7], v[16:17], off
	v_mad_u64_u32 v[8:9], s[34:35], v26, s25, v[0:1]
	ds_read_b128 v[8:11], v8
	v_add_u32_e32 v12, s29, v3
	v_ashrrev_i32_e32 v13, 31, v12
	v_lshlrev_b64 v[12:13], 10, v[12:13]
	v_or3_b32 v12, v12, s30, v1
	s_waitcnt lgkmcnt(0)
	v_lshlrev_b32_e32 v18, 16, v8
	v_and_b32_e32 v19, 0xffff0000, v8
	v_lshlrev_b32_e32 v8, 16, v9
	v_and_b32_e32 v9, 0xffff0000, v9
	v_lshlrev_b32_e32 v20, 16, v10
	v_and_b32_e32 v21, 0xffff0000, v10
	v_lshlrev_b32_e32 v10, 16, v11
	v_and_b32_e32 v11, 0xffff0000, v11
	v_lshlrev_b64 v[12:13], 1, v[12:13]
	v_lshl_add_u64 v[16:17], s[12:13], 0, v[12:13]
	v_lshl_add_u64 v[12:13], s[2:3], 0, v[12:13]
	s_waitcnt vmcnt(0)
	v_lshlrev_b32_e32 v22, 16, v4
	v_and_b32_e32 v23, 0xffff0000, v4
	v_lshlrev_b32_e32 v4, 16, v5
	v_and_b32_e32 v5, 0xffff0000, v5
	v_lshlrev_b32_e32 v24, 16, v6
	v_and_b32_e32 v25, 0xffff0000, v6
	v_lshlrev_b32_e32 v6, 16, v7
	v_and_b32_e32 v7, 0xffff0000, v7
	v_pk_add_f32 v[18:19], v[18:19], v[22:23]
	v_pk_add_f32 v[8:9], v[8:9], v[4:5]
	v_pk_add_f32 v[20:21], v[20:21], v[24:25]
	v_pk_add_f32 v[10:11], v[10:11], v[6:7]
	v_cvt_pk_bf16_f32 v4, v18, v19
	v_cvt_pk_bf16_f32 v5, v8, v9
	v_cvt_pk_bf16_f32 v6, v20, v21
	v_cvt_pk_bf16_f32 v7, v10, v11
	global_store_dwordx4 v[14:15], v[4:7], off
	global_load_dwordx4 v[4:7], v[16:17], off
	v_add_u32_e32 v8, 0xd00, v2
	v_ashrrev_i32_e32 v26, 4, v8
	v_mad_u64_u32 v[8:9], s[34:35], v3, s25, v[0:1]
	ds_read_b128 v[8:11], v8
	v_add_u32_e32 v14, s29, v26
	v_ashrrev_i32_e32 v15, 31, v14
	v_lshlrev_b64 v[14:15], 10, v[14:15]
	v_or3_b32 v14, v14, s30, v1
	s_waitcnt lgkmcnt(0)
; DI int tidx() { int t = __builtin_amdgcn_workitem_id_x(); asm volatile("" : "+v"(t)); return t; }
; DI unsigned cvtpk(float lo, float hi) { const f32x2_ v = {lo, hi}; return __builtin_bit_cast(unsigned, __builtin_convertvector(v, bf16x2_)); }
; DI float bflo(unsigned w) { return __uint_as_float(w << 16); }
; DI float bfhi(unsigned w) { return __uint_as_float(w & 0xffff0000u); }
; DI void phase9(const Params& p, const Sched& sched, unsigned char* smem) {
;     ...
;       const int tid = tidx();
; #pragma unroll
;       for (int i = 0; i < 16; ++i) {
;         const int c = tid + 256 * i, row = c >> 4, ch = (c & 15) * 8;
;         const size_t gi = (size_t)(tm * 256 + row) * 1024 + tn * 128 + ch;
;         const u32x4 sv = *(const u32x4*)(Ls + row * EST + ch), xv = *(const u32x4*)(x1b + gi);
;         u32x4 w;
;         w.x = cvtpk(bflo(xv.x) + bflo(sv.x), bfhi(xv.x) + bfhi(sv.x)); w.y = cvtpk(bflo(xv.y) + bflo(sv.y), bfhi(xv.y) + bfhi(sv.y));
;         w.z = cvtpk(bflo(xv.z) + bflo(sv.z), bfhi(xv.z) + bfhi(sv.z)); w.w = cvtpk(bflo(xv.w) + bflo(sv.w), bfhi(xv.w) + bfhi(sv.w));
;         *(u32x4*)(x2b + gi) = w;
;       }
	v_lshlrev_b32_e32 v18, 16, v8
	v_and_b32_e32 v19, 0xffff0000, v8
	v_lshlrev_b32_e32 v8, 16, v9
	v_and_b32_e32 v9, 0xffff0000, v9
	v_lshlrev_b32_e32 v20, 16, v10
	v_and_b32_e32 v21, 0xffff0000, v10
	v_lshlrev_b32_e32 v10, 16, v11
	v_and_b32_e32 v11, 0xffff0000, v11
	v_lshlrev_b64 v[14:15], 1, v[14:15]
	v_lshl_add_u64 v[16:17], s[12:13], 0, v[14:15]
	v_add_u32_e32 v3, 0xe00, v2
	v_ashrrev_i32_e32 v3, 4, v3
	v_lshl_add_u64 v[14:15], s[2:3], 0, v[14:15]
	v_add_u32_e32 v2, 0xf00, v2
	s_waitcnt vmcnt(0)
	v_lshlrev_b32_e32 v22, 16, v4
	v_and_b32_e32 v23, 0xffff0000, v4
	v_lshlrev_b32_e32 v4, 16, v5
	v_and_b32_e32 v5, 0xffff0000, v5
	v_lshlrev_b32_e32 v24, 16, v6
	v_and_b32_e32 v25, 0xffff0000, v6
	v_lshlrev_b32_e32 v6, 16, v7
	v_and_b32_e32 v7, 0xffff0000, v7
	v_pk_add_f32 v[18:19], v[18:19], v[22:23]
	v_pk_add_f32 v[8:9], v[8:9], v[4:5]
	v_pk_add_f32 v[20:21], v[20:21], v[24:25]
	v_pk_add_f32 v[10:11], v[10:11], v[6:7]
	v_cvt_pk_bf16_f32 v4, v18, v19
	v_cvt_pk_bf16_f32 v5, v8, v9
	v_cvt_pk_bf16_f32 v6, v20, v21
	v_cvt_pk_bf16_f32 v7, v10, v11
	global_store_dwordx4 v[12:13], v[4:7], off
	global_load_dwordx4 v[4:7], v[16:17], off
	v_mad_u64_u32 v[8:9], s[34:35], v26, s25, v[0:1]
	ds_read_b128 v[8:11], v8
	v_add_u32_e32 v12, s29, v3
	v_ashrrev_i32_e32 v13, 31, v12
	v_lshlrev_b64 v[12:13], 10, v[12:13]
	v_or3_b32 v12, v12, s30, v1
	s_waitcnt lgkmcnt(0)
	v_lshlrev_b32_e32 v18, 16, v8
	v_and_b32_e32 v19, 0xffff0000, v8
	v_lshlrev_b32_e32 v8, 16, v9
	v_and_b32_e32 v9, 0xffff0000, v9
	v_lshlrev_b32_e32 v20, 16, v10
	v_and_b32_e32 v21, 0xffff0000, v10
	v_lshlrev_b32_e32 v10, 16, v11
	v_and_b32_e32 v11, 0xffff0000, v11
	v_lshlrev_b64 v[12:13], 1, v[12:13]
	v_lshl_add_u64 v[16:17], s[12:13], 0, v[12:13]
	v_lshl_add_u64 v[12:13], s[2:3], 0, v[12:13]
	s_waitcnt vmcnt(0)
	v_lshlrev_b32_e32 v22, 16, v4
	v_and_b32_e32 v23, 0xffff0000, v4
	v_lshlrev_b32_e32 v4, 16, v5
	v_and_b32_e32 v5, 0xffff0000, v5
	v_lshlrev_b32_e32 v24, 16, v6
	v_and_b32_e32 v25, 0xffff0000, v6
	v_lshlrev_b32_e32 v6, 16, v7
	v_and_b32_e32 v7, 0xffff0000, v7
	v_pk_add_f32 v[18:19], v[18:19], v[22:23]
	v_pk_add_f32 v[8:9], v[8:9], v[4:5]
	v_pk_add_f32 v[20:21], v[20:21], v[24:25]
	v_pk_add_f32 v[10:11], v[10:11], v[6:7]
	v_cvt_pk_bf16_f32 v4, v18, v19
	v_cvt_pk_bf16_f32 v5, v8, v9
	v_cvt_pk_bf16_f32 v6, v20, v21
	v_cvt_pk_bf16_f32 v7, v10, v11
	global_store_dwordx4 v[14:15], v[4:7], off
	global_load_dwordx4 v[4:7], v[16:17], off
	v_mad_u64_u32 v[8:9], s[34:35], v3, s25, v[0:1]
	v_ashrrev_i32_e32 v24, 4, v2
	ds_read_b128 v[8:11], v8
	v_add_u32_e32 v2, s29, v24
	v_ashrrev_i32_e32 v3, 31, v2
	v_lshlrev_b64 v[2:3], 10, v[2:3]
	v_or3_b32 v2, v2, s30, v1
	v_lshlrev_b64 v[14:15], 1, v[2:3]
	s_waitcnt lgkmcnt(0)
	v_lshlrev_b32_e32 v2, 16, v8
	v_and_b32_e32 v3, 0xffff0000, v8
	v_lshlrev_b32_e32 v8, 16, v9
	v_and_b32_e32 v9, 0xffff0000, v9
	v_lshlrev_b32_e32 v18, 16, v10
	v_and_b32_e32 v19, 0xffff0000, v10
	v_lshlrev_b32_e32 v10, 16, v11
	v_and_b32_e32 v11, 0xffff0000, v11
	v_lshl_add_u64 v[16:17], s[12:13], 0, v[14:15]
	v_mad_u64_u32 v[0:1], s[30:31], v24, s25, v[0:1]
	s_waitcnt vmcnt(0)
	v_lshlrev_b32_e32 v20, 16, v4
	v_and_b32_e32 v21, 0xffff0000, v4
	v_lshlrev_b32_e32 v4, 16, v5
	v_and_b32_e32 v5, 0xffff0000, v5
	v_lshlrev_b32_e32 v22, 16, v6
	v_and_b32_e32 v23, 0xffff0000, v6
	v_lshlrev_b32_e32 v6, 16, v7
	v_and_b32_e32 v7, 0xffff0000, v7
	v_pk_add_f32 v[2:3], v[2:3], v[20:21]
	v_pk_add_f32 v[4:5], v[8:9], v[4:5]
	v_pk_add_f32 v[8:9], v[18:19], v[22:23]
	v_pk_add_f32 v[6:7], v[10:11], v[6:7]
	v_cvt_pk_bf16_f32 v2, v2, v3
	v_cvt_pk_bf16_f32 v3, v4, v5
	v_cvt_pk_bf16_f32 v4, v8, v9
	v_cvt_pk_bf16_f32 v5, v6, v7
	global_store_dwordx4 v[12:13], v[2:5], off
	global_load_dwordx4 v[2:5], v[16:17], off
	ds_read_b128 v[6:9], v0
	v_lshl_add_u64 v[10:11], s[2:3], 0, v[14:15]
	s_waitcnt lgkmcnt(0)
	v_lshlrev_b32_e32 v0, 16, v6
	v_and_b32_e32 v1, 0xffff0000, v6
	v_lshlrev_b32_e32 v6, 16, v7
	v_and_b32_e32 v7, 0xffff0000, v7
	v_lshlrev_b32_e32 v12, 16, v8
	v_and_b32_e32 v13, 0xffff0000, v8
	v_lshlrev_b32_e32 v8, 16, v9
	v_and_b32_e32 v9, 0xffff0000, v9
	s_waitcnt vmcnt(0)
	v_lshlrev_b32_e32 v14, 16, v2
	v_and_b32_e32 v15, 0xffff0000, v2
	v_lshlrev_b32_e32 v2, 16, v3
	v_and_b32_e32 v3, 0xffff0000, v3
	v_lshlrev_b32_e32 v16, 16, v4
	v_and_b32_e32 v17, 0xffff0000, v4
	v_lshlrev_b32_e32 v4, 16, v5
	v_and_b32_e32 v5, 0xffff0000, v5
	v_pk_add_f32 v[0:1], v[0:1], v[14:15]
	v_pk_add_f32 v[2:3], v[6:7], v[2:3]
	v_pk_add_f32 v[6:7], v[12:13], v[16:17]
	v_pk_add_f32 v[4:5], v[8:9], v[4:5]
	v_cvt_pk_bf16_f32 v0, v0, v1
	v_cvt_pk_bf16_f32 v1, v2, v3
	v_cvt_pk_bf16_f32 v2, v6, v7
	v_cvt_pk_bf16_f32 v3, v4, v5
	global_store_dwordx4 v[10:11], v[0:3], off
	s_cbranch_scc0 .LBB0_1094
	s_branch .LBB0_1091

; __global__ void __launch_bounds__(256, 2) mega_kernel(Params p) {
;   __shared__ __attribute__((aligned(16))) unsigned char smem[SMEM_BYTES];
	.amdhsa_kernel _Z11mega_kernel6Params
		.amdhsa_group_segment_fixed_size 74256
		.amdhsa_private_segment_fixed_size 0
		.amdhsa_kernarg_size 480
		.amdhsa_user_sgpr_count 2
		.amdhsa_user_sgpr_dispatch_ptr 0
		.amdhsa_user_sgpr_queue_ptr 0
		.amdhsa_user_sgpr_kernarg_segment_ptr 1
		.amdhsa_user_sgpr_dispatch_id 0
		.amdhsa_user_sgpr_kernarg_preload_length 0
		.amdhsa_user_sgpr_kernarg_preload_offset 0
		.amdhsa_user_sgpr_private_segment_size 0
		.amdhsa_uses_dynamic_stack 0
		.amdhsa_enable_private_segment 0
		.amdhsa_system_sgpr_workgroup_id_x 1
		.amdhsa_system_sgpr_workgroup_id_y 0
		.amdhsa_system_sgpr_workgroup_id_z 0
		.amdhsa_system_sgpr_workgroup_info 0
		.amdhsa_system_vgpr_workitem_id 2
		.amdhsa_next_free_vgpr 246
		.amdhsa_next_free_sgpr 102
		.amdhsa_accum_offset 248
		.amdhsa_reserve_vcc 1
		.amdhsa_float_round_mode_32 0
		.amdhsa_float_round_mode_16_64 0
		.amdhsa_float_denorm_mode_32 3
		.amdhsa_float_denorm_mode_16_64 3
		.amdhsa_dx10_clamp 1
		.amdhsa_ieee_mode 1
		.amdhsa_fp16_overflow 0
		.amdhsa_tg_split 0
		.amdhsa_exception_fp_ieee_invalid_op 0
		.amdhsa_exception_fp_denorm_src 0
		.amdhsa_exception_fp_ieee_div_zero 0
		.amdhsa_exception_fp_ieee_overflow 0
		.amdhsa_exception_fp_ieee_underflow 0
		.amdhsa_exception_fp_ieee_inexact 0
		.amdhsa_exception_int_div_zero 0
	.end_amdhsa_kernel

; __global__ void __launch_bounds__(256, 2) mega_kernel(Params p) {
;   __shared__ __attribute__((aligned(16))) unsigned char smem[SMEM_BYTES];
amdhsa.kernels:
  - .agpr_count:     0
    .args:
      - .offset:         0
        .size:           224
        .value_kind:     by_value
      - .offset:         224
        .size:           4
        .value_kind:     hidden_block_count_x
      - .offset:         228
        .size:           4
        .value_kind:     hidden_block_count_y
      - .offset:         232
        .size:           4
        .value_kind:     hidden_block_count_z
      - .offset:         236
        .size:           2
        .value_kind:     hidden_group_size_x
      - .offset:         238
        .size:           2
        .value_kind:     hidden_group_size_y
      - .offset:         240
        .size:           2
        .value_kind:     hidden_group_size_z
      - .offset:         242
        .size:           2
        .value_kind:     hidden_remainder_x
      - .offset:         244
        .size:           2
        .value_kind:     hidden_remainder_y
      - .offset:         246
        .size:           2
        .value_kind:     hidden_remainder_z
      - .offset:         264
        .size:           8
        .value_kind:     hidden_global_offset_x
      - .offset:         272
        .size:           8
        .value_kind:     hidden_global_offset_y
      - .offset:         280
        .size:           8
        .value_kind:     hidden_global_offset_z
      - .offset:         288
        .size:           2
        .value_kind:     hidden_grid_dims
      - .offset:         312
        .size:           8
        .value_kind:     hidden_multigrid_sync_arg
    .group_segment_fixed_size: 74256
    .kernarg_segment_align: 8
    .kernarg_segment_size: 480
    .language:       OpenCL C
    .language_version:
      - 2
      - 0
    .max_flat_workgroup_size: 256
    .name:           _Z11mega_kernel6Params
    .private_segment_fixed_size: 0
    .sgpr_count:     108
    .sgpr_spill_count: 57
    .symbol:         _Z11mega_kernel6Params.kd
    .uniform_work_group_size: 1
    .uses_dynamic_stack: false
    .vgpr_count:     246
    .vgpr_spill_count: 0
    .wavefront_size: 64
